# v14 plus software-pipelined K-fragment LDS reads in attention QK^T (depth 3) and per-row ssq/pos loads hoisted out of the P8 up-projection epilogue ladders
# speedup vs baseline: 1.0128x; 1.0069x over previous
; __device__ __forceinline__ f32x4 silu4(f32x4 v) { f32x4 o; o[0] = silu_f(v[0]); o[1] = silu_f(v[1]); o[2] = silu_f(v[2]); o[3] = silu_f(v[3]); return o; }
;     __device__ __forceinline__ void operator()(const f32x4 (&acc)[2][2][4][2], const Unit& u, int wr, int wc, int fr, int fq) const {
;     ...
;         } else if (u.pn < 12) {
;             bf16_t* base = SG1 + (u.pn - 4) * 256 + cl;
; #pragma unroll
;             for (int ai = 0; ai < 2; ++ai)
; #pragma unroll
;                 for (int m = 0; m < 4; ++m) { bf16_t* rowp = base + (size_t)(row0 + ai * HALF + m * 16) * 2048;
; #pragma unroll
;                     for (int bj = 0; bj < 2; ++bj) st8(rowp + bj * HALF, silu4(acc[ai][bj][m][0]), silu4(acc[ai][bj][m][1])); }
.LBB0_776:
	s_andn2_b64 vcc, exec, s[36:37]
	s_cbranch_vccnz .LBB0_778
	v_mul_f32_e32 v128, 0xbfb8aa3b, v124
	v_exp_f32_e32 v157, v128
	s_lshl_b32 s31, s46, 9
	s_add_u32 s36, s90, s31
	s_addc_u32 s37, s91, 0
	v_lshlrev_b32_e32 v140, 1, v142
	v_lshl_add_u64 v[128:129], s[36:37], 0, v[140:141]
	s_mov_b64 s[36:37], 0x127ff800
	v_add_f32_e32 v140, 1.0, v157
	v_lshl_add_u64 v[130:131], v[128:129], 0, s[36:37]
	v_rcp_f32_e32 v159, v140
	v_ashrrev_i32_e32 v157, 31, v156
	v_lshlrev_b64 v[128:129], 12, v[156:157]
	v_mul_f32_e32 v161, 0xbfb8aa3b, v125
	v_exp_f32_e32 v161, v161
	s_nop 0
	v_add_f32_e32 v158, 1.0, v161
	v_rcp_f32_e32 v162, v158
	v_mul_f32_e32 v157, v124, v159
	v_mul_f32_e32 v160, 0xbfb8aa3b, v126
	v_mov_b32_e32 v140, v157
	v_exp_f32_e32 v160, v160
	s_nop 0
	v_add_f32_e32 v160, 1.0, v160
	v_rcp_f32_e32 v163, v160
	v_mul_f32_e32 v157, v125, v162
	v_mul_f32_e32 v162, 0xbfb8aa3b, v127
	v_exp_f32_e32 v162, v162
	s_nop 0
	v_add_f32_e32 v161, 1.0, v162
	v_rcp_f32_e32 v170, v161
	v_mul_f32_e32 v158, v126, v163
	v_mov_b32_e32 v159, v158
	v_mul_f32_e32 v163, 0xbfb8aa3b, v120
	v_exp_f32_e32 v163, v163
	s_nop 0
	v_add_f32_e32 v162, 1.0, v163
	v_rcp_f32_e32 v171, v162
	v_mul_f32_e32 v158, v127, v170
	v_mov_b32_e32 v160, v158
	v_mul_f32_e32 v170, 0xbfb8aa3b, v121
	v_exp_f32_e32 v170, v170
	s_nop 0
	v_add_f32_e32 v163, 1.0, v170
	v_rcp_f32_e32 v172, v163
	v_mul_f32_e32 v158, v120, v171
	v_mov_b32_e32 v161, v158
	v_mul_f32_e32 v171, 0xbfb8aa3b, v122
	v_exp_f32_e32 v171, v171
	s_nop 0
	v_add_f32_e32 v170, 1.0, v171
	v_rcp_f32_e32 v173, v170
	v_mul_f32_e32 v158, v121, v172
	v_mov_b32_e32 v162, v158
	v_mul_f32_e32 v172, 0xbfb8aa3b, v123
	v_exp_f32_e32 v172, v172
	s_nop 0
	v_add_f32_e32 v171, 1.0, v172
	v_rcp_f32_e32 v174, v171
	v_mul_f32_e32 v158, v122, v173
	v_mov_b32_e32 v163, v158
	v_lshl_add_u64 v[128:129], v[130:131], 0, v[128:129]
	v_mul_f32_e32 v158, v123, v174
	v_mul_f32_e32 v170, 0xbfb8aa3b, v116
	v_exp_f32_e32 v170, v170
	v_mov_b32_e32 v171, v158
	v_cvt_pk_bf16_f32 v158, v140, v157
	v_cvt_pk_bf16_f32 v159, v159, v160
	v_add_f32_e32 v140, 1.0, v170
	v_rcp_f32_e32 v170, v140
	v_cvt_pk_bf16_f32 v160, v161, v162
	v_cvt_pk_bf16_f32 v161, v163, v171
	global_store_dwordx4 v[128:129], v[158:161], off
	v_mul_f32_e32 v162, 0xbfb8aa3b, v118
	v_exp_f32_e32 v162, v162
	v_mul_f32_e32 v160, 0xbfb8aa3b, v117
	v_exp_f32_e32 v160, v160
	s_nop 0
	v_add_f32_e32 v158, 1.0, v160
	v_rcp_f32_e32 v161, v158
	v_mul_f32_e32 v157, v116, v170
	v_mov_b32_e32 v140, v157
	v_add_f32_e32 v160, 1.0, v162
	v_rcp_f32_e32 v163, v160
	v_mul_f32_e32 v157, v117, v161
	v_mul_f32_e32 v161, 0xbfb8aa3b, v119
	v_exp_f32_e32 v161, v161
	s_nop 0
	v_add_f32_e32 v161, 1.0, v161
	v_rcp_f32_e32 v170, v161
	v_mul_f32_e32 v158, v118, v163
	v_mov_b32_e32 v159, v158
	v_mul_f32_e32 v163, 0xbfb8aa3b, v112
	v_exp_f32_e32 v163, v163
	s_nop 0
	v_add_f32_e32 v162, 1.0, v163
	v_rcp_f32_e32 v171, v162
	v_mul_f32_e32 v158, v119, v170
	v_mov_b32_e32 v160, v158
	v_mul_f32_e32 v170, 0xbfb8aa3b, v113
	v_exp_f32_e32 v170, v170
	s_nop 0
	v_add_f32_e32 v163, 1.0, v170
	v_rcp_f32_e32 v172, v163
	v_mul_f32_e32 v158, v112, v171
	v_mov_b32_e32 v161, v158
	v_mul_f32_e32 v171, 0xbfb8aa3b, v114
	v_exp_f32_e32 v171, v171
	s_nop 0
	v_add_f32_e32 v170, 1.0, v171
	v_rcp_f32_e32 v173, v170
	v_mul_f32_e32 v158, v113, v172
	v_mov_b32_e32 v162, v158
	v_mul_f32_e32 v172, 0xbfb8aa3b, v115
	v_exp_f32_e32 v172, v172
	s_nop 0
	v_add_f32_e32 v171, 1.0, v172
	v_rcp_f32_e32 v174, v171
	v_mul_f32_e32 v158, v114, v173
	v_mov_b32_e32 v163, v158
	v_mul_f32_e32 v158, v115, v174
	v_mov_b32_e32 v170, v158
	v_cvt_pk_bf16_f32 v158, v140, v157
	v_mul_f32_e32 v140, 0xbfb8aa3b, v108
	v_exp_f32_e32 v140, v140
	v_cvt_pk_bf16_f32 v159, v159, v160
	v_cvt_pk_bf16_f32 v160, v161, v162
	v_cvt_pk_bf16_f32 v161, v163, v170
	global_store_dwordx4 v[128:129], v[158:161], off offset:256
	s_nop 0
	v_add_f32_e32 v140, 1.0, v140
	v_rcp_f32_e32 v160, v140
	v_mul_f32_e32 v163, 0xbfb8aa3b, v109
	v_exp_f32_e32 v163, v163
	v_or_b32_e32 v158, 16, v156
	v_add_f32_e32 v161, 1.0, v163
	v_rcp_f32_e32 v170, v161
	v_mul_f32_e32 v157, v108, v160
	v_mul_f32_e32 v162, 0xbfb8aa3b, v110
	v_mov_b32_e32 v140, v157
	v_exp_f32_e32 v162, v162
	s_nop 0
	v_add_f32_e32 v162, 1.0, v162
	v_rcp_f32_e32 v171, v162
	v_mul_f32_e32 v157, v109, v170
	v_mul_f32_e32 v170, 0xbfb8aa3b, v111
	v_exp_f32_e32 v170, v170
	s_nop 0
	v_add_f32_e32 v163, 1.0, v170
	v_rcp_f32_e32 v172, v163
	v_mul_f32_e32 v160, v110, v171
	v_mov_b32_e32 v161, v160
	v_mul_f32_e32 v171, 0xbfb8aa3b, v104
	v_exp_f32_e32 v171, v171
	s_nop 0
	v_add_f32_e32 v170, 1.0, v171
	v_rcp_f32_e32 v173, v170
	v_mul_f32_e32 v160, v111, v172
	v_mov_b32_e32 v162, v160
	v_mul_f32_e32 v172, 0xbfb8aa3b, v105
	v_exp_f32_e32 v172, v172
	s_nop 0
	v_add_f32_e32 v171, 1.0, v172
	v_rcp_f32_e32 v174, v171
	v_mul_f32_e32 v160, v104, v173
	v_mov_b32_e32 v163, v160
	v_mul_f32_e32 v173, 0xbfb8aa3b, v106
	v_exp_f32_e32 v173, v173
	s_nop 0
	v_add_f32_e32 v172, 1.0, v173
	v_rcp_f32_e32 v175, v172
	v_mul_f32_e32 v160, v105, v174
	v_mov_b32_e32 v170, v160
	v_mul_f32_e32 v174, 0xbfb8aa3b, v107
	v_exp_f32_e32 v174, v174
	s_nop 0
	v_add_f32_e32 v173, 1.0, v174
	v_rcp_f32_e32 v176, v173
	v_mul_f32_e32 v160, v106, v175
	v_mov_b32_e32 v171, v160
	v_ashrrev_i32_e32 v159, 31, v158
	v_mul_f32_e32 v160, v107, v176
	v_mul_f32_e32 v172, 0xbfb8aa3b, v100
	v_exp_f32_e32 v172, v172
	v_mov_b32_e32 v173, v160
	v_cvt_pk_bf16_f32 v160, v140, v157
	v_lshlrev_b64 v[158:159], 12, v[158:159]
	v_add_f32_e32 v140, 1.0, v172
	v_rcp_f32_e32 v172, v140
	v_lshl_add_u64 v[158:159], v[130:131], 0, v[158:159]
	v_cvt_pk_bf16_f32 v161, v161, v162
	v_cvt_pk_bf16_f32 v162, v163, v170
; __device__ __forceinline__ f32x4 silu4(f32x4 v) { f32x4 o; o[0] = silu_f(v[0]); o[1] = silu_f(v[1]); o[2] = silu_f(v[2]); o[3] = silu_f(v[3]); return o; }
;     __device__ __forceinline__ void operator()(const f32x4 (&acc)[2][2][4][2], const Unit& u, int wr, int wc, int fr, int fq) const {
;     ...
;                 for (int m = 0; m < 4; ++m) { bf16_t* rowp = base + (size_t)(row0 + ai * HALF + m * 16) * 2048;
; #pragma unroll
;                     for (int bj = 0; bj < 2; ++bj) st8(rowp + bj * HALF, silu4(acc[ai][bj][m][0]), silu4(acc[ai][bj][m][1])); }
	v_cvt_pk_bf16_f32 v163, v171, v173
	global_store_dwordx4 v[158:159], v[160:163], off
	v_mul_f32_e32 v170, 0xbfb8aa3b, v102
	v_exp_f32_e32 v170, v170
	v_mul_f32_e32 v162, 0xbfb8aa3b, v101
	v_exp_f32_e32 v162, v162
	s_nop 0
	v_add_f32_e32 v160, 1.0, v162
	v_rcp_f32_e32 v163, v160
	v_mul_f32_e32 v157, v100, v172
	v_mov_b32_e32 v140, v157
	v_add_f32_e32 v162, 1.0, v170
	v_rcp_f32_e32 v171, v162
	v_mul_f32_e32 v157, v101, v163
	v_mul_f32_e32 v163, 0xbfb8aa3b, v103
	v_exp_f32_e32 v163, v163
	s_nop 0
	v_add_f32_e32 v163, 1.0, v163
	v_rcp_f32_e32 v172, v163
	v_mul_f32_e32 v160, v102, v171
	v_mov_b32_e32 v161, v160
	v_mul_f32_e32 v171, 0xbfb8aa3b, v96
	v_exp_f32_e32 v171, v171
	s_nop 0
	v_add_f32_e32 v170, 1.0, v171
	v_rcp_f32_e32 v173, v170
	v_mul_f32_e32 v160, v103, v172
	v_mov_b32_e32 v162, v160
	v_mul_f32_e32 v172, 0xbfb8aa3b, v97
	v_exp_f32_e32 v172, v172
	s_nop 0
	v_add_f32_e32 v171, 1.0, v172
	v_rcp_f32_e32 v174, v171
	v_mul_f32_e32 v160, v96, v173
	v_mov_b32_e32 v163, v160
	v_mul_f32_e32 v173, 0xbfb8aa3b, v98
	v_exp_f32_e32 v173, v173
	s_nop 0
	v_add_f32_e32 v172, 1.0, v173
	v_rcp_f32_e32 v175, v172
	v_mul_f32_e32 v160, v97, v174
	v_mov_b32_e32 v170, v160
	v_mul_f32_e32 v174, 0xbfb8aa3b, v99
	v_exp_f32_e32 v174, v174
	s_nop 0
	v_add_f32_e32 v173, 1.0, v174
	v_rcp_f32_e32 v176, v173
	v_mul_f32_e32 v160, v98, v175
	v_mov_b32_e32 v171, v160
	v_mul_f32_e32 v160, v99, v176
	v_mov_b32_e32 v172, v160
	v_cvt_pk_bf16_f32 v160, v140, v157
	v_mul_f32_e32 v140, 0xbfb8aa3b, v92
	v_exp_f32_e32 v140, v140
	v_cvt_pk_bf16_f32 v161, v161, v162
	v_cvt_pk_bf16_f32 v162, v163, v170
	v_cvt_pk_bf16_f32 v163, v171, v172
	global_store_dwordx4 v[158:159], v[160:163], off offset:256
	s_nop 0
	v_add_f32_e32 v140, 1.0, v140
	v_rcp_f32_e32 v160, v140
	v_mul_f32_e32 v163, 0xbfb8aa3b, v93
	v_exp_f32_e32 v163, v163
	v_or_b32_e32 v158, 32, v156
	v_add_f32_e32 v161, 1.0, v163
	v_rcp_f32_e32 v170, v161
	v_mul_f32_e32 v157, v92, v160
	v_mul_f32_e32 v162, 0xbfb8aa3b, v94
	v_mov_b32_e32 v140, v157
	v_exp_f32_e32 v162, v162
	s_nop 0
	v_add_f32_e32 v162, 1.0, v162
	v_rcp_f32_e32 v171, v162
	v_mul_f32_e32 v157, v93, v170
	v_mul_f32_e32 v170, 0xbfb8aa3b, v95
	v_exp_f32_e32 v170, v170
	s_nop 0
	v_add_f32_e32 v163, 1.0, v170
	v_rcp_f32_e32 v172, v163
	v_mul_f32_e32 v160, v94, v171
	v_mov_b32_e32 v161, v160
	v_mul_f32_e32 v171, 0xbfb8aa3b, v88
	v_exp_f32_e32 v171, v171
	s_nop 0
	v_add_f32_e32 v170, 1.0, v171
	v_rcp_f32_e32 v173, v170
	v_mul_f32_e32 v160, v95, v172
	v_mov_b32_e32 v162, v160
	v_mul_f32_e32 v172, 0xbfb8aa3b, v89
	v_exp_f32_e32 v172, v172
	s_nop 0
	v_add_f32_e32 v171, 1.0, v172
	v_rcp_f32_e32 v174, v171
	v_mul_f32_e32 v160, v88, v173
	v_mov_b32_e32 v163, v160
	v_mul_f32_e32 v173, 0xbfb8aa3b, v90
	v_exp_f32_e32 v173, v173
	s_nop 0
	v_add_f32_e32 v172, 1.0, v173
	v_rcp_f32_e32 v175, v172
	v_mul_f32_e32 v160, v89, v174
	v_mov_b32_e32 v170, v160
	v_mul_f32_e32 v174, 0xbfb8aa3b, v91
	v_exp_f32_e32 v174, v174
	s_nop 0
	v_add_f32_e32 v173, 1.0, v174
	v_rcp_f32_e32 v176, v173
	v_mul_f32_e32 v160, v90, v175
	v_mov_b32_e32 v171, v160
	v_ashrrev_i32_e32 v159, 31, v158
	v_mul_f32_e32 v160, v91, v176
	v_mul_f32_e32 v172, 0xbfb8aa3b, v84
	v_exp_f32_e32 v172, v172
	v_mov_b32_e32 v173, v160
	v_cvt_pk_bf16_f32 v160, v140, v157
	v_lshlrev_b64 v[158:159], 12, v[158:159]
	v_add_f32_e32 v140, 1.0, v172
	v_rcp_f32_e32 v172, v140
	v_lshl_add_u64 v[158:159], v[130:131], 0, v[158:159]
	v_cvt_pk_bf16_f32 v161, v161, v162
	v_cvt_pk_bf16_f32 v162, v163, v170
	v_cvt_pk_bf16_f32 v163, v171, v173
	global_store_dwordx4 v[158:159], v[160:163], off
	v_mul_f32_e32 v170, 0xbfb8aa3b, v86
	v_exp_f32_e32 v170, v170
	v_mul_f32_e32 v162, 0xbfb8aa3b, v85
	v_exp_f32_e32 v162, v162
	s_nop 0
	v_add_f32_e32 v160, 1.0, v162
	v_rcp_f32_e32 v163, v160
	v_mul_f32_e32 v157, v84, v172
	v_mov_b32_e32 v140, v157
	v_add_f32_e32 v162, 1.0, v170
	v_rcp_f32_e32 v171, v162
	v_mul_f32_e32 v157, v85, v163
	v_mul_f32_e32 v163, 0xbfb8aa3b, v87
	v_exp_f32_e32 v163, v163
	s_nop 0
	v_add_f32_e32 v163, 1.0, v163
	v_rcp_f32_e32 v172, v163
	v_mul_f32_e32 v160, v86, v171
	v_mov_b32_e32 v161, v160
	v_mul_f32_e32 v171, 0xbfb8aa3b, v80
	v_exp_f32_e32 v171, v171
	s_nop 0
	v_add_f32_e32 v170, 1.0, v171
	v_rcp_f32_e32 v173, v170
	v_mul_f32_e32 v160, v87, v172
	v_mov_b32_e32 v162, v160
	v_mul_f32_e32 v172, 0xbfb8aa3b, v81
	v_exp_f32_e32 v172, v172
	s_nop 0
	v_add_f32_e32 v171, 1.0, v172
	v_rcp_f32_e32 v174, v171
	v_mul_f32_e32 v160, v80, v173
	v_mov_b32_e32 v163, v160
	v_mul_f32_e32 v173, 0xbfb8aa3b, v82
	v_exp_f32_e32 v173, v173
	s_nop 0
	v_add_f32_e32 v172, 1.0, v173
	v_rcp_f32_e32 v175, v172
	v_mul_f32_e32 v160, v81, v174
	v_mov_b32_e32 v170, v160
	v_mul_f32_e32 v174, 0xbfb8aa3b, v83
	v_exp_f32_e32 v174, v174
	s_nop 0
	v_add_f32_e32 v173, 1.0, v174
	v_rcp_f32_e32 v176, v173
	v_mul_f32_e32 v160, v82, v175
	v_mov_b32_e32 v171, v160
	v_mul_f32_e32 v160, v83, v176
	v_mov_b32_e32 v172, v160
	v_cvt_pk_bf16_f32 v160, v140, v157
	v_mul_f32_e32 v140, 0xbfb8aa3b, v76
	v_exp_f32_e32 v140, v140
	v_cvt_pk_bf16_f32 v161, v161, v162
	v_cvt_pk_bf16_f32 v162, v163, v170
	v_cvt_pk_bf16_f32 v163, v171, v172
	global_store_dwordx4 v[158:159], v[160:163], off offset:256
	s_nop 0
	v_add_f32_e32 v140, 1.0, v140
	v_rcp_f32_e32 v160, v140
	v_or_b32_e32 v158, 48, v156
	v_ashrrev_i32_e32 v159, 31, v158
	v_lshlrev_b64 v[158:159], 12, v[158:159]
	v_lshl_add_u64 v[130:131], v[130:131], 0, v[158:159]
	v_mul_f32_e32 v161, 0xbfb8aa3b, v77
	v_exp_f32_e32 v161, v161
	s_nop 0
	v_add_f32_e32 v158, 1.0, v161
	v_rcp_f32_e32 v162, v158
	v_mul_f32_e32 v157, v76, v160
	v_mul_f32_e32 v160, 0xbfb8aa3b, v78
	v_mov_b32_e32 v140, v157
	v_exp_f32_e32 v160, v160
	s_nop 0
	v_add_f32_e32 v160, 1.0, v160
; __device__ __forceinline__ f32x4 silu4(f32x4 v) { f32x4 o; o[0] = silu_f(v[0]); o[1] = silu_f(v[1]); o[2] = silu_f(v[2]); o[3] = silu_f(v[3]); return o; }
;     __device__ __forceinline__ void operator()(const f32x4 (&acc)[2][2][4][2], const Unit& u, int wr, int wc, int fr, int fq) const {
;     ...
;                 for (int m = 0; m < 4; ++m) { bf16_t* rowp = base + (size_t)(row0 + ai * HALF + m * 16) * 2048;
; #pragma unroll
;                     for (int bj = 0; bj < 2; ++bj) st8(rowp + bj * HALF, silu4(acc[ai][bj][m][0]), silu4(acc[ai][bj][m][1])); }
	v_rcp_f32_e32 v163, v160
	v_mul_f32_e32 v157, v77, v162
	v_mul_f32_e32 v162, 0xbfb8aa3b, v79
	v_exp_f32_e32 v162, v162
	s_nop 0
	v_add_f32_e32 v161, 1.0, v162
	v_rcp_f32_e32 v170, v161
	v_mul_f32_e32 v158, v78, v163
	v_mov_b32_e32 v159, v158
	v_mul_f32_e32 v163, 0xbfb8aa3b, v72
	v_exp_f32_e32 v163, v163
	s_nop 0
	v_add_f32_e32 v162, 1.0, v163
	v_rcp_f32_e32 v171, v162
	v_mul_f32_e32 v158, v79, v170
	v_mov_b32_e32 v160, v158
	v_mul_f32_e32 v170, 0xbfb8aa3b, v73
	v_exp_f32_e32 v170, v170
	s_nop 0
	v_add_f32_e32 v163, 1.0, v170
	v_rcp_f32_e32 v172, v163
	v_mul_f32_e32 v158, v72, v171
	v_mov_b32_e32 v161, v158
	v_mul_f32_e32 v171, 0xbfb8aa3b, v74
	v_exp_f32_e32 v171, v171
	s_nop 0
	v_add_f32_e32 v170, 1.0, v171
	v_rcp_f32_e32 v173, v170
	v_mul_f32_e32 v158, v73, v172
	v_mov_b32_e32 v162, v158
	v_mul_f32_e32 v172, 0xbfb8aa3b, v75
	v_exp_f32_e32 v172, v172
	s_nop 0
	v_add_f32_e32 v171, 1.0, v172
	v_rcp_f32_e32 v174, v171
	v_mul_f32_e32 v158, v74, v173
	v_mov_b32_e32 v163, v158
	v_mul_f32_e32 v158, v75, v174
	v_mul_f32_e32 v170, 0xbfb8aa3b, v68
	v_exp_f32_e32 v170, v170
	v_mov_b32_e32 v171, v158
	v_cvt_pk_bf16_f32 v158, v140, v157
	v_cvt_pk_bf16_f32 v159, v159, v160
	v_add_f32_e32 v140, 1.0, v170
	v_rcp_f32_e32 v170, v140
	v_cvt_pk_bf16_f32 v160, v161, v162
	v_cvt_pk_bf16_f32 v161, v163, v171
	global_store_dwordx4 v[130:131], v[158:161], off
	v_mul_f32_e32 v162, 0xbfb8aa3b, v70
	v_exp_f32_e32 v162, v162
	v_mul_f32_e32 v160, 0xbfb8aa3b, v69
	v_exp_f32_e32 v160, v160
	s_nop 0
	v_add_f32_e32 v158, 1.0, v160
	v_rcp_f32_e32 v161, v158
	v_mul_f32_e32 v157, v68, v170
	v_mov_b32_e32 v140, v157
	v_add_f32_e32 v160, 1.0, v162
	v_rcp_f32_e32 v163, v160
	v_mul_f32_e32 v157, v69, v161
	v_mul_f32_e32 v161, 0xbfb8aa3b, v71
	v_exp_f32_e32 v161, v161
	s_nop 0
	v_add_f32_e32 v161, 1.0, v161
	v_rcp_f32_e32 v170, v161
	v_mul_f32_e32 v158, v70, v163
	v_mov_b32_e32 v159, v158
	v_mul_f32_e32 v163, 0xbfb8aa3b, v64
	v_exp_f32_e32 v163, v163
	s_nop 0
	v_add_f32_e32 v162, 1.0, v163
	v_rcp_f32_e32 v171, v162
	v_mul_f32_e32 v158, v71, v170
	v_mov_b32_e32 v160, v158
	v_mul_f32_e32 v170, 0xbfb8aa3b, v65
	v_exp_f32_e32 v170, v170
	s_nop 0
	v_add_f32_e32 v163, 1.0, v170
	v_rcp_f32_e32 v172, v163
	v_mul_f32_e32 v158, v64, v171
	v_mov_b32_e32 v161, v158
	v_mul_f32_e32 v171, 0xbfb8aa3b, v66
	v_exp_f32_e32 v171, v171
	s_nop 0
	v_add_f32_e32 v170, 1.0, v171
	v_rcp_f32_e32 v173, v170
	v_mul_f32_e32 v158, v65, v172
	v_mov_b32_e32 v162, v158
	v_mul_f32_e32 v172, 0xbfb8aa3b, v67
	v_exp_f32_e32 v172, v172
	s_nop 0
	v_add_f32_e32 v171, 1.0, v172
	v_rcp_f32_e32 v174, v171
	v_mul_f32_e32 v158, v66, v173
	v_mov_b32_e32 v163, v158
	v_mul_f32_e32 v158, v67, v174
	v_mov_b32_e32 v170, v158
	v_mul_f32_e32 v158, 0xbfb8aa3b, v60
	v_exp_f32_e32 v171, v158
	v_cvt_pk_bf16_f32 v158, v140, v157
	v_cvt_pk_bf16_f32 v159, v159, v160
	v_cvt_pk_bf16_f32 v160, v161, v162
	v_cvt_pk_bf16_f32 v161, v163, v170
	global_store_dwordx4 v[130:131], v[158:161], off offset:256
	v_add_f32_e32 v140, 1.0, v171
	v_rcp_f32_e32 v162, v140
	v_mul_f32_e32 v160, 0xbfb8aa3b, v61
	v_exp_f32_e32 v160, v160
	s_mov_b64 s[36:37], 0x80000
	v_add_f32_e32 v158, 1.0, v160
	v_lshl_add_u64 v[130:131], v[128:129], 0, s[36:37]
	v_rcp_f32_e32 v161, v158
	v_mul_f32_e32 v157, v60, v162
	v_mov_b32_e32 v140, v157
	v_mul_f32_e32 v162, 0xbfb8aa3b, v62
	v_exp_f32_e32 v162, v162
	s_nop 0
	v_add_f32_e32 v160, 1.0, v162
	v_rcp_f32_e32 v163, v160
	v_mul_f32_e32 v157, v61, v161
	v_mul_f32_e32 v161, 0xbfb8aa3b, v63
	v_exp_f32_e32 v161, v161
	s_nop 0
	v_add_f32_e32 v161, 1.0, v161
	v_rcp_f32_e32 v170, v161
	v_mul_f32_e32 v158, v62, v163
	v_mov_b32_e32 v159, v158
	v_mul_f32_e32 v163, 0xbfb8aa3b, v56
	v_exp_f32_e32 v163, v163
	s_nop 0
	v_add_f32_e32 v162, 1.0, v163
	v_rcp_f32_e32 v171, v162
	v_mul_f32_e32 v158, v63, v170
	v_mov_b32_e32 v160, v158
	v_mul_f32_e32 v170, 0xbfb8aa3b, v57
	v_exp_f32_e32 v170, v170
	s_nop 0
	v_add_f32_e32 v163, 1.0, v170
	v_rcp_f32_e32 v172, v163
	v_mul_f32_e32 v158, v56, v171
	v_mov_b32_e32 v161, v158
	v_mul_f32_e32 v171, 0xbfb8aa3b, v58
	v_exp_f32_e32 v171, v171
	s_nop 0
	v_add_f32_e32 v170, 1.0, v171
	v_rcp_f32_e32 v173, v170
	v_mul_f32_e32 v158, v57, v172
	v_mov_b32_e32 v162, v158
	v_mul_f32_e32 v172, 0xbfb8aa3b, v59
	v_exp_f32_e32 v172, v172
	s_nop 0
	v_add_f32_e32 v171, 1.0, v172
	v_rcp_f32_e32 v174, v171
	v_mul_f32_e32 v158, v58, v173
	v_mov_b32_e32 v163, v158
	v_mul_f32_e32 v158, v59, v174
	v_mov_b32_e32 v170, v158
	v_cvt_pk_bf16_f32 v158, v140, v157
	v_mul_f32_e32 v140, 0xbfb8aa3b, v52
	v_exp_f32_e32 v140, v140
	v_cvt_pk_bf16_f32 v159, v159, v160
	v_cvt_pk_bf16_f32 v160, v161, v162
	v_cvt_pk_bf16_f32 v161, v163, v170
	v_add_co_u32_e32 v162, vcc, s68, v128
	v_add_f32_e32 v140, 1.0, v140
	v_rcp_f32_e32 v170, v140
	v_addc_co_u32_e32 v163, vcc, 0, v129, vcc
	global_store_dwordx4 v[162:163], v[158:161], off
	v_mul_f32_e32 v162, 0xbfb8aa3b, v54
	v_exp_f32_e32 v162, v162
	v_mul_f32_e32 v160, 0xbfb8aa3b, v53
	v_exp_f32_e32 v160, v160
	s_nop 0
	v_add_f32_e32 v158, 1.0, v160
	v_rcp_f32_e32 v161, v158
	v_mul_f32_e32 v157, v52, v170
	v_mov_b32_e32 v140, v157
	v_add_f32_e32 v160, 1.0, v162
	v_rcp_f32_e32 v163, v160
	v_mul_f32_e32 v157, v53, v161
	v_mul_f32_e32 v161, 0xbfb8aa3b, v55
	v_exp_f32_e32 v161, v161
	s_nop 0
	v_add_f32_e32 v161, 1.0, v161
	v_rcp_f32_e32 v170, v161
	v_mul_f32_e32 v158, v54, v163
	v_mov_b32_e32 v159, v158
	v_mul_f32_e32 v163, 0xbfb8aa3b, v48
	v_exp_f32_e32 v163, v163
	s_nop 0
	v_add_f32_e32 v162, 1.0, v163
	v_rcp_f32_e32 v171, v162
	v_mul_f32_e32 v158, v55, v170
	v_mov_b32_e32 v160, v158
	v_mul_f32_e32 v170, 0xbfb8aa3b, v49
	v_exp_f32_e32 v170, v170
	s_nop 0
	v_add_f32_e32 v163, 1.0, v170
	v_rcp_f32_e32 v172, v163
; __device__ __forceinline__ f32x4 silu4(f32x4 v) { f32x4 o; o[0] = silu_f(v[0]); o[1] = silu_f(v[1]); o[2] = silu_f(v[2]); o[3] = silu_f(v[3]); return o; }
;     __device__ __forceinline__ void operator()(const f32x4 (&acc)[2][2][4][2], const Unit& u, int wr, int wc, int fr, int fq) const {
;     ...
;                 for (int m = 0; m < 4; ++m) { bf16_t* rowp = base + (size_t)(row0 + ai * HALF + m * 16) * 2048;
; #pragma unroll
;                     for (int bj = 0; bj < 2; ++bj) st8(rowp + bj * HALF, silu4(acc[ai][bj][m][0]), silu4(acc[ai][bj][m][1])); }
	v_mul_f32_e32 v158, v48, v171
	v_mov_b32_e32 v161, v158
	v_mul_f32_e32 v171, 0xbfb8aa3b, v50
	v_exp_f32_e32 v171, v171
	s_nop 0
	v_add_f32_e32 v170, 1.0, v171
	v_rcp_f32_e32 v173, v170
	v_mul_f32_e32 v158, v49, v172
	v_mov_b32_e32 v162, v158
	v_mul_f32_e32 v172, 0xbfb8aa3b, v51
	v_exp_f32_e32 v172, v172
	s_nop 0
	v_add_f32_e32 v171, 1.0, v172
	v_rcp_f32_e32 v174, v171
	v_mul_f32_e32 v158, v50, v173
	v_mov_b32_e32 v163, v158
	v_mul_f32_e32 v158, v51, v174
	v_mov_b32_e32 v170, v158
	v_mul_f32_e32 v158, 0xbfb8aa3b, v44
	v_exp_f32_e32 v171, v158
	v_cvt_pk_bf16_f32 v158, v140, v157
	v_cvt_pk_bf16_f32 v159, v159, v160
	v_cvt_pk_bf16_f32 v160, v161, v162
	v_cvt_pk_bf16_f32 v161, v163, v170
	global_store_dwordx4 v[130:131], v[158:161], off offset:256
	v_add_f32_e32 v140, 1.0, v171
	v_rcp_f32_e32 v162, v140
	v_mul_f32_e32 v160, 0xbfb8aa3b, v45
	v_exp_f32_e32 v160, v160
	v_lshl_add_u64 v[130:131], v[128:129], 0, s[16:17]
	v_add_f32_e32 v158, 1.0, v160
	v_rcp_f32_e32 v161, v158
	v_mul_f32_e32 v157, v44, v162
	v_mov_b32_e32 v140, v157
	v_mul_f32_e32 v162, 0xbfb8aa3b, v46
	v_exp_f32_e32 v162, v162
	s_nop 0
	v_add_f32_e32 v160, 1.0, v162
	v_rcp_f32_e32 v163, v160
	v_mul_f32_e32 v157, v45, v161
	v_mul_f32_e32 v161, 0xbfb8aa3b, v47
	v_exp_f32_e32 v161, v161
	s_nop 0
	v_add_f32_e32 v161, 1.0, v161
	v_rcp_f32_e32 v170, v161
	v_mul_f32_e32 v158, v46, v163
	v_mov_b32_e32 v159, v158
	v_mul_f32_e32 v163, 0xbfb8aa3b, v40
	v_exp_f32_e32 v163, v163
	s_nop 0
	v_add_f32_e32 v162, 1.0, v163
	v_rcp_f32_e32 v171, v162
	v_mul_f32_e32 v158, v47, v170
	v_mov_b32_e32 v160, v158
	v_mul_f32_e32 v170, 0xbfb8aa3b, v41
	v_exp_f32_e32 v170, v170
	s_nop 0
	v_add_f32_e32 v163, 1.0, v170
	v_rcp_f32_e32 v172, v163
	v_mul_f32_e32 v158, v40, v171
	v_mov_b32_e32 v161, v158
	v_mul_f32_e32 v171, 0xbfb8aa3b, v42
	v_exp_f32_e32 v171, v171
	s_nop 0
	v_add_f32_e32 v170, 1.0, v171
	v_rcp_f32_e32 v173, v170
	v_mul_f32_e32 v158, v41, v172
	v_mov_b32_e32 v162, v158
	v_mul_f32_e32 v172, 0xbfb8aa3b, v43
	v_exp_f32_e32 v172, v172
	s_nop 0
	v_add_f32_e32 v171, 1.0, v172
	v_rcp_f32_e32 v174, v171
	v_mul_f32_e32 v158, v42, v173
	v_mov_b32_e32 v163, v158
	v_mul_f32_e32 v158, v43, v174
	v_mov_b32_e32 v170, v158
	v_cvt_pk_bf16_f32 v158, v140, v157
	v_mul_f32_e32 v140, 0xbfb8aa3b, v36
	v_exp_f32_e32 v140, v140
	v_cvt_pk_bf16_f32 v159, v159, v160
	v_cvt_pk_bf16_f32 v160, v161, v162
	v_cvt_pk_bf16_f32 v161, v163, v170
	v_add_co_u32_e32 v162, vcc, s69, v128
	v_add_f32_e32 v140, 1.0, v140
	v_rcp_f32_e32 v170, v140
	v_addc_co_u32_e32 v163, vcc, 0, v129, vcc
	global_store_dwordx4 v[162:163], v[158:161], off
	v_mul_f32_e32 v162, 0xbfb8aa3b, v38
	v_exp_f32_e32 v162, v162
	v_mul_f32_e32 v160, 0xbfb8aa3b, v37
	v_exp_f32_e32 v160, v160
	s_nop 0
	v_add_f32_e32 v158, 1.0, v160
	v_rcp_f32_e32 v161, v158
	v_mul_f32_e32 v157, v36, v170
	v_mov_b32_e32 v140, v157
	v_add_f32_e32 v160, 1.0, v162
	v_rcp_f32_e32 v163, v160
	v_mul_f32_e32 v157, v37, v161
	v_mul_f32_e32 v161, 0xbfb8aa3b, v39
	v_exp_f32_e32 v161, v161
	s_nop 0
	v_add_f32_e32 v161, 1.0, v161
	v_rcp_f32_e32 v170, v161
	v_mul_f32_e32 v158, v38, v163
	v_mov_b32_e32 v159, v158
	v_mul_f32_e32 v163, 0xbfb8aa3b, v32
	v_exp_f32_e32 v163, v163
	s_nop 0
	v_add_f32_e32 v162, 1.0, v163
	v_rcp_f32_e32 v171, v162
	v_mul_f32_e32 v158, v39, v170
	v_mov_b32_e32 v160, v158
	v_mul_f32_e32 v170, 0xbfb8aa3b, v33
	v_exp_f32_e32 v170, v170
	s_nop 0
	v_add_f32_e32 v163, 1.0, v170
	v_rcp_f32_e32 v172, v163
	v_mul_f32_e32 v158, v32, v171
	v_mov_b32_e32 v161, v158
	v_mul_f32_e32 v171, 0xbfb8aa3b, v34
	v_exp_f32_e32 v171, v171
	s_nop 0
	v_add_f32_e32 v170, 1.0, v171
	v_rcp_f32_e32 v173, v170
	v_mul_f32_e32 v158, v33, v172
	v_mov_b32_e32 v162, v158
	v_mul_f32_e32 v172, 0xbfb8aa3b, v35
	v_exp_f32_e32 v172, v172
	s_nop 0
	v_add_f32_e32 v171, 1.0, v172
	v_rcp_f32_e32 v174, v171
	v_mul_f32_e32 v158, v34, v173
	v_mov_b32_e32 v163, v158
	v_mul_f32_e32 v158, v35, v174
	v_mov_b32_e32 v170, v158
	v_mul_f32_e32 v158, 0xbfb8aa3b, v28
	v_exp_f32_e32 v171, v158
	v_cvt_pk_bf16_f32 v158, v140, v157
	v_cvt_pk_bf16_f32 v159, v159, v160
	v_cvt_pk_bf16_f32 v160, v161, v162
	v_cvt_pk_bf16_f32 v161, v163, v170
	global_store_dwordx4 v[130:131], v[158:161], off offset:256
	v_add_f32_e32 v140, 1.0, v171
	v_rcp_f32_e32 v162, v140
	v_mul_f32_e32 v160, 0xbfb8aa3b, v29
	v_exp_f32_e32 v160, v160
	v_lshl_add_u64 v[130:131], v[128:129], 0, s[18:19]
	v_add_f32_e32 v158, 1.0, v160
	v_rcp_f32_e32 v161, v158
	v_mul_f32_e32 v157, v28, v162
	v_mov_b32_e32 v140, v157
	v_mul_f32_e32 v162, 0xbfb8aa3b, v30
	v_exp_f32_e32 v162, v162
	s_nop 0
	v_add_f32_e32 v160, 1.0, v162
	v_rcp_f32_e32 v163, v160
	v_mul_f32_e32 v157, v29, v161
	v_mul_f32_e32 v161, 0xbfb8aa3b, v31
	v_exp_f32_e32 v161, v161
	s_nop 0
	v_add_f32_e32 v161, 1.0, v161
	v_rcp_f32_e32 v170, v161
	v_mul_f32_e32 v158, v30, v163
	v_mov_b32_e32 v159, v158
	v_mul_f32_e32 v163, 0xbfb8aa3b, v24
	v_exp_f32_e32 v163, v163
	s_nop 0
	v_add_f32_e32 v162, 1.0, v163
	v_rcp_f32_e32 v171, v162
	v_mul_f32_e32 v158, v31, v170
	v_mov_b32_e32 v160, v158
	v_mul_f32_e32 v170, 0xbfb8aa3b, v25
	v_exp_f32_e32 v170, v170
	s_nop 0
	v_add_f32_e32 v163, 1.0, v170
	v_rcp_f32_e32 v172, v163
	v_mul_f32_e32 v158, v24, v171
	v_mov_b32_e32 v161, v158
	v_mul_f32_e32 v171, 0xbfb8aa3b, v26
	v_exp_f32_e32 v171, v171
	s_nop 0
	v_add_f32_e32 v170, 1.0, v171
	v_rcp_f32_e32 v173, v170
	v_mul_f32_e32 v158, v25, v172
	v_mov_b32_e32 v162, v158
	v_mul_f32_e32 v172, 0xbfb8aa3b, v27
	v_exp_f32_e32 v172, v172
	s_nop 0
; __device__ __forceinline__ f32x4 silu4(f32x4 v) { f32x4 o; o[0] = silu_f(v[0]); o[1] = silu_f(v[1]); o[2] = silu_f(v[2]); o[3] = silu_f(v[3]); return o; }
;     __device__ __forceinline__ void operator()(const f32x4 (&acc)[2][2][4][2], const Unit& u, int wr, int wc, int fr, int fq) const {
;     ...
;                 for (int m = 0; m < 4; ++m) { bf16_t* rowp = base + (size_t)(row0 + ai * HALF + m * 16) * 2048;
; #pragma unroll
;                     for (int bj = 0; bj < 2; ++bj) st8(rowp + bj * HALF, silu4(acc[ai][bj][m][0]), silu4(acc[ai][bj][m][1])); }
	v_add_f32_e32 v171, 1.0, v172
	v_rcp_f32_e32 v174, v171
	v_mul_f32_e32 v158, v26, v173
	v_mov_b32_e32 v163, v158
	v_mul_f32_e32 v158, v27, v174
	v_mov_b32_e32 v170, v158
	v_cvt_pk_bf16_f32 v158, v140, v157
	v_mul_f32_e32 v140, 0xbfb8aa3b, v20
	v_exp_f32_e32 v140, v140
	v_cvt_pk_bf16_f32 v159, v159, v160
	v_cvt_pk_bf16_f32 v160, v161, v162
	v_cvt_pk_bf16_f32 v161, v163, v170
	v_add_co_u32_e32 v162, vcc, s70, v128
	v_add_f32_e32 v140, 1.0, v140
	v_rcp_f32_e32 v170, v140
	v_addc_co_u32_e32 v163, vcc, 0, v129, vcc
	global_store_dwordx4 v[162:163], v[158:161], off
	v_mul_f32_e32 v162, 0xbfb8aa3b, v22
	v_exp_f32_e32 v162, v162
	v_mul_f32_e32 v160, 0xbfb8aa3b, v21
	v_exp_f32_e32 v160, v160
	s_nop 0
	v_add_f32_e32 v158, 1.0, v160
	v_rcp_f32_e32 v161, v158
	v_mul_f32_e32 v157, v20, v170
	v_mov_b32_e32 v140, v157
	v_add_f32_e32 v160, 1.0, v162
	v_rcp_f32_e32 v163, v160
	v_mul_f32_e32 v157, v21, v161
	v_mul_f32_e32 v161, 0xbfb8aa3b, v23
	v_exp_f32_e32 v161, v161
	s_nop 0
	v_add_f32_e32 v161, 1.0, v161
	v_rcp_f32_e32 v170, v161
	v_mul_f32_e32 v158, v22, v163
	v_mov_b32_e32 v159, v158
	v_mul_f32_e32 v163, 0xbfb8aa3b, v16
	v_exp_f32_e32 v163, v163
	s_nop 0
	v_add_f32_e32 v162, 1.0, v163
	v_rcp_f32_e32 v171, v162
	v_mul_f32_e32 v158, v23, v170
	v_mov_b32_e32 v160, v158
	v_mul_f32_e32 v170, 0xbfb8aa3b, v17
	v_exp_f32_e32 v170, v170
	s_nop 0
	v_add_f32_e32 v163, 1.0, v170
	v_rcp_f32_e32 v172, v163
	v_mul_f32_e32 v158, v16, v171
	v_mov_b32_e32 v161, v158
	v_mul_f32_e32 v171, 0xbfb8aa3b, v18
	v_exp_f32_e32 v171, v171
	s_nop 0
	v_add_f32_e32 v170, 1.0, v171
	v_rcp_f32_e32 v173, v170
	v_mul_f32_e32 v158, v17, v172
	v_mov_b32_e32 v162, v158
	v_mul_f32_e32 v172, 0xbfb8aa3b, v19
	v_exp_f32_e32 v172, v172
	s_nop 0
	v_add_f32_e32 v171, 1.0, v172
	v_rcp_f32_e32 v174, v171
	v_mul_f32_e32 v158, v18, v173
	v_mov_b32_e32 v163, v158
	v_mul_f32_e32 v158, v19, v174
	v_mov_b32_e32 v170, v158
	v_mul_f32_e32 v158, 0xbfb8aa3b, v12
	v_exp_f32_e32 v171, v158
	v_cvt_pk_bf16_f32 v158, v140, v157
	v_cvt_pk_bf16_f32 v159, v159, v160
	v_cvt_pk_bf16_f32 v160, v161, v162
	v_cvt_pk_bf16_f32 v161, v163, v170
	global_store_dwordx4 v[130:131], v[158:161], off offset:256
	v_add_f32_e32 v140, 1.0, v171
	v_rcp_f32_e32 v162, v140
	v_mul_f32_e32 v160, 0xbfb8aa3b, v13
	v_exp_f32_e32 v160, v160
	v_lshl_add_u64 v[130:131], v[128:129], 0, s[20:21]
	v_add_f32_e32 v158, 1.0, v160
	v_rcp_f32_e32 v161, v158
	v_mul_f32_e32 v157, v12, v162
	v_mov_b32_e32 v140, v157
	v_mul_f32_e32 v162, 0xbfb8aa3b, v14
	v_exp_f32_e32 v162, v162
	s_nop 0
	v_add_f32_e32 v160, 1.0, v162
	v_rcp_f32_e32 v163, v160
	v_mul_f32_e32 v157, v13, v161
	v_mul_f32_e32 v161, 0xbfb8aa3b, v15
	v_exp_f32_e32 v161, v161
	s_nop 0
	v_add_f32_e32 v161, 1.0, v161
	v_rcp_f32_e32 v170, v161
	v_mul_f32_e32 v158, v14, v163
	v_mov_b32_e32 v159, v158
	v_mul_f32_e32 v163, 0xbfb8aa3b, v8
	v_exp_f32_e32 v163, v163
	s_nop 0
	v_add_f32_e32 v162, 1.0, v163
	v_rcp_f32_e32 v171, v162
	v_mul_f32_e32 v158, v15, v170
	v_mov_b32_e32 v160, v158
	v_mul_f32_e32 v170, 0xbfb8aa3b, v9
	v_exp_f32_e32 v170, v170
	s_nop 0
	v_add_f32_e32 v163, 1.0, v170
	v_rcp_f32_e32 v172, v163
	v_mul_f32_e32 v158, v8, v171
	v_mov_b32_e32 v161, v158
	v_mul_f32_e32 v171, 0xbfb8aa3b, v10
	v_exp_f32_e32 v171, v171
	s_nop 0
	v_add_f32_e32 v170, 1.0, v171
	v_rcp_f32_e32 v173, v170
	v_mul_f32_e32 v158, v9, v172
	v_mov_b32_e32 v162, v158
	v_mul_f32_e32 v172, 0xbfb8aa3b, v11
	v_exp_f32_e32 v172, v172
	s_nop 0
	v_add_f32_e32 v171, 1.0, v172
	v_rcp_f32_e32 v174, v171
	v_mul_f32_e32 v158, v10, v173
	v_mov_b32_e32 v163, v158
	v_mul_f32_e32 v158, v11, v174
	v_mov_b32_e32 v170, v158
	v_cvt_pk_bf16_f32 v158, v140, v157
	v_mul_f32_e32 v140, 0xbfb8aa3b, v4
	v_exp_f32_e32 v140, v140
	v_cvt_pk_bf16_f32 v159, v159, v160
	v_cvt_pk_bf16_f32 v160, v161, v162
	v_add_co_u32_e32 v128, vcc, s71, v128
	v_add_f32_e32 v140, 1.0, v140
	v_rcp_f32_e32 v162, v140
	v_addc_co_u32_e32 v129, vcc, 0, v129, vcc
	v_cvt_pk_bf16_f32 v161, v163, v170
	global_store_dwordx4 v[128:129], v[158:161], off
	s_nop 0
	s_nop 1
	v_mul_f32_e32 v158, 0xbfb8aa3b, v5
	v_exp_f32_e32 v158, v158
	s_nop 0
	v_add_f32_e32 v157, 1.0, v158
	v_rcp_f32_e32 v159, v157
	v_mul_f32_e32 v128, v4, v162
	v_mul_f32_e32 v160, 0xbfb8aa3b, v6
	v_exp_f32_e32 v160, v160
	s_nop 0
	v_add_f32_e32 v158, 1.0, v160
	v_rcp_f32_e32 v161, v158
	v_mul_f32_e32 v129, v5, v159
	v_mul_f32_e32 v159, 0xbfb8aa3b, v7
	v_exp_f32_e32 v159, v159
	s_nop 0
	v_add_f32_e32 v159, 1.0, v159
	v_rcp_f32_e32 v162, v159
	v_mul_f32_e32 v140, v6, v161
	v_mul_f32_e32 v161, 0xbfb8aa3b, v0
	v_exp_f32_e32 v161, v161
	s_nop 0
	v_add_f32_e32 v160, 1.0, v161
	v_rcp_f32_e32 v163, v160
	v_mul_f32_e32 v157, v7, v162
	v_mul_f32_e32 v162, 0xbfb8aa3b, v1
	v_exp_f32_e32 v162, v162
	s_nop 0
	v_add_f32_e32 v161, 1.0, v162
	v_rcp_f32_e32 v170, v161
	v_mul_f32_e32 v158, v0, v163
	v_mov_b32_e32 v160, v158
	v_mul_f32_e32 v163, 0xbfb8aa3b, v2
	v_exp_f32_e32 v163, v163
	s_nop 0
	v_add_f32_e32 v162, 1.0, v163
	v_rcp_f32_e32 v171, v162
	v_mul_f32_e32 v158, v1, v170
	v_mov_b32_e32 v161, v158
	v_mul_f32_e32 v170, 0xbfb8aa3b, v3
	v_exp_f32_e32 v170, v170
	s_nop 0
	v_add_f32_e32 v163, 1.0, v170
	v_rcp_f32_e32 v172, v163
	v_mul_f32_e32 v158, v2, v171
	v_mov_b32_e32 v162, v158
	v_mul_f32_e32 v158, v3, v172
	v_mov_b32_e32 v163, v158
	v_cvt_pk_bf16_f32 v158, v128, v129
	v_cvt_pk_bf16_f32 v159, v140, v157
	v_cvt_pk_bf16_f32 v160, v160, v161
	v_cvt_pk_bf16_f32 v161, v162, v163
	global_store_dwordx4 v[130:131], v[158:161], off offset:256

;     __device__ __forceinline__ void operator()(const f32x4 (&acc)[2][2][4][2], const Unit& u, int wr, int wc, int fr, int fq) const {
;     ...
;         } else {
;             const f32x4 invf = *(const f32x4*)(INVF64 + 16 * (wc & 1) + 4 * fq);
; #pragma unroll
;             for (int ai = 0; ai < 2; ++ai)
; #pragma unroll
;                 for (int m = 0; m < 4; ++m) { const int row = row0 + ai * HALF + m * 16; const float rs = rsqrtf(ssq[row] * (1.0f / 512.0f) + EPS); const float p = (float)pos[row];
;                     float sn[4], cs[4];
; #pragma unroll
;                     for (int e = 0; e < 4; ++e) sincos_rr(p * invf[e], sn[e], cs[e]);
; #pragma unroll
;                     for (int bj = 0; bj < 2; ++bj) { const int head = 4 * (u.pn - 8) + 2 * bj + (wc >> 1); f32x4 o0, o1;
; #pragma unroll
;                         for (int e = 0; e < 4; ++e) { const float x1 = acc[ai][bj][m][0][e] * rs, x2 = acc[ai][bj][m][1][e] * rs;
;                             o0[e] = x1 * cs[e] - x2 * sn[e]; o1[e] = x2 * cs[e] + x1 * sn[e]; }
;                         st8(QR + (size_t)row * 1024 + head * 64 + 32 * (wc & 1) + 8 * fq, o0, o1); } }
.LBB0_869:
	v_lshlrev_b64 v[128:129], 2, v[160:161]
	v_lshl_add_u64 v[162:163], s[38:39], 0, v[128:129]
	v_lshl_add_u64 v[164:165], s[44:45], 0, v[128:129]
	global_load_dword v155, v[162:163], off
	global_load_dword v183, v[164:165], off
	global_load_dword v240, v[162:163], off offset:64
	global_load_dword v241, v[162:163], off offset:128
	global_load_dword v242, v[162:163], off offset:192
	global_load_dword v243, v[162:163], off offset:512
	global_load_dword v244, v[162:163], off offset:576
	global_load_dword v245, v[162:163], off offset:640
	global_load_dword v246, v[162:163], off offset:704
	global_load_dword v247, v[164:165], off offset:64
	global_load_dword v248, v[164:165], off offset:128
	global_load_dword v249, v[164:165], off offset:192
	global_load_dword v250, v[164:165], off offset:512
	global_load_dword v251, v[164:165], off offset:576
	global_load_dword v252, v[164:165], off offset:640
	global_load_dword v253, v[164:165], off offset:704
	global_load_dwordx4 v[128:131], v[142:143], off
	s_lshl_b32 s0, s80, 8
	v_lshlrev_b64 v[166:167], 11, v[160:161]
	s_add_i32 s8, s0, s64
	v_mov_b32_e32 v184, v124
	v_mov_b32_e32 v185, v120
	v_mov_b32_e32 v186, v125
	v_mov_b32_e32 v187, v121
	v_mov_b32_e32 v188, v126
	v_mov_b32_e32 v189, v122
	v_mov_b32_e32 v190, v127
	v_mov_b32_e32 v191, v123
	v_mov_b32_e32 v192, v116
	v_mov_b32_e32 v193, v112
	v_lshl_add_u64 v[166:167], s[12:13], 0, v[166:167]
	s_lshl_b64 s[0:1], s[8:9], 1
	s_mov_b32 s19, s9
	v_lshl_add_u64 v[166:167], v[166:167], 0, s[0:1]
	v_lshl_add_u64 v[166:167], v[166:167], 0, s[18:19]
	v_lshl_add_u64 v[166:167], v[166:167], 0, v[140:141]
	s_waitcnt vmcnt(0)
	v_cvt_f32_i32_e32 v183, v183
	v_fmamk_f32 v155, v155, 0x3b000000, v182
	v_mul_f32_e32 v194, 0x4b800000, v155
	v_cmp_gt_f32_e32 vcc, s69, v155
	v_mul_f32_e32 v195, v128, v183
	v_mul_f32_e32 v196, v129, v183
	v_cndmask_b32_e32 v155, v155, v194, vcc
	v_rsq_f32_e32 v155, v155
	v_mul_f32_e32 v197, v130, v183
	v_mul_f32_e32 v183, v131, v183
	v_mul_f32_e32 v194, 0.15915494, v195
	v_mul_f32_e32 v198, 0.15915494, v196
	v_mul_f32_e32 v199, 0.15915494, v197
	v_mul_f32_e32 v200, 0.15915494, v183
	v_rndne_f32_e32 v194, v194
	v_rndne_f32_e32 v198, v198
	v_rndne_f32_e32 v199, v199
	v_rndne_f32_e32 v200, v200
	v_fmac_f32_e32 v195, 0xc0c90fdb, v194
	v_fmac_f32_e32 v196, 0xc0c90fdb, v198
	v_fmac_f32_e32 v197, 0xc0c90fdb, v199
	v_mul_f32_e32 v201, 0x45800000, v155
	v_fmac_f32_e32 v183, 0xc0c90fdb, v200
	v_fmac_f32_e32 v195, 0x343bbd2e, v194
	v_fmac_f32_e32 v196, 0x343bbd2e, v198
	v_fmac_f32_e32 v197, 0x343bbd2e, v199
	v_fmac_f32_e32 v183, 0x343bbd2e, v200
	v_cndmask_b32_e32 v194, v155, v201, vcc
	v_mul_f32_e32 v155, 0.15915494, v195
	v_mul_f32_e32 v195, 0.15915494, v196
	v_mul_f32_e32 v200, 0.15915494, v197
	v_mul_f32_e32 v183, 0.15915494, v183
	v_sin_f32_e32 v197, v155
	v_cos_f32_e32 v196, v155
	v_sin_f32_e32 v199, v195
	v_cos_f32_e32 v198, v195
	v_sin_f32_e32 v201, v200
	v_cos_f32_e32 v200, v200
	v_sin_f32_e32 v203, v183
	v_cos_f32_e32 v202, v183
	v_pk_mul_f32 v[184:185], v[184:185], v[194:195] op_sel_hi:[1,0]
	v_pk_mul_f32 v[186:187], v[186:187], v[194:195] op_sel_hi:[1,0]
	v_pk_mul_f32 v[188:189], v[188:189], v[194:195] op_sel_hi:[1,0]
	v_pk_mul_f32 v[190:191], v[190:191], v[194:195] op_sel_hi:[1,0]
	v_pk_mul_f32 v[192:193], v[192:193], v[194:195] op_sel_hi:[1,0]
	v_mov_b32_e32 v206, v197
	v_mov_b32_e32 v207, v196
	v_mov_b32_e32 v210, v199
	v_mov_b32_e32 v211, v198
	v_mov_b32_e32 v214, v201
	v_mov_b32_e32 v215, v200
	v_pk_mul_f32 v[204:205], v[184:185], v[196:197]
	v_pk_mul_f32 v[208:209], v[186:187], v[198:199]
	v_pk_mul_f32 v[212:213], v[188:189], v[200:201]
	v_pk_mul_f32 v[216:217], v[190:191], v[202:203]
	v_mov_b32_e32 v218, v203
	v_mov_b32_e32 v219, v202
	v_pk_mul_f32 v[196:197], v[192:193], v[196:197]
	v_pk_mul_f32 v[184:185], v[184:185], v[206:207]
	v_pk_mul_f32 v[186:187], v[186:187], v[210:211]
	v_pk_mul_f32 v[188:189], v[188:189], v[214:215]
	v_sub_f32_e32 v155, v204, v205
	v_sub_f32_e32 v183, v208, v209
	v_sub_f32_e32 v195, v212, v213
	v_sub_f32_e32 v204, v216, v217
	v_pk_mul_f32 v[190:191], v[190:191], v[218:219]
	v_sub_f32_e32 v196, v196, v197
	v_add_f32_e32 v197, v184, v185
	v_add_f32_e32 v186, v186, v187
	v_add_f32_e32 v187, v188, v189
	v_cvt_pk_bf16_f32 v184, v155, v183
	v_cvt_pk_bf16_f32 v185, v195, v204
	v_add_f32_e32 v188, v190, v191
	v_cvt_pk_bf16_f32 v186, v197, v186
	v_cvt_pk_bf16_f32 v187, v187, v188
	global_store_dwordx4 v[166:167], v[184:187], off
	v_mov_b32_e32 v191, v106
	s_nop 0
	v_pk_mul_f32 v[184:185], v[192:193], v[206:207]
	s_nop 0
	v_add_f32_e32 v155, v184, v185
	v_mov_b32_e32 v184, v117
	v_mov_b32_e32 v185, v113
	v_pk_mul_f32 v[184:185], v[184:185], v[194:195] op_sel_hi:[1,0]
	s_nop 0
	v_pk_mul_f32 v[186:187], v[184:185], v[198:199]
	v_pk_mul_f32 v[184:185], v[184:185], v[210:211]
	v_sub_f32_e32 v183, v186, v187
	v_add_f32_e32 v188, v184, v185
	v_mov_b32_e32 v184, v118
	v_mov_b32_e32 v185, v114
	v_pk_mul_f32 v[184:185], v[184:185], v[194:195] op_sel_hi:[1,0]
	s_nop 0
	v_pk_mul_f32 v[186:187], v[184:185], v[200:201]
	v_pk_mul_f32 v[184:185], v[184:185], v[214:215]
	v_sub_f32_e32 v189, v186, v187
	v_add_f32_e32 v190, v184, v185
	v_mov_b32_e32 v184, v119
	v_mov_b32_e32 v185, v115
	v_pk_mul_f32 v[184:185], v[184:185], v[194:195] op_sel_hi:[1,0]
	s_nop 0
	v_pk_mul_f32 v[186:187], v[184:185], v[202:203]
	v_pk_mul_f32 v[184:185], v[184:185], v[218:219]
	v_sub_f32_e32 v186, v186, v187
	v_add_f32_e32 v187, v184, v185
	v_cvt_pk_bf16_f32 v184, v196, v183
	v_cvt_pk_bf16_f32 v185, v189, v186
	v_cvt_pk_bf16_f32 v186, v155, v188
	v_cvt_pk_bf16_f32 v187, v190, v187
	global_store_dwordx4 v[166:167], v[184:187], off offset:256
;     __device__ __forceinline__ void operator()(const f32x4 (&acc)[2][2][4][2], const Unit& u, int wr, int wc, int fr, int fq) const {
;     ...
;                 for (int m = 0; m < 4; ++m) { const int row = row0 + ai * HALF + m * 16; const float rs = rsqrtf(ssq[row] * (1.0f / 512.0f) + EPS); const float p = (float)pos[row];
;                     float sn[4], cs[4];
; #pragma unroll
;                     for (int e = 0; e < 4; ++e) sincos_rr(p * invf[e], sn[e], cs[e]);
; #pragma unroll
;                     for (int bj = 0; bj < 2; ++bj) { const int head = 4 * (u.pn - 8) + 2 * bj + (wc >> 1); f32x4 o0, o1;
; #pragma unroll
;                         for (int e = 0; e < 4; ++e) { const float x1 = acc[ai][bj][m][0][e] * rs, x2 = acc[ai][bj][m][1][e] * rs;
;                             o0[e] = x1 * cs[e] - x2 * sn[e]; o1[e] = x2 * cs[e] + x1 * sn[e]; }
;                         st8(QR + (size_t)row * 1024 + head * 64 + 32 * (wc & 1) + 8 * fq, o0, o1); } }
	v_mov_b32_e32 v190, v110
	v_mov_b32_e32 v188, v109
	v_lshl_add_u64 v[184:185], v[158:159], 2, s[38:39]
	s_nop 1
	v_mov_b32_e32 v155, v240
	s_nop 1
	v_mov_b32_e32 v183, v247
	v_mov_b32_e32 v186, v108
	v_mov_b32_e32 v187, v104
	v_mov_b32_e32 v189, v105
	v_lshlrev_b64 v[184:185], 11, v[158:159]
	v_lshl_add_u64 v[184:185], s[12:13], 0, v[184:185]
	v_lshl_add_u64 v[184:185], v[184:185], 0, s[0:1]
	v_lshl_add_u64 v[184:185], v[184:185], 0, s[18:19]
	v_fmamk_f32 v155, v155, 0x3b000000, v182
	v_cvt_f32_i32_e32 v183, v183
	v_mul_f32_e32 v192, 0x4b800000, v155
	v_cmp_gt_f32_e32 vcc, s69, v155
	v_mul_f32_e32 v193, v128, v183
	s_nop 0
	v_cndmask_b32_e32 v155, v155, v192, vcc
	v_rsq_f32_e32 v155, v155
	v_mul_f32_e32 v194, v129, v183
	v_mul_f32_e32 v195, v130, v183
	v_mul_f32_e32 v192, 0.15915494, v193
	v_mul_f32_e32 v183, v131, v183
	v_mul_f32_e32 v196, 0.15915494, v194
	v_mul_f32_e32 v197, 0.15915494, v195
	v_rndne_f32_e32 v192, v192
	v_mul_f32_e32 v198, 0.15915494, v183
	v_rndne_f32_e32 v196, v196
	v_rndne_f32_e32 v197, v197
	v_fmac_f32_e32 v193, 0xc0c90fdb, v192
	v_rndne_f32_e32 v198, v198
	v_mul_f32_e32 v199, 0x45800000, v155
	v_fmac_f32_e32 v194, 0xc0c90fdb, v196
	v_fmac_f32_e32 v195, 0xc0c90fdb, v197
	v_fmac_f32_e32 v193, 0x343bbd2e, v192
	v_fmac_f32_e32 v183, 0xc0c90fdb, v198
	v_fmac_f32_e32 v194, 0x343bbd2e, v196
	v_fmac_f32_e32 v195, 0x343bbd2e, v197
	v_cndmask_b32_e32 v192, v155, v199, vcc
	v_mul_f32_e32 v155, 0.15915494, v193
	v_fmac_f32_e32 v183, 0x343bbd2e, v198
	v_mul_f32_e32 v193, 0.15915494, v194
	v_mul_f32_e32 v198, 0.15915494, v195
	v_sin_f32_e32 v195, v155
	v_cos_f32_e32 v194, v155
	v_sin_f32_e32 v199, v198
	v_cos_f32_e32 v198, v198
	v_sin_f32_e32 v197, v193
	v_cos_f32_e32 v196, v193
	v_mul_f32_e32 v183, 0.15915494, v183
	v_pk_mul_f32 v[186:187], v[186:187], v[192:193] op_sel_hi:[1,0]
	v_pk_mul_f32 v[190:191], v[190:191], v[192:193] op_sel_hi:[1,0]
	v_sin_f32_e32 v201, v183
	v_cos_f32_e32 v200, v183
	v_mov_b32_e32 v204, v195
	v_mov_b32_e32 v205, v194
	v_pk_mul_f32 v[202:203], v[186:187], v[194:195]
	v_pk_mul_f32 v[210:211], v[190:191], v[198:199]
	v_pk_mul_f32 v[186:187], v[186:187], v[204:205]
	v_pk_mul_f32 v[188:189], v[188:189], v[192:193] op_sel_hi:[1,0]
	v_mov_b32_e32 v208, v197
	v_mov_b32_e32 v209, v196
	v_sub_f32_e32 v155, v202, v203
	v_sub_f32_e32 v193, v210, v211
	v_add_f32_e32 v202, v186, v187
	v_mov_b32_e32 v186, v111
	v_mov_b32_e32 v187, v107
	v_pk_mul_f32 v[206:207], v[188:189], v[196:197]
	v_pk_mul_f32 v[188:189], v[188:189], v[208:209]
	v_pk_mul_f32 v[186:187], v[186:187], v[192:193] op_sel_hi:[1,0]
	v_add_f32_e32 v203, v188, v189
	v_pk_mul_f32 v[188:189], v[186:187], v[200:201]
	v_mov_b32_e32 v212, v199
	v_mov_b32_e32 v213, v198
	v_sub_f32_e32 v183, v206, v207
	v_sub_f32_e32 v207, v188, v189
	v_mov_b32_e32 v188, v201
	v_mov_b32_e32 v189, v200
	v_pk_mul_f32 v[190:191], v[190:191], v[212:213]
	v_pk_mul_f32 v[186:187], v[186:187], v[188:189]
	v_add_f32_e32 v206, v190, v191
	v_add_f32_e32 v187, v186, v187
	v_lshl_add_u64 v[190:191], v[184:185], 0, v[140:141]
	v_cvt_pk_bf16_f32 v184, v155, v183
	v_cvt_pk_bf16_f32 v185, v193, v207
	v_cvt_pk_bf16_f32 v186, v202, v203
	v_cvt_pk_bf16_f32 v187, v206, v187
	global_store_dwordx4 v[190:191], v[184:187], off
	s_nop 1
	v_mov_b32_e32 v184, v100
	v_mov_b32_e32 v185, v96
	v_pk_mul_f32 v[184:185], v[184:185], v[192:193] op_sel_hi:[1,0]
	s_nop 0
	v_pk_mul_f32 v[186:187], v[184:185], v[194:195]
	v_pk_mul_f32 v[184:185], v[184:185], v[204:205]
	v_sub_f32_e32 v155, v186, v187
	v_add_f32_e32 v183, v184, v185
	v_mov_b32_e32 v184, v101
	v_mov_b32_e32 v185, v97
	v_pk_mul_f32 v[184:185], v[184:185], v[192:193] op_sel_hi:[1,0]
	s_nop 0
	v_pk_mul_f32 v[186:187], v[184:185], v[196:197]
	v_pk_mul_f32 v[184:185], v[184:185], v[208:209]
	v_sub_f32_e32 v193, v186, v187
	v_add_f32_e32 v194, v184, v185
	v_mov_b32_e32 v184, v102
	v_mov_b32_e32 v185, v98
	v_pk_mul_f32 v[184:185], v[184:185], v[192:193] op_sel_hi:[1,0]
	s_nop 0
	v_pk_mul_f32 v[186:187], v[184:185], v[198:199]
	v_pk_mul_f32 v[184:185], v[184:185], v[212:213]
	v_sub_f32_e32 v195, v186, v187
	v_add_f32_e32 v196, v184, v185
	v_mov_b32_e32 v184, v103
	v_mov_b32_e32 v185, v99
	v_pk_mul_f32 v[184:185], v[184:185], v[192:193] op_sel_hi:[1,0]
	s_nop 0
	v_pk_mul_f32 v[186:187], v[184:185], v[200:201]
	v_pk_mul_f32 v[184:185], v[184:185], v[188:189]
	v_sub_f32_e32 v186, v186, v187
	v_add_f32_e32 v187, v184, v185
	v_cvt_pk_bf16_f32 v184, v155, v193
	v_cvt_pk_bf16_f32 v185, v195, v186
	v_cvt_pk_bf16_f32 v186, v183, v194
	v_cvt_pk_bf16_f32 v187, v196, v187
	global_store_dwordx4 v[190:191], v[184:187], off offset:256
	s_nop 1
	v_lshl_add_u64 v[184:185], v[156:157], 2, s[38:39]
	s_nop 1
	v_mov_b32_e32 v155, v241
	s_nop 1
	v_mov_b32_e32 v183, v248
	v_fmamk_f32 v155, v155, 0x3b000000, v182
	v_cvt_f32_i32_e32 v183, v183
	v_mul_f32_e32 v184, 0x4b800000, v155
	v_cmp_gt_f32_e32 vcc, s69, v155
	v_mul_f32_e32 v185, v129, v183
	s_nop 0
	v_cndmask_b32_e32 v155, v155, v184, vcc
	v_mul_f32_e32 v184, v128, v183
	v_mul_f32_e32 v187, 0.15915494, v184
	v_mul_f32_e32 v186, v130, v183
	v_rndne_f32_e32 v187, v187
	v_rsq_f32_e32 v155, v155
	v_mul_f32_e32 v188, 0.15915494, v185
	v_mul_f32_e32 v189, 0.15915494, v186
	v_fmac_f32_e32 v184, 0xc0c90fdb, v187
	v_rndne_f32_e32 v188, v188
	v_rndne_f32_e32 v189, v189
	v_fmac_f32_e32 v184, 0x343bbd2e, v187
	v_fmac_f32_e32 v185, 0xc0c90fdb, v188
	v_fmac_f32_e32 v186, 0xc0c90fdb, v189
	v_mul_f32_e32 v184, 0.15915494, v184
	v_fmac_f32_e32 v185, 0x343bbd2e, v188
	v_fmac_f32_e32 v186, 0x343bbd2e, v189
	v_sin_f32_e32 v189, v184
	v_cos_f32_e32 v188, v184
	v_mul_f32_e32 v183, v131, v183
	v_mul_f32_e32 v196, 0x45800000, v155
;     __device__ __forceinline__ void operator()(const f32x4 (&acc)[2][2][4][2], const Unit& u, int wr, int wc, int fr, int fq) const {
;     ...
;                 for (int m = 0; m < 4; ++m) { const int row = row0 + ai * HALF + m * 16; const float rs = rsqrtf(ssq[row] * (1.0f / 512.0f) + EPS); const float p = (float)pos[row];
;                     float sn[4], cs[4];
; #pragma unroll
;                     for (int e = 0; e < 4; ++e) sincos_rr(p * invf[e], sn[e], cs[e]);
; #pragma unroll
;                     for (int bj = 0; bj < 2; ++bj) { const int head = 4 * (u.pn - 8) + 2 * bj + (wc >> 1); f32x4 o0, o1;
; #pragma unroll
;                         for (int e = 0; e < 4; ++e) { const float x1 = acc[ai][bj][m][0][e] * rs, x2 = acc[ai][bj][m][1][e] * rs;
;                             o0[e] = x1 * cs[e] - x2 * sn[e]; o1[e] = x2 * cs[e] + x1 * sn[e]; }
;                         st8(QR + (size_t)row * 1024 + head * 64 + 32 * (wc & 1) + 8 * fq, o0, o1); } }
	v_mul_f32_e32 v186, 0.15915494, v186
	v_mul_f32_e32 v190, 0.15915494, v183
	v_sin_f32_e32 v193, v186
	v_cos_f32_e32 v192, v186
	v_cndmask_b32_e32 v196, v155, v196, vcc
	v_mov_b32_e32 v186, v92
	v_mov_b32_e32 v187, v88
	v_rndne_f32_e32 v190, v190
	v_pk_mul_f32 v[186:187], v[186:187], v[196:197] op_sel_hi:[1,0]
	v_fmac_f32_e32 v183, 0xc0c90fdb, v190
	v_mul_f32_e32 v185, 0.15915494, v185
	v_pk_mul_f32 v[198:199], v[186:187], v[188:189]
	v_fmac_f32_e32 v183, 0x343bbd2e, v190
	v_sin_f32_e32 v191, v185
	v_cos_f32_e32 v190, v185
	v_sub_f32_e32 v155, v198, v199
	v_mov_b32_e32 v198, v189
	v_mov_b32_e32 v199, v188
	v_mul_f32_e32 v183, 0.15915494, v183
	v_pk_mul_f32 v[186:187], v[186:187], v[198:199]
	v_sin_f32_e32 v195, v183
	v_cos_f32_e32 v194, v183
	v_add_f32_e32 v183, v186, v187
	v_mov_b32_e32 v186, v93
	v_mov_b32_e32 v187, v89
	v_pk_mul_f32 v[186:187], v[186:187], v[196:197] op_sel_hi:[1,0]
	v_lshlrev_b64 v[184:185], 11, v[156:157]
	v_pk_mul_f32 v[200:201], v[186:187], v[190:191]
	v_lshl_add_u64 v[184:185], s[12:13], 0, v[184:185]
	v_sub_f32_e32 v197, v200, v201
	v_mov_b32_e32 v200, v191
	v_mov_b32_e32 v201, v190
	v_pk_mul_f32 v[186:187], v[186:187], v[200:201]
	v_lshl_add_u64 v[184:185], v[184:185], 0, s[0:1]
	v_add_f32_e32 v208, v186, v187
	v_mov_b32_e32 v186, v94
	v_mov_b32_e32 v187, v90
	v_pk_mul_f32 v[186:187], v[186:187], v[196:197] op_sel_hi:[1,0]
	v_lshl_add_u64 v[184:185], v[184:185], 0, s[18:19]
	v_pk_mul_f32 v[202:203], v[186:187], v[192:193]
	v_lshl_add_u64 v[206:207], v[184:185], 0, v[140:141]
	v_sub_f32_e32 v209, v202, v203
	v_mov_b32_e32 v202, v193
	v_mov_b32_e32 v203, v192
	v_pk_mul_f32 v[186:187], v[186:187], v[202:203]
	v_cvt_pk_bf16_f32 v184, v155, v197
	s_nop 0
	v_add_f32_e32 v210, v186, v187
	v_mov_b32_e32 v186, v95
	v_mov_b32_e32 v187, v91
	v_pk_mul_f32 v[186:187], v[186:187], v[196:197] op_sel_hi:[1,0]
	s_nop 0
	v_pk_mul_f32 v[204:205], v[186:187], v[194:195]
	s_nop 0
	v_sub_f32_e32 v211, v204, v205
	v_mov_b32_e32 v204, v195
	v_mov_b32_e32 v205, v194
	v_pk_mul_f32 v[186:187], v[186:187], v[204:205]
	v_cvt_pk_bf16_f32 v185, v209, v211
	s_nop 0
	v_add_f32_e32 v187, v186, v187
	v_cvt_pk_bf16_f32 v186, v183, v208
	v_cvt_pk_bf16_f32 v187, v210, v187
	global_store_dwordx4 v[206:207], v[184:187], off
	s_nop 1
	v_mov_b32_e32 v184, v84
	v_mov_b32_e32 v185, v76
	v_pk_mul_f32 v[184:185], v[184:185], v[196:197] op_sel_hi:[1,0]
	s_nop 0
	v_pk_mul_f32 v[186:187], v[184:185], v[188:189]
	v_pk_mul_f32 v[184:185], v[184:185], v[198:199]
	v_sub_f32_e32 v155, v186, v187
	v_add_f32_e32 v183, v184, v185
	v_mov_b32_e32 v184, v85
	v_mov_b32_e32 v185, v77
	v_pk_mul_f32 v[184:185], v[184:185], v[196:197] op_sel_hi:[1,0]
	s_nop 0
	v_pk_mul_f32 v[186:187], v[184:185], v[190:191]
	v_pk_mul_f32 v[184:185], v[184:185], v[200:201]
	v_sub_f32_e32 v188, v186, v187
	v_add_f32_e32 v189, v184, v185
	v_mov_b32_e32 v184, v86
	v_mov_b32_e32 v185, v78
	v_pk_mul_f32 v[184:185], v[184:185], v[196:197] op_sel_hi:[1,0]
	s_nop 0
	v_pk_mul_f32 v[186:187], v[184:185], v[192:193]
	v_pk_mul_f32 v[184:185], v[184:185], v[202:203]
	v_sub_f32_e32 v190, v186, v187
	v_add_f32_e32 v191, v184, v185
	v_mov_b32_e32 v184, v87
	v_mov_b32_e32 v185, v79
	v_pk_mul_f32 v[184:185], v[184:185], v[196:197] op_sel_hi:[1,0]
	s_nop 0
	v_pk_mul_f32 v[186:187], v[184:185], v[194:195]
	v_pk_mul_f32 v[184:185], v[184:185], v[204:205]
	v_sub_f32_e32 v186, v186, v187
	v_add_f32_e32 v187, v184, v185
	v_cvt_pk_bf16_f32 v184, v155, v188
	v_cvt_pk_bf16_f32 v185, v190, v186
	v_ashrrev_i32_e32 v155, 31, v154
	v_cvt_pk_bf16_f32 v186, v183, v189
	v_cvt_pk_bf16_f32 v187, v191, v187
	global_store_dwordx4 v[206:207], v[184:187], off offset:256
	s_nop 1
	v_lshl_add_u64 v[184:185], v[154:155], 2, s[38:39]
	s_nop 1
	v_mov_b32_e32 v183, v242
	s_nop 0
	s_nop 1
	v_mov_b32_e32 v184, v249
	v_fmamk_f32 v183, v183, 0x3b000000, v182
	v_cvt_f32_i32_e32 v184, v184
	v_mul_f32_e32 v185, 0x4b800000, v183
	v_cmp_gt_f32_e32 vcc, s69, v183
	v_mul_f32_e32 v186, v129, v184
	s_nop 0
	v_cndmask_b32_e32 v183, v183, v185, vcc
	v_mul_f32_e32 v185, v128, v184
	v_mul_f32_e32 v187, 0.15915494, v185
	v_rndne_f32_e32 v187, v187
	v_fmac_f32_e32 v185, 0xc0c90fdb, v187
	v_fmac_f32_e32 v185, 0x343bbd2e, v187
	v_mul_f32_e32 v185, 0.15915494, v185
	v_sin_f32_e32 v189, v185
	v_cos_f32_e32 v188, v185
	v_mul_f32_e32 v185, 0.15915494, v186
	v_rndne_f32_e32 v185, v185
	v_fmac_f32_e32 v186, 0xc0c90fdb, v185
	v_fmac_f32_e32 v186, 0x343bbd2e, v185
	v_mul_f32_e32 v185, 0.15915494, v186
	v_sin_f32_e32 v191, v185
	v_cos_f32_e32 v190, v185
	v_mul_f32_e32 v185, v130, v184
	v_mul_f32_e32 v186, 0.15915494, v185
	v_rndne_f32_e32 v186, v186
	v_rsq_f32_e32 v183, v183
	v_fmac_f32_e32 v185, 0xc0c90fdb, v186
	v_fmac_f32_e32 v185, 0x343bbd2e, v186
	v_mul_f32_e32 v185, 0.15915494, v185
	v_mul_f32_e32 v184, v131, v184
	v_sin_f32_e32 v193, v185
	v_cos_f32_e32 v192, v185
	v_mul_f32_e32 v185, 0.15915494, v184
	v_mul_f32_e32 v196, 0x45800000, v183
	v_rndne_f32_e32 v185, v185
	v_fmac_f32_e32 v184, 0xc0c90fdb, v185
	v_cndmask_b32_e32 v196, v183, v196, vcc
	v_mov_b32_e32 v186, v80
	v_mov_b32_e32 v187, v72
	v_fmac_f32_e32 v184, 0x343bbd2e, v185
	v_pk_mul_f32 v[186:187], v[186:187], v[196:197] op_sel_hi:[1,0]
	v_mul_f32_e32 v184, 0.15915494, v184
	v_pk_mul_f32 v[198:199], v[186:187], v[188:189]
	v_sin_f32_e32 v195, v184
	v_cos_f32_e32 v194, v184
	v_lshlrev_b64 v[184:185], 11, v[154:155]
	v_sub_f32_e32 v155, v198, v199
	v_mov_b32_e32 v198, v189
	v_mov_b32_e32 v199, v188
	v_pk_mul_f32 v[186:187], v[186:187], v[198:199]
	v_lshl_add_u64 v[184:185], s[12:13], 0, v[184:185]
	v_add_f32_e32 v183, v186, v187
	v_mov_b32_e32 v186, v81
	v_mov_b32_e32 v187, v73
;     __device__ __forceinline__ void operator()(const f32x4 (&acc)[2][2][4][2], const Unit& u, int wr, int wc, int fr, int fq) const {
;     ...
;                 for (int m = 0; m < 4; ++m) { const int row = row0 + ai * HALF + m * 16; const float rs = rsqrtf(ssq[row] * (1.0f / 512.0f) + EPS); const float p = (float)pos[row];
;                     float sn[4], cs[4];
; #pragma unroll
;                     for (int e = 0; e < 4; ++e) sincos_rr(p * invf[e], sn[e], cs[e]);
; #pragma unroll
;                     for (int bj = 0; bj < 2; ++bj) { const int head = 4 * (u.pn - 8) + 2 * bj + (wc >> 1); f32x4 o0, o1;
; #pragma unroll
;                         for (int e = 0; e < 4; ++e) { const float x1 = acc[ai][bj][m][0][e] * rs, x2 = acc[ai][bj][m][1][e] * rs;
;                             o0[e] = x1 * cs[e] - x2 * sn[e]; o1[e] = x2 * cs[e] + x1 * sn[e]; }
;                         st8(QR + (size_t)row * 1024 + head * 64 + 32 * (wc & 1) + 8 * fq, o0, o1); } }
	v_pk_mul_f32 v[186:187], v[186:187], v[196:197] op_sel_hi:[1,0]
	v_lshl_add_u64 v[184:185], v[184:185], 0, s[0:1]
	v_pk_mul_f32 v[200:201], v[186:187], v[190:191]
	v_lshl_add_u64 v[184:185], v[184:185], 0, s[18:19]
	v_sub_f32_e32 v197, v200, v201
	v_mov_b32_e32 v200, v191
	v_mov_b32_e32 v201, v190
	v_pk_mul_f32 v[186:187], v[186:187], v[200:201]
	v_lshl_add_u64 v[206:207], v[184:185], 0, v[140:141]
	v_add_f32_e32 v208, v186, v187
	v_mov_b32_e32 v186, v82
	v_mov_b32_e32 v187, v74
	v_pk_mul_f32 v[186:187], v[186:187], v[196:197] op_sel_hi:[1,0]
	v_cvt_pk_bf16_f32 v184, v155, v197
	s_mov_b64 s[0:1], 0x40000
	v_pk_mul_f32 v[202:203], v[186:187], v[192:193]
	s_nop 0
	v_sub_f32_e32 v209, v202, v203
	v_mov_b32_e32 v202, v193
	v_mov_b32_e32 v203, v192
	v_pk_mul_f32 v[186:187], v[186:187], v[202:203]
	s_nop 0
	v_add_f32_e32 v210, v186, v187
	v_mov_b32_e32 v186, v83
	v_mov_b32_e32 v187, v75
	v_pk_mul_f32 v[186:187], v[186:187], v[196:197] op_sel_hi:[1,0]
	s_nop 0
	v_pk_mul_f32 v[204:205], v[186:187], v[194:195]
	s_nop 0
	v_sub_f32_e32 v211, v204, v205
	v_mov_b32_e32 v204, v195
	v_mov_b32_e32 v205, v194
	v_pk_mul_f32 v[186:187], v[186:187], v[204:205]
	v_cvt_pk_bf16_f32 v185, v209, v211
	s_nop 0
	v_add_f32_e32 v187, v186, v187
	v_cvt_pk_bf16_f32 v186, v183, v208
	v_cvt_pk_bf16_f32 v187, v210, v187
	global_store_dwordx4 v[206:207], v[184:187], off
	s_nop 1
	v_mov_b32_e32 v184, v68
	v_mov_b32_e32 v185, v64
	v_pk_mul_f32 v[184:185], v[184:185], v[196:197] op_sel_hi:[1,0]
	s_nop 0
	v_pk_mul_f32 v[186:187], v[184:185], v[188:189]
	v_pk_mul_f32 v[184:185], v[184:185], v[198:199]
	v_sub_f32_e32 v155, v186, v187
	v_add_f32_e32 v183, v184, v185
	v_mov_b32_e32 v184, v69
	v_mov_b32_e32 v185, v65
	v_pk_mul_f32 v[184:185], v[184:185], v[196:197] op_sel_hi:[1,0]
	s_nop 0
	v_pk_mul_f32 v[186:187], v[184:185], v[190:191]
	v_pk_mul_f32 v[184:185], v[184:185], v[200:201]
	v_sub_f32_e32 v188, v186, v187
	v_add_f32_e32 v189, v184, v185
	v_mov_b32_e32 v184, v70
	v_mov_b32_e32 v185, v66
	v_pk_mul_f32 v[184:185], v[184:185], v[196:197] op_sel_hi:[1,0]
	s_nop 0
	v_pk_mul_f32 v[186:187], v[184:185], v[192:193]
	v_pk_mul_f32 v[184:185], v[184:185], v[202:203]
	v_sub_f32_e32 v190, v186, v187
	v_add_f32_e32 v191, v184, v185
	v_mov_b32_e32 v184, v71
	v_mov_b32_e32 v185, v67
	v_pk_mul_f32 v[184:185], v[184:185], v[196:197] op_sel_hi:[1,0]
	s_nop 0
	v_pk_mul_f32 v[186:187], v[184:185], v[194:195]
	v_pk_mul_f32 v[184:185], v[184:185], v[204:205]
	v_sub_f32_e32 v186, v186, v187
	v_add_f32_e32 v187, v184, v185
	v_cvt_pk_bf16_f32 v184, v155, v188
	v_cvt_pk_bf16_f32 v185, v190, v186
	v_cvt_pk_bf16_f32 v186, v183, v189
	v_cvt_pk_bf16_f32 v187, v191, v187
	global_store_dwordx4 v[206:207], v[184:187], off offset:256
	s_nop 1
	v_mov_b32_e32 v155, v243
	s_nop 1
	v_mov_b32_e32 v183, v250
	v_lshl_add_u64 v[206:207], v[166:167], 0, s[0:1]
	s_mov_b32 s0, 0x40000
	v_fmamk_f32 v155, v155, 0x3b000000, v182
	v_cvt_f32_i32_e32 v183, v183
	v_mul_f32_e32 v184, 0x4b800000, v155
	v_cmp_gt_f32_e32 vcc, s69, v155
	v_mul_f32_e32 v185, v128, v183
	v_mul_f32_e32 v186, 0.15915494, v185
	v_rndne_f32_e32 v186, v186
	v_fmac_f32_e32 v185, 0xc0c90fdb, v186
	v_fmac_f32_e32 v185, 0x343bbd2e, v186
	v_mul_f32_e32 v185, 0.15915494, v185
	v_sin_f32_e32 v189, v185
	v_cos_f32_e32 v188, v185
	v_mul_f32_e32 v185, v129, v183
	v_mul_f32_e32 v186, 0.15915494, v185
	v_rndne_f32_e32 v186, v186
	v_fmac_f32_e32 v185, 0xc0c90fdb, v186
	v_fmac_f32_e32 v185, 0x343bbd2e, v186
	v_mul_f32_e32 v185, 0.15915494, v185
	v_sin_f32_e32 v191, v185
	v_cos_f32_e32 v190, v185
	v_mul_f32_e32 v185, v130, v183
	v_mul_f32_e32 v186, 0.15915494, v185
	v_rndne_f32_e32 v186, v186
	v_cndmask_b32_e32 v155, v155, v184, vcc
	v_fmac_f32_e32 v185, 0xc0c90fdb, v186
	v_rsq_f32_e32 v155, v155
	v_fmac_f32_e32 v185, 0x343bbd2e, v186
	v_mul_f32_e32 v185, 0.15915494, v185
	v_mul_f32_e32 v183, v131, v183
	v_sin_f32_e32 v193, v185
	v_cos_f32_e32 v192, v185
	v_mul_f32_e32 v185, 0.15915494, v183
	v_rndne_f32_e32 v185, v185
	v_mul_f32_e32 v184, 0x45800000, v155
	v_fmac_f32_e32 v183, 0xc0c90fdb, v185
	v_fmac_f32_e32 v183, 0x343bbd2e, v185
	v_cndmask_b32_e32 v196, v155, v184, vcc
	v_mov_b32_e32 v184, v60
	v_mov_b32_e32 v185, v56
	v_pk_mul_f32 v[184:185], v[184:185], v[196:197] op_sel_hi:[1,0]
	v_mov_b32_e32 v198, v189
	v_mov_b32_e32 v199, v188
	v_mul_f32_e32 v183, 0.15915494, v183
	v_pk_mul_f32 v[186:187], v[184:185], v[188:189]
	v_pk_mul_f32 v[184:185], v[184:185], v[198:199]
	v_sin_f32_e32 v195, v183
	v_cos_f32_e32 v194, v183
	v_add_f32_e32 v183, v184, v185
	v_mov_b32_e32 v184, v61
	v_mov_b32_e32 v185, v57
	v_pk_mul_f32 v[184:185], v[184:185], v[196:197] op_sel_hi:[1,0]
	v_mov_b32_e32 v200, v191
	v_mov_b32_e32 v201, v190
	v_sub_f32_e32 v155, v186, v187
	v_pk_mul_f32 v[186:187], v[184:185], v[190:191]
	v_pk_mul_f32 v[184:185], v[184:185], v[200:201]
	v_sub_f32_e32 v197, v186, v187
	v_add_f32_e32 v208, v184, v185
	v_mov_b32_e32 v184, v62
	v_mov_b32_e32 v185, v58
	v_pk_mul_f32 v[184:185], v[184:185], v[196:197] op_sel_hi:[1,0]
	v_mov_b32_e32 v202, v193
	v_mov_b32_e32 v203, v192
	v_pk_mul_f32 v[186:187], v[184:185], v[192:193]
	v_pk_mul_f32 v[184:185], v[184:185], v[202:203]
	v_sub_f32_e32 v209, v186, v187
	v_add_f32_e32 v210, v184, v185
	v_mov_b32_e32 v184, v63
	v_mov_b32_e32 v185, v59
	v_pk_mul_f32 v[184:185], v[184:185], v[196:197] op_sel_hi:[1,0]
	v_mov_b32_e32 v204, v195
	v_pk_mul_f32 v[186:187], v[184:185], v[194:195]
	v_mov_b32_e32 v205, v194
	v_sub_f32_e32 v186, v186, v187
	v_pk_mul_f32 v[184:185], v[184:185], v[204:205]
	s_nop 0
	v_add_f32_e32 v187, v184, v185
	v_cvt_pk_bf16_f32 v184, v155, v197
	v_cvt_pk_bf16_f32 v185, v209, v186
	v_cvt_pk_bf16_f32 v186, v183, v208
;     __device__ __forceinline__ void operator()(const f32x4 (&acc)[2][2][4][2], const Unit& u, int wr, int wc, int fr, int fq) const {
;     ...
;                 for (int m = 0; m < 4; ++m) { const int row = row0 + ai * HALF + m * 16; const float rs = rsqrtf(ssq[row] * (1.0f / 512.0f) + EPS); const float p = (float)pos[row];
;                     float sn[4], cs[4];
; #pragma unroll
;                     for (int e = 0; e < 4; ++e) sincos_rr(p * invf[e], sn[e], cs[e]);
; #pragma unroll
;                     for (int bj = 0; bj < 2; ++bj) { const int head = 4 * (u.pn - 8) + 2 * bj + (wc >> 1); f32x4 o0, o1;
; #pragma unroll
;                         for (int e = 0; e < 4; ++e) { const float x1 = acc[ai][bj][m][0][e] * rs, x2 = acc[ai][bj][m][1][e] * rs;
;                             o0[e] = x1 * cs[e] - x2 * sn[e]; o1[e] = x2 * cs[e] + x1 * sn[e]; }
;                         st8(QR + (size_t)row * 1024 + head * 64 + 32 * (wc & 1) + 8 * fq, o0, o1); } }
	v_add_co_u32_e32 v208, vcc, s0, v166
	v_cvt_pk_bf16_f32 v187, v210, v187
	s_mov_b64 s[0:1], 0x48000
	s_nop 0
	v_addc_co_u32_e32 v209, vcc, 0, v167, vcc
	global_store_dwordx4 v[208:209], v[184:187], off
	s_nop 1
	v_mov_b32_e32 v184, v52
	v_mov_b32_e32 v185, v48
	v_pk_mul_f32 v[184:185], v[184:185], v[196:197] op_sel_hi:[1,0]
	s_nop 0
	v_pk_mul_f32 v[186:187], v[184:185], v[188:189]
	v_pk_mul_f32 v[184:185], v[184:185], v[198:199]
	v_sub_f32_e32 v155, v186, v187
	v_add_f32_e32 v183, v184, v185
	v_mov_b32_e32 v184, v53
	v_mov_b32_e32 v185, v49
	v_pk_mul_f32 v[184:185], v[184:185], v[196:197] op_sel_hi:[1,0]
	s_nop 0
	v_pk_mul_f32 v[186:187], v[184:185], v[190:191]
	v_pk_mul_f32 v[184:185], v[184:185], v[200:201]
	v_sub_f32_e32 v188, v186, v187
	v_add_f32_e32 v189, v184, v185
	v_mov_b32_e32 v184, v54
	v_mov_b32_e32 v185, v50
	v_pk_mul_f32 v[184:185], v[184:185], v[196:197] op_sel_hi:[1,0]
	s_nop 0
	v_pk_mul_f32 v[186:187], v[184:185], v[192:193]
	v_pk_mul_f32 v[184:185], v[184:185], v[202:203]
	v_sub_f32_e32 v190, v186, v187
	v_add_f32_e32 v191, v184, v185
	v_mov_b32_e32 v184, v55
	v_mov_b32_e32 v185, v51
	v_pk_mul_f32 v[184:185], v[184:185], v[196:197] op_sel_hi:[1,0]
	s_nop 0
	v_pk_mul_f32 v[186:187], v[184:185], v[194:195]
	v_pk_mul_f32 v[184:185], v[184:185], v[204:205]
	v_sub_f32_e32 v186, v186, v187
	v_add_f32_e32 v187, v184, v185
	v_cvt_pk_bf16_f32 v184, v155, v188
	v_cvt_pk_bf16_f32 v185, v190, v186
	v_cvt_pk_bf16_f32 v186, v183, v189
	v_cvt_pk_bf16_f32 v187, v191, v187
	global_store_dwordx4 v[206:207], v[184:187], off offset:256
	s_nop 1
	v_mov_b32_e32 v155, v244
	s_nop 1
	v_mov_b32_e32 v183, v251
	v_lshl_add_u64 v[206:207], v[166:167], 0, s[0:1]
	v_fmamk_f32 v155, v155, 0x3b000000, v182
	v_cvt_f32_i32_e32 v183, v183
	v_mul_f32_e32 v184, 0x4b800000, v155
	v_cmp_gt_f32_e32 vcc, s69, v155
	v_mul_f32_e32 v185, v128, v183
	v_mul_f32_e32 v186, 0.15915494, v185
	v_rndne_f32_e32 v186, v186
	v_fmac_f32_e32 v185, 0xc0c90fdb, v186
	v_fmac_f32_e32 v185, 0x343bbd2e, v186
	v_mul_f32_e32 v185, 0.15915494, v185
	v_sin_f32_e32 v189, v185
	v_cos_f32_e32 v188, v185
	v_mul_f32_e32 v185, v129, v183
	v_mul_f32_e32 v186, 0.15915494, v185
	v_rndne_f32_e32 v186, v186
	v_fmac_f32_e32 v185, 0xc0c90fdb, v186
	v_fmac_f32_e32 v185, 0x343bbd2e, v186
	v_mul_f32_e32 v185, 0.15915494, v185
	v_sin_f32_e32 v191, v185
	v_cos_f32_e32 v190, v185
	v_mul_f32_e32 v185, v130, v183
	v_mul_f32_e32 v186, 0.15915494, v185
	v_rndne_f32_e32 v186, v186
	v_cndmask_b32_e32 v155, v155, v184, vcc
	v_fmac_f32_e32 v185, 0xc0c90fdb, v186
	v_rsq_f32_e32 v155, v155
	v_fmac_f32_e32 v185, 0x343bbd2e, v186
	v_mul_f32_e32 v185, 0.15915494, v185
	v_mul_f32_e32 v183, v131, v183
	v_sin_f32_e32 v193, v185
	v_cos_f32_e32 v192, v185
	v_mul_f32_e32 v185, 0.15915494, v183
	v_rndne_f32_e32 v185, v185
	v_mul_f32_e32 v184, 0x45800000, v155
	v_fmac_f32_e32 v183, 0xc0c90fdb, v185
	v_fmac_f32_e32 v183, 0x343bbd2e, v185
	v_cndmask_b32_e32 v196, v155, v184, vcc
	v_mov_b32_e32 v184, v44
	v_mov_b32_e32 v185, v40
	v_pk_mul_f32 v[184:185], v[184:185], v[196:197] op_sel_hi:[1,0]
	v_mov_b32_e32 v198, v189
	v_mov_b32_e32 v199, v188
	v_mul_f32_e32 v183, 0.15915494, v183
	v_pk_mul_f32 v[186:187], v[184:185], v[188:189]
	v_pk_mul_f32 v[184:185], v[184:185], v[198:199]
	v_sin_f32_e32 v195, v183
	v_cos_f32_e32 v194, v183
	v_add_f32_e32 v183, v184, v185
	v_mov_b32_e32 v184, v45
	v_mov_b32_e32 v185, v41
	v_pk_mul_f32 v[184:185], v[184:185], v[196:197] op_sel_hi:[1,0]
	v_mov_b32_e32 v200, v191
	v_mov_b32_e32 v201, v190
	v_sub_f32_e32 v155, v186, v187
	v_pk_mul_f32 v[186:187], v[184:185], v[190:191]
	v_pk_mul_f32 v[184:185], v[184:185], v[200:201]
	v_sub_f32_e32 v197, v186, v187
	v_add_f32_e32 v208, v184, v185
	v_mov_b32_e32 v184, v46
	v_mov_b32_e32 v185, v42
	v_pk_mul_f32 v[184:185], v[184:185], v[196:197] op_sel_hi:[1,0]
	v_mov_b32_e32 v202, v193
	v_mov_b32_e32 v203, v192
	v_pk_mul_f32 v[186:187], v[184:185], v[192:193]
	v_pk_mul_f32 v[184:185], v[184:185], v[202:203]
	v_sub_f32_e32 v209, v186, v187
	v_add_f32_e32 v210, v184, v185
	v_mov_b32_e32 v184, v47
	v_mov_b32_e32 v185, v43
	v_pk_mul_f32 v[184:185], v[184:185], v[196:197] op_sel_hi:[1,0]
	v_mov_b32_e32 v204, v195
	v_pk_mul_f32 v[186:187], v[184:185], v[194:195]
	v_mov_b32_e32 v205, v194
	v_sub_f32_e32 v186, v186, v187
	v_pk_mul_f32 v[184:185], v[184:185], v[204:205]
	s_nop 0
	v_add_f32_e32 v187, v184, v185
	v_cvt_pk_bf16_f32 v184, v155, v197
	v_cvt_pk_bf16_f32 v185, v209, v186
	v_cvt_pk_bf16_f32 v186, v183, v208
	v_add_co_u32_e32 v208, vcc, s70, v166
	v_cvt_pk_bf16_f32 v187, v210, v187
	s_nop 1
	v_addc_co_u32_e32 v209, vcc, 0, v167, vcc
	global_store_dwordx4 v[208:209], v[184:187], off
	s_nop 1
	v_mov_b32_e32 v184, v36
	v_mov_b32_e32 v185, v32
	v_pk_mul_f32 v[184:185], v[184:185], v[196:197] op_sel_hi:[1,0]
	s_nop 0
	v_pk_mul_f32 v[186:187], v[184:185], v[188:189]
	v_pk_mul_f32 v[184:185], v[184:185], v[198:199]
	v_sub_f32_e32 v155, v186, v187
	v_add_f32_e32 v183, v184, v185
	v_mov_b32_e32 v184, v37
	v_mov_b32_e32 v185, v33
	v_pk_mul_f32 v[184:185], v[184:185], v[196:197] op_sel_hi:[1,0]
	s_nop 0
	v_pk_mul_f32 v[186:187], v[184:185], v[190:191]
	v_pk_mul_f32 v[184:185], v[184:185], v[200:201]
	v_sub_f32_e32 v188, v186, v187
	v_add_f32_e32 v189, v184, v185
	v_mov_b32_e32 v184, v38
	v_mov_b32_e32 v185, v34
	v_pk_mul_f32 v[184:185], v[184:185], v[196:197] op_sel_hi:[1,0]
	s_nop 0
	v_pk_mul_f32 v[186:187], v[184:185], v[192:193]
	v_pk_mul_f32 v[184:185], v[184:185], v[202:203]
	v_sub_f32_e32 v190, v186, v187
	v_add_f32_e32 v191, v184, v185
	v_mov_b32_e32 v184, v39
	v_mov_b32_e32 v185, v35
	v_pk_mul_f32 v[184:185], v[184:185], v[196:197] op_sel_hi:[1,0]
	s_nop 0
;     __device__ __forceinline__ void operator()(const f32x4 (&acc)[2][2][4][2], const Unit& u, int wr, int wc, int fr, int fq) const {
;     ...
;                 for (int m = 0; m < 4; ++m) { const int row = row0 + ai * HALF + m * 16; const float rs = rsqrtf(ssq[row] * (1.0f / 512.0f) + EPS); const float p = (float)pos[row];
;                     float sn[4], cs[4];
; #pragma unroll
;                     for (int e = 0; e < 4; ++e) sincos_rr(p * invf[e], sn[e], cs[e]);
; #pragma unroll
;                     for (int bj = 0; bj < 2; ++bj) { const int head = 4 * (u.pn - 8) + 2 * bj + (wc >> 1); f32x4 o0, o1;
; #pragma unroll
;                         for (int e = 0; e < 4; ++e) { const float x1 = acc[ai][bj][m][0][e] * rs, x2 = acc[ai][bj][m][1][e] * rs;
;                             o0[e] = x1 * cs[e] - x2 * sn[e]; o1[e] = x2 * cs[e] + x1 * sn[e]; }
;                         st8(QR + (size_t)row * 1024 + head * 64 + 32 * (wc & 1) + 8 * fq, o0, o1); } }
	v_pk_mul_f32 v[186:187], v[184:185], v[194:195]
	v_pk_mul_f32 v[184:185], v[184:185], v[204:205]
	v_sub_f32_e32 v186, v186, v187
	v_add_f32_e32 v187, v184, v185
	v_cvt_pk_bf16_f32 v184, v155, v188
	v_cvt_pk_bf16_f32 v185, v190, v186
	v_cvt_pk_bf16_f32 v186, v183, v189
	v_cvt_pk_bf16_f32 v187, v191, v187
	global_store_dwordx4 v[206:207], v[184:187], off offset:256
	s_nop 1
	v_mov_b32_e32 v155, v245
	s_nop 1
	v_mov_b32_e32 v183, v252
	v_lshl_add_u64 v[206:207], v[166:167], 0, s[20:21]
	v_fmamk_f32 v155, v155, 0x3b000000, v182
	v_cvt_f32_i32_e32 v183, v183
	v_mul_f32_e32 v184, 0x4b800000, v155
	v_cmp_gt_f32_e32 vcc, s69, v155
	v_mul_f32_e32 v185, v128, v183
	v_mul_f32_e32 v186, 0.15915494, v185
	v_rndne_f32_e32 v186, v186
	v_fmac_f32_e32 v185, 0xc0c90fdb, v186
	v_fmac_f32_e32 v185, 0x343bbd2e, v186
	v_mul_f32_e32 v185, 0.15915494, v185
	v_sin_f32_e32 v189, v185
	v_cos_f32_e32 v188, v185
	v_mul_f32_e32 v185, v129, v183
	v_mul_f32_e32 v186, 0.15915494, v185
	v_rndne_f32_e32 v186, v186
	v_fmac_f32_e32 v185, 0xc0c90fdb, v186
	v_fmac_f32_e32 v185, 0x343bbd2e, v186
	v_mul_f32_e32 v185, 0.15915494, v185
	v_sin_f32_e32 v191, v185
	v_cos_f32_e32 v190, v185
	v_mul_f32_e32 v185, v130, v183
	v_mul_f32_e32 v186, 0.15915494, v185
	v_rndne_f32_e32 v186, v186
	v_cndmask_b32_e32 v155, v155, v184, vcc
	v_fmac_f32_e32 v185, 0xc0c90fdb, v186
	v_rsq_f32_e32 v155, v155
	v_fmac_f32_e32 v185, 0x343bbd2e, v186
	v_mul_f32_e32 v185, 0.15915494, v185
	v_mul_f32_e32 v183, v131, v183
	v_sin_f32_e32 v193, v185
	v_cos_f32_e32 v192, v185
	v_mul_f32_e32 v185, 0.15915494, v183
	v_rndne_f32_e32 v185, v185
	v_mul_f32_e32 v184, 0x45800000, v155
	v_fmac_f32_e32 v183, 0xc0c90fdb, v185
	v_fmac_f32_e32 v183, 0x343bbd2e, v185
	v_cndmask_b32_e32 v196, v155, v184, vcc
	v_mov_b32_e32 v184, v28
	v_mov_b32_e32 v185, v24
	v_pk_mul_f32 v[184:185], v[184:185], v[196:197] op_sel_hi:[1,0]
	v_mov_b32_e32 v198, v189
	v_mov_b32_e32 v199, v188
	v_mul_f32_e32 v183, 0.15915494, v183
	v_pk_mul_f32 v[186:187], v[184:185], v[188:189]
	v_pk_mul_f32 v[184:185], v[184:185], v[198:199]
	v_sin_f32_e32 v195, v183
	v_cos_f32_e32 v194, v183
	v_add_f32_e32 v183, v184, v185
	v_mov_b32_e32 v184, v29
	v_mov_b32_e32 v185, v25
	v_pk_mul_f32 v[184:185], v[184:185], v[196:197] op_sel_hi:[1,0]
	v_mov_b32_e32 v200, v191
	v_mov_b32_e32 v201, v190
	v_sub_f32_e32 v155, v186, v187
	v_pk_mul_f32 v[186:187], v[184:185], v[190:191]
	v_pk_mul_f32 v[184:185], v[184:185], v[200:201]
	v_sub_f32_e32 v197, v186, v187
	v_add_f32_e32 v208, v184, v185
	v_mov_b32_e32 v184, v30
	v_mov_b32_e32 v185, v26
	v_pk_mul_f32 v[184:185], v[184:185], v[196:197] op_sel_hi:[1,0]
	v_mov_b32_e32 v202, v193
	v_mov_b32_e32 v203, v192
	v_pk_mul_f32 v[186:187], v[184:185], v[192:193]
	v_pk_mul_f32 v[184:185], v[184:185], v[202:203]
	v_sub_f32_e32 v209, v186, v187
	v_add_f32_e32 v210, v184, v185
	v_mov_b32_e32 v184, v31
	v_mov_b32_e32 v185, v27
	v_pk_mul_f32 v[184:185], v[184:185], v[196:197] op_sel_hi:[1,0]
	v_mov_b32_e32 v204, v195
	v_pk_mul_f32 v[186:187], v[184:185], v[194:195]
	v_mov_b32_e32 v205, v194
	v_sub_f32_e32 v186, v186, v187
	v_pk_mul_f32 v[184:185], v[184:185], v[204:205]
	s_nop 0
	v_add_f32_e32 v187, v184, v185
	v_cvt_pk_bf16_f32 v184, v155, v197
	v_cvt_pk_bf16_f32 v185, v209, v186
	v_cvt_pk_bf16_f32 v186, v183, v208
	v_add_co_u32_e32 v208, vcc, s71, v166
	v_cvt_pk_bf16_f32 v187, v210, v187
	s_nop 1
	v_addc_co_u32_e32 v209, vcc, 0, v167, vcc
	global_store_dwordx4 v[208:209], v[184:187], off
	s_nop 1
	v_mov_b32_e32 v184, v20
	v_mov_b32_e32 v185, v16
	v_pk_mul_f32 v[184:185], v[184:185], v[196:197] op_sel_hi:[1,0]
	s_nop 0
	v_pk_mul_f32 v[186:187], v[184:185], v[188:189]
	v_pk_mul_f32 v[184:185], v[184:185], v[198:199]
	v_sub_f32_e32 v155, v186, v187
	v_add_f32_e32 v183, v184, v185
	v_mov_b32_e32 v184, v21
	v_mov_b32_e32 v185, v17
	v_pk_mul_f32 v[184:185], v[184:185], v[196:197] op_sel_hi:[1,0]
	v_lshl_add_u64 v[198:199], v[166:167], 0, s[22:23]
	v_pk_mul_f32 v[186:187], v[184:185], v[190:191]
	v_pk_mul_f32 v[184:185], v[184:185], v[200:201]
	v_sub_f32_e32 v188, v186, v187
	v_add_f32_e32 v189, v184, v185
	v_mov_b32_e32 v184, v22
	v_mov_b32_e32 v185, v18
	v_pk_mul_f32 v[184:185], v[184:185], v[196:197] op_sel_hi:[1,0]
	s_nop 0
	v_pk_mul_f32 v[186:187], v[184:185], v[192:193]
	v_pk_mul_f32 v[184:185], v[184:185], v[202:203]
	v_sub_f32_e32 v190, v186, v187
	v_add_f32_e32 v191, v184, v185
	v_mov_b32_e32 v184, v23
	v_mov_b32_e32 v185, v19
	v_pk_mul_f32 v[184:185], v[184:185], v[196:197] op_sel_hi:[1,0]
	s_nop 0
	v_pk_mul_f32 v[186:187], v[184:185], v[194:195]
	v_pk_mul_f32 v[184:185], v[184:185], v[204:205]
	v_sub_f32_e32 v186, v186, v187
	v_add_f32_e32 v187, v184, v185
	v_cvt_pk_bf16_f32 v184, v155, v188
	v_cvt_pk_bf16_f32 v185, v190, v186
	v_cvt_pk_bf16_f32 v186, v183, v189
	v_cvt_pk_bf16_f32 v187, v191, v187
	global_store_dwordx4 v[206:207], v[184:187], off offset:256
	s_nop 1
	v_mov_b32_e32 v155, v246
	s_nop 0
	s_nop 1
	v_mov_b32_e32 v162, v253
	v_fmamk_f32 v155, v155, 0x3b000000, v182
	v_cvt_f32_i32_e32 v183, v162
	v_mul_f32_e32 v163, 0x4b800000, v155
	v_cmp_gt_f32_e32 vcc, s69, v155
	v_mul_f32_e32 v128, v128, v183
	v_mul_f32_e32 v162, 0.15915494, v128
	v_rndne_f32_e32 v162, v162
	v_fmac_f32_e32 v128, 0xc0c90fdb, v162
	v_fmac_f32_e32 v128, 0x343bbd2e, v162
	v_mul_f32_e32 v128, 0.15915494, v128
	v_cndmask_b32_e32 v155, v155, v163, vcc
	v_sin_f32_e32 v163, v128
	v_cos_f32_e32 v162, v128
	v_mul_f32_e32 v128, v129, v183
	v_mul_f32_e32 v129, 0.15915494, v128
	v_rndne_f32_e32 v129, v129
	v_fmac_f32_e32 v128, 0xc0c90fdb, v129
	v_fmac_f32_e32 v128, 0x343bbd2e, v129
	v_mul_f32_e32 v128, 0.15915494, v128
	v_sin_f32_e32 v165, v128
	v_cos_f32_e32 v164, v128
;     __device__ __forceinline__ void operator()(const f32x4 (&acc)[2][2][4][2], const Unit& u, int wr, int wc, int fr, int fq) const {
;     ...
;                 for (int m = 0; m < 4; ++m) { const int row = row0 + ai * HALF + m * 16; const float rs = rsqrtf(ssq[row] * (1.0f / 512.0f) + EPS);
;     ...
;                 for (int m = 0; m < 4; ++m) { const int row = row0 + ai * HALF + m * 16; const float rs = rsqrtf(ssq[row] * (1.0f / 512.0f) + EPS); const float p = (float)pos[row];
;                     float sn[4], cs[4];
; #pragma unroll
;                     for (int e = 0; e < 4; ++e) sincos_rr(p * invf[e], sn[e], cs[e]);
; #pragma unroll
;                     for (int bj = 0; bj < 2; ++bj) { const int head = 4 * (u.pn - 8) + 2 * bj + (wc >> 1); f32x4 o0, o1;
; #pragma unroll
;                         for (int e = 0; e < 4; ++e) { const float x1 = acc[ai][bj][m][0][e] * rs, x2 = acc[ai][bj][m][1][e] * rs;
;                             o0[e] = x1 * cs[e] - x2 * sn[e]; o1[e] = x2 * cs[e] + x1 * sn[e]; }
;                         st8(QR + (size_t)row * 1024 + head * 64 + 32 * (wc & 1) + 8 * fq, o0, o1); } }
	v_mul_f32_e32 v128, v130, v183
	v_mul_f32_e32 v129, 0.15915494, v128
	v_rndne_f32_e32 v129, v129
	v_fmac_f32_e32 v128, 0xc0c90fdb, v129
	v_fmac_f32_e32 v128, 0x343bbd2e, v129
	v_mul_f32_e32 v128, 0.15915494, v128
	v_sin_f32_e32 v185, v128
	v_cos_f32_e32 v184, v128
	v_mul_f32_e32 v128, v131, v183
	v_rsq_f32_e32 v155, v155
	v_mul_f32_e32 v129, 0.15915494, v128
	v_rndne_f32_e32 v129, v129
	v_fmac_f32_e32 v128, 0xc0c90fdb, v129
	v_fmac_f32_e32 v128, 0x343bbd2e, v129
	v_mul_f32_e32 v188, 0x45800000, v155
	v_mul_f32_e32 v128, 0.15915494, v128
	v_sin_f32_e32 v187, v128
	v_cos_f32_e32 v186, v128
	v_cndmask_b32_e32 v188, v155, v188, vcc
	v_mov_b32_e32 v128, v12
	v_mov_b32_e32 v129, v8
	v_pk_mul_f32 v[128:129], v[128:129], v[188:189] op_sel_hi:[1,0]
	v_mov_b32_e32 v190, v163
	v_mov_b32_e32 v191, v162
	v_pk_mul_f32 v[130:131], v[128:129], v[162:163]
	v_pk_mul_f32 v[128:129], v[128:129], v[190:191]
	v_mov_b32_e32 v192, v165
	v_add_f32_e32 v183, v128, v129
	v_mov_b32_e32 v128, v13
	v_mov_b32_e32 v129, v9
	v_pk_mul_f32 v[128:129], v[128:129], v[188:189] op_sel_hi:[1,0]
	v_mov_b32_e32 v193, v164
	v_sub_f32_e32 v155, v130, v131
	v_pk_mul_f32 v[130:131], v[128:129], v[164:165]
	v_pk_mul_f32 v[128:129], v[128:129], v[192:193]
	v_sub_f32_e32 v189, v130, v131
	v_add_f32_e32 v200, v128, v129
	v_mov_b32_e32 v128, v14
	v_mov_b32_e32 v129, v10
	v_pk_mul_f32 v[128:129], v[128:129], v[188:189] op_sel_hi:[1,0]
	v_mov_b32_e32 v194, v185
	v_mov_b32_e32 v195, v184
	v_pk_mul_f32 v[130:131], v[128:129], v[184:185]
	v_pk_mul_f32 v[128:129], v[128:129], v[194:195]
	v_mov_b32_e32 v196, v187
	v_add_f32_e32 v202, v128, v129
	v_mov_b32_e32 v128, v15
	v_mov_b32_e32 v129, v11
	v_pk_mul_f32 v[128:129], v[128:129], v[188:189] op_sel_hi:[1,0]
	v_mov_b32_e32 v197, v186
	v_sub_f32_e32 v201, v130, v131
	v_pk_mul_f32 v[130:131], v[128:129], v[186:187]
	v_pk_mul_f32 v[128:129], v[128:129], v[196:197]
	v_add_co_u32_e32 v166, vcc, s72, v166
	v_sub_f32_e32 v130, v130, v131
	v_add_f32_e32 v131, v128, v129
	v_cvt_pk_bf16_f32 v128, v155, v189
	v_cvt_pk_bf16_f32 v129, v201, v130
	v_addc_co_u32_e32 v167, vcc, 0, v167, vcc
	v_cvt_pk_bf16_f32 v130, v183, v200
	v_cvt_pk_bf16_f32 v131, v202, v131
	global_store_dwordx4 v[166:167], v[128:131], off
	s_nop 1
	v_mov_b32_e32 v128, v4
	v_mov_b32_e32 v129, v0
	v_pk_mul_f32 v[128:129], v[128:129], v[188:189] op_sel_hi:[1,0]
	s_nop 0
	v_pk_mul_f32 v[130:131], v[128:129], v[162:163]
	v_pk_mul_f32 v[128:129], v[128:129], v[190:191]
	v_sub_f32_e32 v155, v130, v131
	v_add_f32_e32 v162, v128, v129
	v_mov_b32_e32 v128, v5
	v_mov_b32_e32 v129, v1
	v_pk_mul_f32 v[128:129], v[128:129], v[188:189] op_sel_hi:[1,0]
	s_nop 0
	v_pk_mul_f32 v[130:131], v[128:129], v[164:165]
	v_pk_mul_f32 v[128:129], v[128:129], v[192:193]
	v_sub_f32_e32 v163, v130, v131
	v_add_f32_e32 v164, v128, v129
	v_mov_b32_e32 v128, v6
	v_mov_b32_e32 v129, v2
	v_pk_mul_f32 v[128:129], v[128:129], v[188:189] op_sel_hi:[1,0]
	s_nop 0
	v_pk_mul_f32 v[130:131], v[128:129], v[184:185]
	v_pk_mul_f32 v[128:129], v[128:129], v[194:195]
	v_sub_f32_e32 v165, v130, v131
	v_add_f32_e32 v166, v128, v129
	v_mov_b32_e32 v128, v7
	v_mov_b32_e32 v129, v3
	v_pk_mul_f32 v[128:129], v[128:129], v[188:189] op_sel_hi:[1,0]
	s_nop 0
	v_pk_mul_f32 v[130:131], v[128:129], v[186:187]
	v_pk_mul_f32 v[128:129], v[128:129], v[196:197]
	v_sub_f32_e32 v130, v130, v131
	v_add_f32_e32 v131, v128, v129
	v_cvt_pk_bf16_f32 v128, v155, v163
	v_cvt_pk_bf16_f32 v129, v165, v130
	v_cvt_pk_bf16_f32 v130, v162, v164
	v_cvt_pk_bf16_f32 v131, v166, v131
	global_store_dwordx4 v[198:199], v[128:131], off offset:256
	s_cbranch_execnz .LBB0_868
.LBB0_870:
	s_nop 0
	v_lshl_add_u64 v[128:129], v[160:161], 2, s[38:39]
	global_load_dword v155, v[128:129], off
	global_load_dword v240, v[128:129], off offset:64
	global_load_dword v241, v[128:129], off offset:128
	global_load_dword v242, v[128:129], off offset:192
	global_load_dword v243, v[128:129], off offset:512
	global_load_dword v244, v[128:129], off offset:576
	global_load_dword v245, v[128:129], off offset:640
	global_load_dword v246, v[128:129], off offset:704
	s_lshl_b32 s0, s80, 8
	s_ashr_i32 s1, s0, 31
	v_lshlrev_b64 v[130:131], 12, v[160:161]
	v_lshl_add_u64 v[160:161], v[158:159], 2, s[38:39]
	s_waitcnt vmcnt(0)
;     __device__ __forceinline__ void operator()(const f32x4 (&acc)[2][2][4][2], const Unit& u, int wr, int wc, int fr, int fq) const {
;     ...
;         if (u.pn < 8) {
;             bf16_t* base = QN + u.pn * 256 + cl;
; #pragma unroll
;             for (int ai = 0; ai < 2; ++ai)
; #pragma unroll
;                 for (int m = 0; m < 4; ++m) { const int row = row0 + ai * HALF + m * 16; const float rs = rsqrtf(ssq[row] * (1.0f / 512.0f) + EPS);
; #pragma unroll
;                     for (int bj = 0; bj < 2; ++bj) st8(base + (size_t)row * 2048 + bj * HALF, acc[ai][bj][m][0] * rs, acc[ai][bj][m][1] * rs); }
	v_fmamk_f32 v155, v155, 0x3b000000, v182
	v_mul_f32_e32 v162, 0x4b800000, v155
	v_cmp_gt_f32_e32 vcc, s69, v155
	s_nop 1
	v_cndmask_b32_e32 v155, v155, v162, vcc
	v_rsq_f32_e32 v155, v155
	v_lshl_add_u64 v[162:163], s[0:1], 1, v[144:145]
	v_lshl_add_u64 v[130:131], v[162:163], 0, v[130:131]
	v_mul_f32_e32 v164, 0x45800000, v155
	v_cndmask_b32_e32 v164, v155, v164, vcc
	v_pk_mul_f32 v[126:127], v[126:127], v[164:165] op_sel_hi:[1,0]
	v_pk_mul_f32 v[124:125], v[124:125], v[164:165] op_sel_hi:[1,0]
	v_pk_mul_f32 v[122:123], v[122:123], v[164:165] op_sel_hi:[1,0]
	v_pk_mul_f32 v[120:121], v[120:121], v[164:165] op_sel_hi:[1,0]
	v_pk_mul_f32 v[118:119], v[118:119], v[164:165] op_sel_hi:[1,0]
	v_pk_mul_f32 v[116:117], v[116:117], v[164:165] op_sel_hi:[1,0]
	v_pk_mul_f32 v[166:167], v[114:115], v[164:165] op_sel_hi:[1,0]
	v_pk_mul_f32 v[164:165], v[112:113], v[164:165] op_sel_hi:[1,0]
	v_cvt_pk_bf16_f32 v112, v124, v125
	v_cvt_pk_bf16_f32 v113, v126, v127
	v_cvt_pk_bf16_f32 v114, v120, v121
	v_cvt_pk_bf16_f32 v115, v122, v123
	global_store_dwordx4 v[130:131], v[112:115], off
	v_ashrrev_i32_e32 v155, 31, v154
	s_nop 0
	v_cvt_pk_bf16_f32 v112, v116, v117
	v_cvt_pk_bf16_f32 v113, v118, v119
	v_cvt_pk_bf16_f32 v114, v164, v165
	v_cvt_pk_bf16_f32 v115, v166, v167
	global_store_dwordx4 v[130:131], v[112:115], off offset:256
	s_nop 1
	v_mov_b32_e32 v112, v240
	s_nop 0
	v_lshl_add_u64 v[114:115], v[156:157], 2, s[38:39]
	v_fmamk_f32 v112, v112, 0x3b000000, v182
	v_mul_f32_e32 v113, 0x4b800000, v112
	v_cmp_gt_f32_e32 vcc, s69, v112
	s_nop 1
	v_cndmask_b32_e32 v112, v112, v113, vcc
	v_rsq_f32_e32 v116, v112
	v_lshlrev_b64 v[112:113], 12, v[158:159]
	v_lshl_add_u64 v[112:113], v[162:163], 0, v[112:113]
	v_mul_f32_e32 v117, 0x45800000, v116
	v_cndmask_b32_e32 v116, v116, v117, vcc
	v_pk_mul_f32 v[110:111], v[110:111], v[116:117] op_sel_hi:[1,0]
	v_pk_mul_f32 v[108:109], v[108:109], v[116:117] op_sel_hi:[1,0]
	v_pk_mul_f32 v[106:107], v[106:107], v[116:117] op_sel_hi:[1,0]
	v_pk_mul_f32 v[104:105], v[104:105], v[116:117] op_sel_hi:[1,0]
	v_pk_mul_f32 v[102:103], v[102:103], v[116:117] op_sel_hi:[1,0]
	v_pk_mul_f32 v[100:101], v[100:101], v[116:117] op_sel_hi:[1,0]
	v_pk_mul_f32 v[118:119], v[98:99], v[116:117] op_sel_hi:[1,0]
	v_pk_mul_f32 v[116:117], v[96:97], v[116:117] op_sel_hi:[1,0]
	v_cvt_pk_bf16_f32 v96, v108, v109
	v_cvt_pk_bf16_f32 v97, v110, v111
	v_cvt_pk_bf16_f32 v98, v104, v105
	v_cvt_pk_bf16_f32 v99, v106, v107
	global_store_dwordx4 v[112:113], v[96:99], off
	s_nop 1
	v_cvt_pk_bf16_f32 v96, v100, v101
	v_cvt_pk_bf16_f32 v97, v102, v103
	v_cvt_pk_bf16_f32 v98, v116, v117
	v_cvt_pk_bf16_f32 v99, v118, v119
	global_store_dwordx4 v[112:113], v[96:99], off offset:256
	s_nop 1
	v_mov_b32_e32 v98, v241
	s_nop 0
	v_lshlrev_b64 v[96:97], 12, v[156:157]
	v_lshl_add_u64 v[96:97], v[162:163], 0, v[96:97]
	v_fmamk_f32 v98, v98, 0x3b000000, v182
	v_mul_f32_e32 v99, 0x4b800000, v98
	v_cmp_gt_f32_e32 vcc, s69, v98
	s_nop 1
	v_cndmask_b32_e32 v98, v98, v99, vcc
	v_rsq_f32_e32 v100, v98
	v_lshl_add_u64 v[98:99], v[154:155], 2, s[38:39]
	v_mul_f32_e32 v101, 0x45800000, v100
	v_cndmask_b32_e32 v100, v100, v101, vcc
	v_pk_mul_f32 v[94:95], v[94:95], v[100:101] op_sel_hi:[1,0]
	v_pk_mul_f32 v[92:93], v[92:93], v[100:101] op_sel_hi:[1,0]
	v_pk_mul_f32 v[90:91], v[90:91], v[100:101] op_sel_hi:[1,0]
	v_pk_mul_f32 v[88:89], v[88:89], v[100:101] op_sel_hi:[1,0]
	v_pk_mul_f32 v[86:87], v[86:87], v[100:101] op_sel_hi:[1,0]
	v_pk_mul_f32 v[84:85], v[84:85], v[100:101] op_sel_hi:[1,0]
	v_pk_mul_f32 v[102:103], v[78:79], v[100:101] op_sel_hi:[1,0]
	v_pk_mul_f32 v[100:101], v[76:77], v[100:101] op_sel_hi:[1,0]
	v_cvt_pk_bf16_f32 v76, v92, v93
	v_cvt_pk_bf16_f32 v77, v94, v95
	v_cvt_pk_bf16_f32 v78, v88, v89
	v_cvt_pk_bf16_f32 v79, v90, v91
	global_store_dwordx4 v[96:97], v[76:79], off
	s_nop 1
	v_cvt_pk_bf16_f32 v76, v84, v85
	v_cvt_pk_bf16_f32 v77, v86, v87
	v_cvt_pk_bf16_f32 v78, v100, v101
	v_cvt_pk_bf16_f32 v79, v102, v103
	global_store_dwordx4 v[96:97], v[76:79], off offset:256
	s_nop 1
	v_mov_b32_e32 v76, v242
	v_fmamk_f32 v76, v76, 0x3b000000, v182
	v_mul_f32_e32 v77, 0x4b800000, v76
	v_cmp_gt_f32_e32 vcc, s69, v76
	s_nop 1
	v_cndmask_b32_e32 v76, v76, v77, vcc
	v_rsq_f32_e32 v78, v76
	v_lshlrev_b64 v[76:77], 12, v[154:155]
	v_lshl_add_u64 v[76:77], v[162:163], 0, v[76:77]
	v_mul_f32_e32 v79, 0x45800000, v78
	v_cndmask_b32_e32 v78, v78, v79, vcc
	v_pk_mul_f32 v[82:83], v[82:83], v[78:79] op_sel_hi:[1,0]
	v_pk_mul_f32 v[80:81], v[80:81], v[78:79] op_sel_hi:[1,0]
	v_pk_mul_f32 v[74:75], v[74:75], v[78:79] op_sel_hi:[1,0]
	v_pk_mul_f32 v[72:73], v[72:73], v[78:79] op_sel_hi:[1,0]
	v_pk_mul_f32 v[70:71], v[70:71], v[78:79] op_sel_hi:[1,0]
	v_pk_mul_f32 v[68:69], v[68:69], v[78:79] op_sel_hi:[1,0]
	v_pk_mul_f32 v[84:85], v[66:67], v[78:79] op_sel_hi:[1,0]
	v_pk_mul_f32 v[78:79], v[64:65], v[78:79] op_sel_hi:[1,0]
	v_cvt_pk_bf16_f32 v64, v80, v81
	v_cvt_pk_bf16_f32 v65, v82, v83
	v_cvt_pk_bf16_f32 v66, v72, v73
	v_cvt_pk_bf16_f32 v67, v74, v75
	global_store_dwordx4 v[76:77], v[64:67], off
	s_nop 1
	v_cvt_pk_bf16_f32 v64, v68, v69
	v_cvt_pk_bf16_f32 v65, v70, v71
	v_cvt_pk_bf16_f32 v66, v78, v79
	v_cvt_pk_bf16_f32 v67, v84, v85
;     __device__ __forceinline__ void operator()(const f32x4 (&acc)[2][2][4][2], const Unit& u, int wr, int wc, int fr, int fq) const {
;     ...
;                 for (int m = 0; m < 4; ++m) { const int row = row0 + ai * HALF + m * 16; const float rs = rsqrtf(ssq[row] * (1.0f / 512.0f) + EPS);
; #pragma unroll
;                     for (int bj = 0; bj < 2; ++bj) st8(base + (size_t)row * 2048 + bj * HALF, acc[ai][bj][m][0] * rs, acc[ai][bj][m][1] * rs); }
	global_store_dwordx4 v[76:77], v[64:67], off offset:256
	s_nop 1
	v_mov_b32_e32 v66, v243
	s_nop 0
	v_lshl_add_u64 v[64:65], v[130:131], 0, s[24:25]
	v_fmamk_f32 v66, v66, 0x3b000000, v182
	v_mul_f32_e32 v67, 0x4b800000, v66
	v_cmp_gt_f32_e32 vcc, s69, v66
	s_nop 1
	v_cndmask_b32_e32 v66, v66, v67, vcc
	v_rsq_f32_e32 v68, v66
	v_add_co_u32_e64 v66, s[0:1], s73, v130
	v_mul_f32_e32 v69, 0x45800000, v68
	v_cndmask_b32_e32 v68, v68, v69, vcc
	v_addc_co_u32_e64 v67, s[0:1], 0, v131, s[0:1]
	v_pk_mul_f32 v[62:63], v[62:63], v[68:69] op_sel_hi:[1,0]
	v_pk_mul_f32 v[60:61], v[60:61], v[68:69] op_sel_hi:[1,0]
	v_pk_mul_f32 v[58:59], v[58:59], v[68:69] op_sel_hi:[1,0]
	v_pk_mul_f32 v[56:57], v[56:57], v[68:69] op_sel_hi:[1,0]
	v_pk_mul_f32 v[54:55], v[54:55], v[68:69] op_sel_hi:[1,0]
	v_pk_mul_f32 v[52:53], v[52:53], v[68:69] op_sel_hi:[1,0]
	v_pk_mul_f32 v[70:71], v[50:51], v[68:69] op_sel_hi:[1,0]
	v_pk_mul_f32 v[68:69], v[48:49], v[68:69] op_sel_hi:[1,0]
	v_cvt_pk_bf16_f32 v48, v60, v61
	v_cvt_pk_bf16_f32 v49, v62, v63
	v_cvt_pk_bf16_f32 v50, v56, v57
	v_cvt_pk_bf16_f32 v51, v58, v59
	global_store_dwordx4 v[66:67], v[48:51], off
	s_nop 1
	v_cvt_pk_bf16_f32 v48, v52, v53
	v_cvt_pk_bf16_f32 v49, v54, v55
	v_cvt_pk_bf16_f32 v50, v68, v69
	v_cvt_pk_bf16_f32 v51, v70, v71
	global_store_dwordx4 v[64:65], v[48:51], off offset:256
	s_nop 1
	v_mov_b32_e32 v50, v244
	s_nop 0
	v_lshl_add_u64 v[48:49], v[130:131], 0, s[26:27]
	v_fmamk_f32 v50, v50, 0x3b000000, v182
	v_mul_f32_e32 v51, 0x4b800000, v50
	v_cmp_gt_f32_e32 vcc, s69, v50
	s_nop 1
	v_cndmask_b32_e32 v50, v50, v51, vcc
	v_rsq_f32_e32 v52, v50
	v_add_co_u32_e64 v50, s[0:1], s74, v130
	v_mul_f32_e32 v53, 0x45800000, v52
	v_cndmask_b32_e32 v52, v52, v53, vcc
	v_addc_co_u32_e64 v51, s[0:1], 0, v131, s[0:1]
	v_pk_mul_f32 v[46:47], v[46:47], v[52:53] op_sel_hi:[1,0]
	v_pk_mul_f32 v[44:45], v[44:45], v[52:53] op_sel_hi:[1,0]
	v_pk_mul_f32 v[42:43], v[42:43], v[52:53] op_sel_hi:[1,0]
	v_pk_mul_f32 v[40:41], v[40:41], v[52:53] op_sel_hi:[1,0]
	v_pk_mul_f32 v[38:39], v[38:39], v[52:53] op_sel_hi:[1,0]
	v_pk_mul_f32 v[36:37], v[36:37], v[52:53] op_sel_hi:[1,0]
	v_pk_mul_f32 v[54:55], v[34:35], v[52:53] op_sel_hi:[1,0]
	v_pk_mul_f32 v[52:53], v[32:33], v[52:53] op_sel_hi:[1,0]
	v_cvt_pk_bf16_f32 v32, v44, v45
	v_cvt_pk_bf16_f32 v33, v46, v47
	v_cvt_pk_bf16_f32 v34, v40, v41
	v_cvt_pk_bf16_f32 v35, v42, v43
	global_store_dwordx4 v[50:51], v[32:35], off
	s_nop 1
	v_cvt_pk_bf16_f32 v32, v36, v37
	v_cvt_pk_bf16_f32 v33, v38, v39
	v_cvt_pk_bf16_f32 v34, v52, v53
	v_cvt_pk_bf16_f32 v35, v54, v55
	global_store_dwordx4 v[48:49], v[32:35], off offset:256
	s_nop 1
	v_mov_b32_e32 v34, v245
	s_nop 0
	v_lshl_add_u64 v[32:33], v[130:131], 0, s[28:29]
	v_fmamk_f32 v34, v34, 0x3b000000, v182
	v_mul_f32_e32 v35, 0x4b800000, v34
	v_cmp_gt_f32_e32 vcc, s69, v34
	s_nop 1
	v_cndmask_b32_e32 v34, v34, v35, vcc
	v_rsq_f32_e32 v36, v34
	v_add_co_u32_e64 v34, s[0:1], s75, v130
	v_mul_f32_e32 v37, 0x45800000, v36
	v_cndmask_b32_e32 v36, v36, v37, vcc
	v_addc_co_u32_e64 v35, s[0:1], 0, v131, s[0:1]
	v_pk_mul_f32 v[30:31], v[30:31], v[36:37] op_sel_hi:[1,0]
	v_pk_mul_f32 v[28:29], v[28:29], v[36:37] op_sel_hi:[1,0]
	v_pk_mul_f32 v[26:27], v[26:27], v[36:37] op_sel_hi:[1,0]
	v_pk_mul_f32 v[24:25], v[24:25], v[36:37] op_sel_hi:[1,0]
	v_pk_mul_f32 v[22:23], v[22:23], v[36:37] op_sel_hi:[1,0]
	v_pk_mul_f32 v[20:21], v[20:21], v[36:37] op_sel_hi:[1,0]
	v_pk_mul_f32 v[38:39], v[18:19], v[36:37] op_sel_hi:[1,0]
	v_pk_mul_f32 v[36:37], v[16:17], v[36:37] op_sel_hi:[1,0]
	v_cvt_pk_bf16_f32 v16, v28, v29
	v_cvt_pk_bf16_f32 v17, v30, v31
	v_cvt_pk_bf16_f32 v18, v24, v25
	v_cvt_pk_bf16_f32 v19, v26, v27
	global_store_dwordx4 v[34:35], v[16:19], off
	s_nop 1
	v_cvt_pk_bf16_f32 v16, v20, v21
	v_cvt_pk_bf16_f32 v17, v22, v23
	v_cvt_pk_bf16_f32 v18, v36, v37
	v_cvt_pk_bf16_f32 v19, v38, v39
	global_store_dwordx4 v[32:33], v[16:19], off offset:256
	s_nop 1
	v_mov_b32_e32 v18, v246
	s_nop 0
	v_lshl_add_u64 v[16:17], v[130:131], 0, s[30:31]
	v_fmamk_f32 v18, v18, 0x3b000000, v182
	v_mul_f32_e32 v19, 0x4b800000, v18
	v_cmp_gt_f32_e32 vcc, s69, v18
	s_nop 1
	v_cndmask_b32_e32 v18, v18, v19, vcc
	v_rsq_f32_e32 v20, v18
	v_add_co_u32_e64 v18, s[0:1], s76, v130
	v_mul_f32_e32 v21, 0x45800000, v20
	v_cndmask_b32_e32 v20, v20, v21, vcc
	v_addc_co_u32_e64 v19, s[0:1], 0, v131, s[0:1]
	v_pk_mul_f32 v[14:15], v[14:15], v[20:21] op_sel_hi:[1,0]
	v_pk_mul_f32 v[12:13], v[12:13], v[20:21] op_sel_hi:[1,0]
	v_pk_mul_f32 v[10:11], v[10:11], v[20:21] op_sel_hi:[1,0]
	v_pk_mul_f32 v[8:9], v[8:9], v[20:21] op_sel_hi:[1,0]
	v_pk_mul_f32 v[6:7], v[6:7], v[20:21] op_sel_hi:[1,0]
	v_pk_mul_f32 v[4:5], v[4:5], v[20:21] op_sel_hi:[1,0]
	v_pk_mul_f32 v[22:23], v[2:3], v[20:21] op_sel_hi:[1,0]
	v_pk_mul_f32 v[20:21], v[0:1], v[20:21] op_sel_hi:[1,0]
	v_cvt_pk_bf16_f32 v0, v12, v13
	v_cvt_pk_bf16_f32 v1, v14, v15
	v_cvt_pk_bf16_f32 v2, v8, v9
	v_cvt_pk_bf16_f32 v3, v10, v11
	global_store_dwordx4 v[18:19], v[0:3], off
	s_nop 1
	v_cvt_pk_bf16_f32 v0, v4, v5
	v_cvt_pk_bf16_f32 v1, v6, v7
	v_cvt_pk_bf16_f32 v2, v20, v21
	v_cvt_pk_bf16_f32 v3, v22, v23
	global_store_dwordx4 v[16:17], v[0:3], off offset:256
	s_andn2_b64 vcc, exec, s[2:3]
	s_mov_b64 s[0:1], -1
	s_cbranch_vccnz .LBB0_859

;     __device__ __forceinline__ void operator()(const f32x4 (&acc)[2][2][4][2], const Unit& u, int wr, int wc, int fr, int fq) const {
;         const int row0 = u.pm * BM + wr * 64 + fr, cl = wc * 32 + 8 * fq;
;         bf16_t* base = (u.pn < 8 ? KN + u.pn * 256 : V1 + (u.pn - 8) * 256) + cl;
; #pragma unroll
;         for (int ai = 0; ai < 2; ++ai)
; #pragma unroll
;             for (int m = 0; m < 4; ++m) { const int row = row0 + ai * HALF + m * 16; const float rs = rsqrtf(ssq[row] * (1.0f / 512.0f) + EPS);
; #pragma unroll
;                 for (int bj = 0; bj < 2; ++bj) st8(base + (size_t)row * 2048 + bj * HALF, acc[ai][bj][m][0] * rs, acc[ai][bj][m][1] * rs); }
;     }
.LBB0_894:
	v_lshl_add_u32 v150, s0, 8, v152
	v_ashrrev_i32_e32 v151, 31, v150
	v_lshl_add_u64 v[146:147], v[150:151], 2, s[6:7]
	global_load_dword v162, v[146:147], off
	global_load_dword v240, v[146:147], off offset:64
	global_load_dword v241, v[146:147], off offset:128
	global_load_dword v242, v[146:147], off offset:192
	global_load_dword v243, v[146:147], off offset:512
	global_load_dword v244, v[146:147], off offset:576
	global_load_dword v245, v[146:147], off offset:640
	global_load_dword v246, v[146:147], off offset:704
	s_lshl_b32 s34, s1, 8
	s_ashr_i32 s35, s34, 31
	s_lshl_b64 s[36:37], s[34:35], 1
	v_lshlrev_b64 v[148:149], 12, v[150:151]
	s_add_u32 s0, s49, s36
	s_addc_u32 s25, s50, s37
	s_add_i32 s8, s34, 0xfffff800
	s_lshl_b64 s[34:35], s[8:9], 1
	s_add_u32 s8, s51, s34
	s_addc_u32 s27, s52, s35
	s_cmp_lt_i32 s1, 8
	s_cselect_b32 s1, s25, s27
	s_cselect_b32 s0, s0, s8
	v_or_b32_e32 v158, 16, v150
	v_ashrrev_i32_e32 v159, 31, v158
	v_lshl_add_u64 v[160:161], v[158:159], 2, s[6:7]
	s_waitcnt vmcnt(0)
	v_fmamk_f32 v151, v162, 0x3b000000, v157
	v_mul_f32_e32 v162, 0x4b800000, v151
	v_cmp_gt_f32_e32 vcc, s59, v151
	s_nop 1
	v_cndmask_b32_e32 v151, v151, v162, vcc
	v_rsq_f32_e32 v151, v151
	v_lshl_add_u64 v[162:163], s[0:1], 0, v[128:129]
	v_lshl_add_u64 v[148:149], v[162:163], 0, v[148:149]
	v_mul_f32_e32 v164, 0x45800000, v151
	v_cndmask_b32_e32 v164, v151, v164, vcc
	v_pk_mul_f32 v[126:127], v[126:127], v[164:165] op_sel_hi:[1,0]
	v_pk_mul_f32 v[124:125], v[124:125], v[164:165] op_sel_hi:[1,0]
	v_pk_mul_f32 v[122:123], v[122:123], v[164:165] op_sel_hi:[1,0]
	v_pk_mul_f32 v[120:121], v[120:121], v[164:165] op_sel_hi:[1,0]
	v_pk_mul_f32 v[118:119], v[118:119], v[164:165] op_sel_hi:[1,0]
	v_pk_mul_f32 v[116:117], v[116:117], v[164:165] op_sel_hi:[1,0]
	v_pk_mul_f32 v[166:167], v[114:115], v[164:165] op_sel_hi:[1,0]
	v_pk_mul_f32 v[164:165], v[112:113], v[164:165] op_sel_hi:[1,0]
	v_cvt_pk_bf16_f32 v112, v124, v125
	v_cvt_pk_bf16_f32 v113, v126, v127
	v_cvt_pk_bf16_f32 v114, v120, v121
	v_cvt_pk_bf16_f32 v115, v122, v123
	global_store_dwordx4 v[148:149], v[112:115], off
	s_nop 1
	v_cvt_pk_bf16_f32 v112, v116, v117
	v_cvt_pk_bf16_f32 v113, v118, v119
	v_cvt_pk_bf16_f32 v114, v164, v165
	v_cvt_pk_bf16_f32 v115, v166, v167
	global_store_dwordx4 v[148:149], v[112:115], off offset:256
	s_nop 1
	v_mov_b32_e32 v114, v240
	s_nop 0
	v_or_b32_e32 v112, 32, v150
	v_ashrrev_i32_e32 v113, 31, v112
	v_lshl_add_u64 v[116:117], v[112:113], 2, s[6:7]
	v_fmamk_f32 v114, v114, 0x3b000000, v157
	v_mul_f32_e32 v115, 0x4b800000, v114
	v_cmp_gt_f32_e32 vcc, s59, v114
	s_nop 1
	v_cndmask_b32_e32 v114, v114, v115, vcc
	v_rsq_f32_e32 v118, v114
	v_lshlrev_b64 v[114:115], 12, v[158:159]
	v_lshl_add_u64 v[114:115], v[162:163], 0, v[114:115]
	v_mul_f32_e32 v119, 0x45800000, v118
	v_cndmask_b32_e32 v118, v118, v119, vcc
	v_pk_mul_f32 v[110:111], v[110:111], v[118:119] op_sel_hi:[1,0]
	v_pk_mul_f32 v[108:109], v[108:109], v[118:119] op_sel_hi:[1,0]
	v_pk_mul_f32 v[106:107], v[106:107], v[118:119] op_sel_hi:[1,0]
	v_pk_mul_f32 v[104:105], v[104:105], v[118:119] op_sel_hi:[1,0]
	v_pk_mul_f32 v[102:103], v[102:103], v[118:119] op_sel_hi:[1,0]
	v_pk_mul_f32 v[100:101], v[100:101], v[118:119] op_sel_hi:[1,0]
	v_pk_mul_f32 v[120:121], v[98:99], v[118:119] op_sel_hi:[1,0]
	v_pk_mul_f32 v[118:119], v[96:97], v[118:119] op_sel_hi:[1,0]
	v_cvt_pk_bf16_f32 v96, v108, v109
	v_cvt_pk_bf16_f32 v97, v110, v111
	v_cvt_pk_bf16_f32 v98, v104, v105
	v_cvt_pk_bf16_f32 v99, v106, v107
	global_store_dwordx4 v[114:115], v[96:99], off
	s_nop 1
	v_cvt_pk_bf16_f32 v96, v100, v101
	v_cvt_pk_bf16_f32 v97, v102, v103
	v_cvt_pk_bf16_f32 v98, v118, v119
	v_cvt_pk_bf16_f32 v99, v120, v121
	global_store_dwordx4 v[114:115], v[96:99], off offset:256
	s_nop 1
	v_mov_b32_e32 v98, v241
	s_nop 0
	v_or_b32_e32 v96, 48, v150
	v_ashrrev_i32_e32 v97, 31, v96
	v_lshl_add_u64 v[100:101], v[96:97], 2, s[6:7]
	v_fmamk_f32 v98, v98, 0x3b000000, v157
	v_mul_f32_e32 v99, 0x4b800000, v98
	v_cmp_gt_f32_e32 vcc, s59, v98
	s_nop 1
	v_cndmask_b32_e32 v98, v98, v99, vcc
	v_rsq_f32_e32 v102, v98
	v_lshlrev_b64 v[98:99], 12, v[112:113]
	v_lshl_add_u64 v[98:99], v[162:163], 0, v[98:99]
	v_mul_f32_e32 v103, 0x45800000, v102
	v_cndmask_b32_e32 v102, v102, v103, vcc
	v_pk_mul_f32 v[94:95], v[94:95], v[102:103] op_sel_hi:[1,0]
	v_pk_mul_f32 v[92:93], v[92:93], v[102:103] op_sel_hi:[1,0]
	v_pk_mul_f32 v[90:91], v[90:91], v[102:103] op_sel_hi:[1,0]
	v_pk_mul_f32 v[88:89], v[88:89], v[102:103] op_sel_hi:[1,0]
	v_pk_mul_f32 v[86:87], v[86:87], v[102:103] op_sel_hi:[1,0]
	v_pk_mul_f32 v[84:85], v[84:85], v[102:103] op_sel_hi:[1,0]
	v_pk_mul_f32 v[104:105], v[78:79], v[102:103] op_sel_hi:[1,0]
	v_pk_mul_f32 v[102:103], v[76:77], v[102:103] op_sel_hi:[1,0]
	v_cvt_pk_bf16_f32 v76, v92, v93
	v_cvt_pk_bf16_f32 v77, v94, v95
	v_cvt_pk_bf16_f32 v78, v88, v89
	v_cvt_pk_bf16_f32 v79, v90, v91
	global_store_dwordx4 v[98:99], v[76:79], off
	s_nop 1
	v_cvt_pk_bf16_f32 v76, v84, v85
	v_cvt_pk_bf16_f32 v77, v86, v87
	v_cvt_pk_bf16_f32 v78, v102, v103
	v_cvt_pk_bf16_f32 v79, v104, v105
	global_store_dwordx4 v[98:99], v[76:79], off offset:256
	s_nop 1
	v_mov_b32_e32 v76, v242
	v_fmamk_f32 v76, v76, 0x3b000000, v157
	v_mul_f32_e32 v77, 0x4b800000, v76
	v_cmp_gt_f32_e32 vcc, s59, v76
	s_nop 1
	v_cndmask_b32_e32 v76, v76, v77, vcc
	v_rsq_f32_e32 v78, v76
	v_lshlrev_b64 v[76:77], 12, v[96:97]
	v_lshl_add_u64 v[76:77], v[162:163], 0, v[76:77]
	v_mul_f32_e32 v79, 0x45800000, v78
	v_cndmask_b32_e32 v78, v78, v79, vcc
	v_pk_mul_f32 v[82:83], v[82:83], v[78:79] op_sel_hi:[1,0]
	v_pk_mul_f32 v[80:81], v[80:81], v[78:79] op_sel_hi:[1,0]
;     __device__ __forceinline__ void operator()(const f32x4 (&acc)[2][2][4][2], const Unit& u, int wr, int wc, int fr, int fq) const {
;         const int row0 = u.pm * BM + wr * 64 + fr, cl = wc * 32 + 8 * fq;
;         bf16_t* base = (u.pn < 8 ? KN + u.pn * 256 : V1 + (u.pn - 8) * 256) + cl;
; #pragma unroll
;         for (int ai = 0; ai < 2; ++ai)
; #pragma unroll
;             for (int m = 0; m < 4; ++m) { const int row = row0 + ai * HALF + m * 16; const float rs = rsqrtf(ssq[row] * (1.0f / 512.0f) + EPS);
; #pragma unroll
;                 for (int bj = 0; bj < 2; ++bj) st8(base + (size_t)row * 2048 + bj * HALF, acc[ai][bj][m][0] * rs, acc[ai][bj][m][1] * rs); }
;     }
	v_pk_mul_f32 v[74:75], v[74:75], v[78:79] op_sel_hi:[1,0]
	v_pk_mul_f32 v[72:73], v[72:73], v[78:79] op_sel_hi:[1,0]
	v_pk_mul_f32 v[70:71], v[70:71], v[78:79] op_sel_hi:[1,0]
	v_pk_mul_f32 v[68:69], v[68:69], v[78:79] op_sel_hi:[1,0]
	v_pk_mul_f32 v[84:85], v[66:67], v[78:79] op_sel_hi:[1,0]
	v_pk_mul_f32 v[78:79], v[64:65], v[78:79] op_sel_hi:[1,0]
	v_cvt_pk_bf16_f32 v64, v80, v81
	v_cvt_pk_bf16_f32 v65, v82, v83
	v_cvt_pk_bf16_f32 v66, v72, v73
	v_cvt_pk_bf16_f32 v67, v74, v75
	global_store_dwordx4 v[76:77], v[64:67], off
	s_nop 1
	v_cvt_pk_bf16_f32 v64, v68, v69
	v_cvt_pk_bf16_f32 v65, v70, v71
	v_cvt_pk_bf16_f32 v66, v78, v79
	v_cvt_pk_bf16_f32 v67, v84, v85
	global_store_dwordx4 v[76:77], v[64:67], off offset:256
	s_nop 1
	v_mov_b32_e32 v66, v243
	s_nop 0
	v_lshl_add_u64 v[64:65], v[148:149], 0, s[16:17]
	v_fmamk_f32 v66, v66, 0x3b000000, v157
	v_mul_f32_e32 v67, 0x4b800000, v66
	v_cmp_gt_f32_e32 vcc, s59, v66
	s_nop 1
	v_cndmask_b32_e32 v66, v66, v67, vcc
	v_rsq_f32_e32 v68, v66
	v_add_co_u32_e64 v66, s[0:1], s60, v148
	v_mul_f32_e32 v69, 0x45800000, v68
	v_cndmask_b32_e32 v68, v68, v69, vcc
	v_addc_co_u32_e64 v67, s[0:1], 0, v149, s[0:1]
	v_pk_mul_f32 v[62:63], v[62:63], v[68:69] op_sel_hi:[1,0]
	v_pk_mul_f32 v[60:61], v[60:61], v[68:69] op_sel_hi:[1,0]
	v_pk_mul_f32 v[58:59], v[58:59], v[68:69] op_sel_hi:[1,0]
	v_pk_mul_f32 v[56:57], v[56:57], v[68:69] op_sel_hi:[1,0]
	v_pk_mul_f32 v[54:55], v[54:55], v[68:69] op_sel_hi:[1,0]
	v_pk_mul_f32 v[52:53], v[52:53], v[68:69] op_sel_hi:[1,0]
	v_pk_mul_f32 v[70:71], v[50:51], v[68:69] op_sel_hi:[1,0]
	v_pk_mul_f32 v[68:69], v[48:49], v[68:69] op_sel_hi:[1,0]
	v_cvt_pk_bf16_f32 v48, v60, v61
	v_cvt_pk_bf16_f32 v49, v62, v63
	v_cvt_pk_bf16_f32 v50, v56, v57
	v_cvt_pk_bf16_f32 v51, v58, v59
	global_store_dwordx4 v[66:67], v[48:51], off
	s_nop 1
	v_cvt_pk_bf16_f32 v48, v52, v53
	v_cvt_pk_bf16_f32 v49, v54, v55
	v_cvt_pk_bf16_f32 v50, v68, v69
	v_cvt_pk_bf16_f32 v51, v70, v71
	global_store_dwordx4 v[64:65], v[48:51], off offset:256
	s_nop 1
	v_mov_b32_e32 v50, v244
	s_nop 0
	v_lshl_add_u64 v[48:49], v[148:149], 0, s[18:19]
	v_fmamk_f32 v50, v50, 0x3b000000, v157
	v_mul_f32_e32 v51, 0x4b800000, v50
	v_cmp_gt_f32_e32 vcc, s59, v50
	s_nop 1
	v_cndmask_b32_e32 v50, v50, v51, vcc
	v_rsq_f32_e32 v52, v50
	v_add_co_u32_e64 v50, s[0:1], s61, v148
	v_mul_f32_e32 v53, 0x45800000, v52
	v_cndmask_b32_e32 v52, v52, v53, vcc
	v_addc_co_u32_e64 v51, s[0:1], 0, v149, s[0:1]
	v_pk_mul_f32 v[46:47], v[46:47], v[52:53] op_sel_hi:[1,0]
	v_pk_mul_f32 v[44:45], v[44:45], v[52:53] op_sel_hi:[1,0]
	v_pk_mul_f32 v[42:43], v[42:43], v[52:53] op_sel_hi:[1,0]
	v_pk_mul_f32 v[40:41], v[40:41], v[52:53] op_sel_hi:[1,0]
	v_pk_mul_f32 v[38:39], v[38:39], v[52:53] op_sel_hi:[1,0]
	v_pk_mul_f32 v[36:37], v[36:37], v[52:53] op_sel_hi:[1,0]
	v_pk_mul_f32 v[54:55], v[34:35], v[52:53] op_sel_hi:[1,0]
	v_pk_mul_f32 v[52:53], v[32:33], v[52:53] op_sel_hi:[1,0]
	v_cvt_pk_bf16_f32 v32, v44, v45
	v_cvt_pk_bf16_f32 v33, v46, v47
	v_cvt_pk_bf16_f32 v34, v40, v41
	v_cvt_pk_bf16_f32 v35, v42, v43
	global_store_dwordx4 v[50:51], v[32:35], off
	s_nop 1
	v_cvt_pk_bf16_f32 v32, v36, v37
	v_cvt_pk_bf16_f32 v33, v38, v39
	v_cvt_pk_bf16_f32 v34, v52, v53
	v_cvt_pk_bf16_f32 v35, v54, v55
	global_store_dwordx4 v[48:49], v[32:35], off offset:256
	s_nop 1
	v_mov_b32_e32 v34, v245
	s_nop 0
	v_lshl_add_u64 v[32:33], v[148:149], 0, s[20:21]
	v_fmamk_f32 v34, v34, 0x3b000000, v157
	v_mul_f32_e32 v35, 0x4b800000, v34
	v_cmp_gt_f32_e32 vcc, s59, v34
	s_nop 1
	v_cndmask_b32_e32 v34, v34, v35, vcc
	v_rsq_f32_e32 v36, v34
	v_add_co_u32_e64 v34, s[0:1], s62, v148
	v_mul_f32_e32 v37, 0x45800000, v36
	v_cndmask_b32_e32 v36, v36, v37, vcc
	v_addc_co_u32_e64 v35, s[0:1], 0, v149, s[0:1]
	v_pk_mul_f32 v[30:31], v[30:31], v[36:37] op_sel_hi:[1,0]
	v_pk_mul_f32 v[28:29], v[28:29], v[36:37] op_sel_hi:[1,0]
	v_pk_mul_f32 v[26:27], v[26:27], v[36:37] op_sel_hi:[1,0]
	v_pk_mul_f32 v[24:25], v[24:25], v[36:37] op_sel_hi:[1,0]
	v_pk_mul_f32 v[22:23], v[22:23], v[36:37] op_sel_hi:[1,0]
	v_pk_mul_f32 v[20:21], v[20:21], v[36:37] op_sel_hi:[1,0]
	v_pk_mul_f32 v[38:39], v[18:19], v[36:37] op_sel_hi:[1,0]
	v_pk_mul_f32 v[36:37], v[16:17], v[36:37] op_sel_hi:[1,0]
	v_cvt_pk_bf16_f32 v16, v28, v29
	v_cvt_pk_bf16_f32 v17, v30, v31
	v_cvt_pk_bf16_f32 v18, v24, v25
	v_cvt_pk_bf16_f32 v19, v26, v27
	global_store_dwordx4 v[34:35], v[16:19], off
	s_andn2_b64 vcc, exec, s[2:3]
	s_nop 0
	v_cvt_pk_bf16_f32 v16, v20, v21
	v_cvt_pk_bf16_f32 v17, v22, v23
	v_cvt_pk_bf16_f32 v18, v36, v37
	v_cvt_pk_bf16_f32 v19, v38, v39
	global_store_dwordx4 v[32:33], v[16:19], off offset:256
	s_nop 1
	v_mov_b32_e32 v18, v246
	s_nop 0
	v_lshl_add_u64 v[16:17], v[148:149], 0, s[22:23]
	v_fmamk_f32 v18, v18, 0x3b000000, v157
	v_mul_f32_e32 v19, 0x4b800000, v18
	v_cmp_gt_f32_e64 s[0:1], s59, v18
	s_nop 1
	v_cndmask_b32_e64 v18, v18, v19, s[0:1]
	v_rsq_f32_e32 v20, v18
	v_add_co_u32_e64 v18, s[2:3], s63, v148
	v_mul_f32_e32 v21, 0x45800000, v20
	v_cndmask_b32_e64 v20, v20, v21, s[0:1]
	v_addc_co_u32_e64 v19, s[2:3], 0, v149, s[2:3]
	v_pk_mul_f32 v[14:15], v[14:15], v[20:21] op_sel_hi:[1,0]
	v_pk_mul_f32 v[12:13], v[12:13], v[20:21] op_sel_hi:[1,0]
	v_pk_mul_f32 v[10:11], v[10:11], v[20:21] op_sel_hi:[1,0]
	v_pk_mul_f32 v[8:9], v[8:9], v[20:21] op_sel_hi:[1,0]
	v_pk_mul_f32 v[6:7], v[6:7], v[20:21] op_sel_hi:[1,0]
	v_pk_mul_f32 v[4:5], v[4:5], v[20:21] op_sel_hi:[1,0]
	v_pk_mul_f32 v[22:23], v[2:3], v[20:21] op_sel_hi:[1,0]
	v_pk_mul_f32 v[20:21], v[0:1], v[20:21] op_sel_hi:[1,0]
	v_cvt_pk_bf16_f32 v0, v12, v13
	v_cvt_pk_bf16_f32 v1, v14, v15
	v_cvt_pk_bf16_f32 v2, v8, v9
	v_cvt_pk_bf16_f32 v3, v10, v11
	s_mov_b64 s[0:1], -1
	global_store_dwordx4 v[18:19], v[0:3], off
	s_nop 1
	v_cvt_pk_bf16_f32 v0, v4, v5
	v_cvt_pk_bf16_f32 v1, v6, v7
	v_cvt_pk_bf16_f32 v2, v20, v21
	v_cvt_pk_bf16_f32 v3, v22, v23
	global_store_dwordx4 v[16:17], v[0:3], off offset:256
	s_cbranch_vccnz .LBB0_883
	s_andn2_b64 vcc, exec, s[10:11]
	s_cbranch_vccnz .LBB0_882
	s_barrier
	s_branch .LBB0_882

; __device__ __forceinline__ void finishSM(f32x16& p0, f32x16& p1, float alpha, float& l_reg, bf16x8& pa0, bf16x8& pa1, bf16x8& pa2, bf16x8& pa3) {
; #pragma unroll
;     for (int r = 0; r < 16; ++r) p1[r] = __builtin_amdgcn_exp2f(p1[r]);
;     float ps = 0;
; #pragma unroll
;     for (int r = 0; r < 16; ++r) ps += p0[r];
; #pragma unroll
;     for (int r = 0; r < 16; ++r) ps += p1[r];
;     { auto rr = __builtin_amdgcn_permlane32_swap(__float_as_uint(ps), __float_as_uint(ps), false, false);
;       ps = __uint_as_float(rr[0]) + __uint_as_float(rr[1]); }
;     l_reg = l_reg * alpha + ps;
;     PK4(p0, 0, pa0); PK4(p0, 8, pa1); PK4(p1, 0, pa2); PK4(p1, 8, pa3);
; }
; template <int KB>
; __device__ __forceinline__ void qkt(f32x16& p0, f32x16& p1, const char* K_lds, int r32, int hi, const bf16x8* qr, const char* qx) {
;     p0 = f32x16{}; p1 = f32x16{};
;     const char* kb[4];
; #pragma unroll
;     for (int dd = 0; dd < 4; ++dd) kb[dd] = K_lds + KB * SHM_K + KSWZ(r32, (dd * 16 + hi * 8) * 2);
; #pragma unroll
;     for (int d0 = 0; d0 < 12; ++d0) { const char* a = kb[d0 & 3] + (d0 >> 2) * 128;
;         bf16x8 b0 = *reinterpret_cast<const bf16x8*>(a);
;         bf16x8 b1 = *reinterpret_cast<const bf16x8*>(a + 32 * 384);
;         const bf16x8 q = d0 < 8 ? qr[d0 & 7] : *reinterpret_cast<const bf16x8*>(qx + (d0 - 8) * 1024);
;         p0 = __builtin_amdgcn_mfma_f32_32x32x16_bf16(b0, q, p0, 0, 0, 0);
;         p1 = __builtin_amdgcn_mfma_f32_32x32x16_bf16(b1, q, p1, 0, 0, 0); }
.LBB0_971:
	ds_read_b128 v[178:181], v194 offset:24576
	ds_read_b128 v[220:223], v194 offset:36864
	ds_read_b128 v[224:227], v195 offset:24576
	ds_read_b128 v[228:231], v195 offset:36864
	ds_read_b128 v[232:235], v196 offset:24576
	ds_read_b128 v[236:239], v196 offset:36864
	v_add_f32_e32 v149, 0, v159
	v_add_f32_e32 v149, v161, v149
	s_nop 1
	v_add_f32_e32 v149, v157, v149
	v_add_f32_e32 v149, v160, v149
	s_waitcnt lgkmcnt(5)
	v_mfma_f32_32x32x16_bf16 v[80:95], v[178:181], v[124:127], 0
	v_add_f32_e32 v149, v156, v149
	v_add_f32_e32 v149, v158, v149
	v_add_f32_e32 v149, v154, v149
	s_waitcnt lgkmcnt(4)
	v_mfma_f32_32x32x16_bf16 v[64:79], v[220:223], v[124:127], 0
	ds_read_b128 v[178:181], v197 offset:24576
	ds_read_b128 v[220:223], v197 offset:36864
	v_add_f32_e32 v149, v155, v149
	v_add_f32_e32 v149, v150, v149
	s_nop 1
	v_add_f32_e32 v149, v153, v149
	s_waitcnt lgkmcnt(5)
	v_mfma_f32_32x32x16_bf16 v[80:95], v[224:227], v[120:123], v[80:95]
	v_add_f32_e32 v149, v146, v149
	v_add_f32_e32 v149, v151, v149
	v_exp_f32_e32 v142, v142
	s_waitcnt lgkmcnt(4)
	v_mfma_f32_32x32x16_bf16 v[64:79], v[228:231], v[120:123], v[64:79]
	ds_read_b128 v[224:227], v194 offset:24704
	ds_read_b128 v[228:231], v194 offset:36992
	v_add_f32_e32 v149, v144, v149
	v_exp_f32_e32 v143, v143
	v_add_f32_e32 v149, v152, v149
	s_waitcnt lgkmcnt(5)
	v_mfma_f32_32x32x16_bf16 v[80:95], v[232:235], v[116:119], v[80:95]
	v_exp_f32_e32 v140, v140
	v_add_f32_e32 v149, v145, v149
	v_exp_f32_e32 v141, v141
	s_waitcnt lgkmcnt(4)
	v_mfma_f32_32x32x16_bf16 v[64:79], v[236:239], v[116:119], v[64:79]
	ds_read_b128 v[232:235], v195 offset:24704
	ds_read_b128 v[236:239], v195 offset:36992
	v_add_f32_e32 v149, v147, v149
	v_exp_f32_e32 v138, v138
	v_add_f32_e32 v149, v142, v149
	s_waitcnt lgkmcnt(5)
	v_mfma_f32_32x32x16_bf16 v[80:95], v[178:181], v[112:115], v[80:95]
	v_exp_f32_e32 v139, v139
	s_nop 1
	v_add_f32_e32 v149, v143, v149
	v_exp_f32_e32 v136, v136
	s_waitcnt lgkmcnt(4)
	v_mfma_f32_32x32x16_bf16 v[64:79], v[220:223], v[112:115], v[64:79]
	ds_read_b128 v[178:181], v196 offset:24704
	ds_read_b128 v[220:223], v196 offset:36992
	v_add_f32_e32 v149, v140, v149
	v_exp_f32_e32 v137, v137
	v_add_f32_e32 v149, v141, v149
	s_waitcnt lgkmcnt(5)
	v_mfma_f32_32x32x16_bf16 v[80:95], v[224:227], v[108:111], v[80:95]
	v_exp_f32_e32 v134, v134
	s_nop 1
	v_add_f32_e32 v149, v138, v149
	v_exp_f32_e32 v135, v135
	s_waitcnt lgkmcnt(4)
	v_mfma_f32_32x32x16_bf16 v[64:79], v[228:231], v[108:111], v[64:79]
	ds_read_b128 v[224:227], v197 offset:24704
	ds_read_b128 v[228:231], v197 offset:36992
	v_add_f32_e32 v149, v139, v149
	v_exp_f32_e32 v132, v132
	v_add_f32_e32 v149, v136, v149
	s_waitcnt lgkmcnt(5)
	v_mfma_f32_32x32x16_bf16 v[80:95], v[232:235], v[104:107], v[80:95]
	v_exp_f32_e32 v133, v133
	v_add_f32_e32 v149, v137, v149
	s_nop 1
	v_exp_f32_e32 v130, v130
	s_waitcnt lgkmcnt(4)
	v_mfma_f32_32x32x16_bf16 v[64:79], v[236:239], v[104:107], v[64:79]
	ds_read_b128 v[240:243], v204
	ds_read_b128 v[232:235], v194 offset:24832
	ds_read_b128 v[236:239], v194 offset:37120
	v_add_f32_e32 v149, v134, v149
	v_exp_f32_e32 v131, v131
	v_add_f32_e32 v149, v135, v149
	s_waitcnt lgkmcnt(6)
	v_mfma_f32_32x32x16_bf16 v[80:95], v[178:181], v[100:103], v[80:95]
	v_exp_f32_e32 v128, v128
	v_add_f32_e32 v149, v132, v149
	s_nop 1
	v_exp_f32_e32 v129, v129
	s_waitcnt lgkmcnt(5)
	v_mfma_f32_32x32x16_bf16 v[64:79], v[220:223], v[100:103], v[64:79]
	ds_read_b128 v[244:247], v204 offset:1024
	ds_read_b128 v[178:181], v195 offset:24832
	ds_read_b128 v[220:223], v195 offset:37120
	v_add_f32_e32 v149, v133, v149
	v_add_f32_e32 v149, v130, v149
	v_add_f32_e32 v149, v131, v149
	s_waitcnt lgkmcnt(7)
	v_mfma_f32_32x32x16_bf16 v[80:95], v[224:227], v[96:99], v[80:95]
	v_add_f32_e32 v149, v128, v149
	v_add_f32_e32 v211, v129, v149
	s_nop 1
	v_mov_b32_e32 v212, v211
	s_waitcnt lgkmcnt(6)
	v_mfma_f32_32x32x16_bf16 v[64:79], v[228:231], v[96:99], v[64:79]
	ds_read_b128 v[224:227], v196 offset:24832
	ds_read_b128 v[228:231], v196 offset:37120
	s_nop 1
	v_permlane32_swap_b32_e32 v211, v212
	v_cvt_pk_bf16_f32 v214, v159, v161
	s_waitcnt lgkmcnt(6)
	v_mfma_f32_32x32x16_bf16 v[80:95], v[232:235], v[240:243], v[80:95]
	v_cvt_pk_bf16_f32 v215, v157, v160
	v_cvt_pk_bf16_f32 v216, v156, v158
	v_cvt_pk_bf16_f32 v217, v154, v155
	s_waitcnt lgkmcnt(5)
	v_mfma_f32_32x32x16_bf16 v[64:79], v[236:239], v[240:243], v[64:79]
	ds_read_b128 v[232:235], v197 offset:24832
	ds_read_b128 v[236:239], v197 offset:37120
	ds_read_b128 v[240:243], v204 offset:2048
	v_cvt_pk_bf16_f32 v150, v150, v153
	v_cvt_pk_bf16_f32 v151, v146, v151
	v_cvt_pk_bf16_f32 v152, v144, v152
	s_waitcnt lgkmcnt(6)
	v_mfma_f32_32x32x16_bf16 v[80:95], v[178:181], v[244:247], v[80:95]
	v_cvt_pk_bf16_f32 v153, v145, v147
	v_cvt_pk_bf16_f32 v154, v142, v143
	v_cvt_pk_bf16_f32 v155, v140, v141
	s_waitcnt lgkmcnt(5)
	v_mfma_f32_32x32x16_bf16 v[64:79], v[220:223], v[244:247], v[64:79]
	ds_read_b128 v[244:247], v204 offset:3072
	v_cvt_pk_bf16_f32 v156, v138, v139
	v_cvt_pk_bf16_f32 v157, v136, v137
	v_cvt_pk_bf16_f32 v158, v134, v135
	s_waitcnt lgkmcnt(1)
	v_mfma_f32_32x32x16_bf16 v[80:95], v[224:227], v[240:243], v[80:95]
	v_cvt_pk_bf16_f32 v159, v132, v133
	v_cvt_pk_bf16_f32 v160, v130, v131
	v_cvt_pk_bf16_f32 v161, v128, v129
	s_waitcnt lgkmcnt(4)
	v_mfma_f32_32x32x16_bf16 v[64:79], v[228:231], v[240:243], v[64:79]
	s_nop 0
	v_permlane32_swap_b32_e32 v214, v216
	v_permlane32_swap_b32_e32 v215, v217
	s_waitcnt lgkmcnt(0)
	v_mfma_f32_32x32x16_bf16 v[80:95], v[232:235], v[244:247], v[80:95]
	v_permlane32_swap_b32_e32 v150, v152
	v_permlane32_swap_b32_e32 v151, v153
	v_permlane32_swap_b32_e32 v154, v156
	s_waitcnt lgkmcnt(2)
; template <int VB>
; __device__ __forceinline__ void pv_tile(f32x16* o, int vb0, bf16x8 pa0, bf16x8 pa1, bf16x8 pa2, bf16x8 pa3) {
;     ...
;     PV_D2(0, 1); PV_D2(2, 3);
	v_mfma_f32_32x32x16_bf16 v[64:79], v[236:239], v[244:247], v[64:79]
	v_permlane32_swap_b32_e32 v155, v157
	v_permlane32_swap_b32_e32 v158, v160
	v_permlane32_swap_b32_e32 v159, v161
	v_lshl_add_u64 v[180:181], s[70:71], 0, v[170:171]
	v_add_co_u32_e32 v128, vcc, s76, v180
	v_lshl_add_u64 v[178:179], s[96:97], 0, v[170:171]
	s_nop 0
	v_addc_co_u32_e32 v129, vcc, 0, v181, vcc
	v_add_co_u32_e32 v132, vcc, s77, v180
	s_nop 1
	v_addc_co_u32_e32 v133, vcc, 0, v181, vcc
	v_add_co_u32_e32 v136, vcc, s76, v178
	s_nop 1
	v_addc_co_u32_e32 v137, vcc, 0, v179, vcc
	v_add_co_u32_e32 v140, vcc, s77, v178
	s_nop 1
	v_addc_co_u32_e32 v141, vcc, 0, v179, vcc
	global_load_dwordx4 v[136:139], v[136:137], off
	global_load_dwordx4 v[140:143], v[140:141], off
	global_load_dwordx4 v[144:147], v[176:177], off
	global_load_dwordx4 v[128:131], v[128:129], off
	global_load_dwordx4 v[132:135], v[132:133], off
	ds_read_b64_tr_b16 v[218:219], v188 offset:0
	ds_read_b64_tr_b16 v[220:221], v188 offset:0x800
	ds_read_b64_tr_b16 v[222:223], v188 offset:0x200
	ds_read_b64_tr_b16 v[224:225], v188 offset:0xa00
	ds_read_b64_tr_b16 v[226:227], v188 offset:0x1000
	ds_read_b64_tr_b16 v[228:229], v188 offset:0x1800
	ds_read_b64_tr_b16 v[230:231], v188 offset:0x1200
	ds_read_b64_tr_b16 v[232:233], v188 offset:0x1a00
	ds_read_b64_tr_b16 v[234:235], v188 offset:0x2000
	ds_read_b64_tr_b16 v[236:237], v188 offset:0x2800
	ds_read_b64_tr_b16 v[238:239], v188 offset:0x2200
	ds_read_b64_tr_b16 v[240:241], v188 offset:0x2a00
	ds_read_b64_tr_b16 v[242:243], v188 offset:0x3000
	ds_read_b64_tr_b16 v[244:245], v188 offset:0x3800
	ds_read_b64_tr_b16 v[246:247], v188 offset:0x3200
	ds_read_b64_tr_b16 v[248:249], v188 offset:0x3a00
	s_waitcnt lgkmcnt(14)
	s_nop 0
	v_mfma_f32_32x32x16_bf16 v[48:63], v[214:217], v[218:221], v[48:63]
	ds_read_b64_tr_b16 v[218:219], v188 offset:0x400
	ds_read_b64_tr_b16 v[220:221], v188 offset:0xc00
	s_waitcnt lgkmcnt(14)
	v_mfma_f32_32x32x16_bf16 v[32:47], v[214:217], v[222:225], v[32:47]
	ds_read_b64_tr_b16 v[222:223], v188 offset:0x600
	ds_read_b64_tr_b16 v[224:225], v188 offset:0xe00
	s_waitcnt lgkmcnt(14)
	v_mfma_f32_32x32x16_bf16 v[48:63], v[150:153], v[226:229], v[48:63]
	ds_read_b64_tr_b16 v[226:227], v188 offset:0x1400
	ds_read_b64_tr_b16 v[228:229], v188 offset:0x1c00
	s_waitcnt lgkmcnt(14)
	v_mfma_f32_32x32x16_bf16 v[32:47], v[150:153], v[230:233], v[32:47]
	ds_read_b64_tr_b16 v[230:231], v188 offset:0x1600
	ds_read_b64_tr_b16 v[232:233], v188 offset:0x1e00
	s_waitcnt lgkmcnt(14)
	v_mfma_f32_32x32x16_bf16 v[48:63], v[154:157], v[234:237], v[48:63]
	ds_read_b64_tr_b16 v[234:235], v188 offset:0x2400
	ds_read_b64_tr_b16 v[236:237], v188 offset:0x2c00
	s_waitcnt lgkmcnt(14)
	v_mfma_f32_32x32x16_bf16 v[32:47], v[154:157], v[238:241], v[32:47]
	ds_read_b64_tr_b16 v[238:239], v188 offset:0x2600
	ds_read_b64_tr_b16 v[240:241], v188 offset:0x2e00
	s_waitcnt lgkmcnt(14)
	v_mfma_f32_32x32x16_bf16 v[48:63], v[158:161], v[242:245], v[48:63]
	ds_read_b64_tr_b16 v[242:243], v188 offset:0x3400
	ds_read_b64_tr_b16 v[244:245], v188 offset:0x3c00
	s_waitcnt lgkmcnt(14)
	v_mfma_f32_32x32x16_bf16 v[32:47], v[158:161], v[246:249], v[32:47]
	ds_read_b64_tr_b16 v[250:251], v188 offset:0x3600
	ds_read_b64_tr_b16 v[252:253], v188 offset:0x3e00
	s_waitcnt lgkmcnt(14)
	v_mfma_f32_32x32x16_bf16 v[16:31], v[214:217], v[218:221], v[16:31]
	s_sub_i32 s0, s68, 64
	s_cmp_le_i32 s0, s95
	s_waitcnt lgkmcnt(12)
	v_mfma_f32_32x32x16_bf16 v[0:15], v[214:217], v[222:225], v[0:15]
	s_waitcnt lgkmcnt(10)
	v_mfma_f32_32x32x16_bf16 v[16:31], v[150:153], v[226:229], v[16:31]
	s_waitcnt lgkmcnt(8)
	v_mfma_f32_32x32x16_bf16 v[0:15], v[150:153], v[230:233], v[0:15]
	s_waitcnt lgkmcnt(6)
	v_mfma_f32_32x32x16_bf16 v[16:31], v[154:157], v[234:237], v[16:31]
	s_waitcnt lgkmcnt(4)
	v_mfma_f32_32x32x16_bf16 v[0:15], v[154:157], v[238:241], v[0:15]
	s_waitcnt lgkmcnt(2)
	v_mfma_f32_32x32x16_bf16 v[16:31], v[158:161], v[242:245], v[16:31]
	s_waitcnt lgkmcnt(0)
	v_mfma_f32_32x32x16_bf16 v[0:15], v[158:161], v[250:253], v[0:15]
	s_waitcnt vmcnt(2)
	ds_write_b128 v169, v[136:139]
	ds_write_b128 v169, v[140:143] offset:12288
	ds_write_b128 v182, v[144:147]
	s_cbranch_scc1 .LBB0_973
; __device__ __forceinline__ void mask_tile(f32x16& p0, f32x16& p1, int dq) {
;     const float NEG = -__builtin_inff();
; #pragma unroll
;     for (int r = 0; r < 16; ++r) { const int c = (r & 3) + 8 * (r >> 2); if (dq - c < 0) p0[r] = NEG; if (dq - c - 32 < 0) p1[r] = NEG; }
; }
	v_add_u32_e32 v149, 64, v210
	v_cmp_gt_i32_e64 s[64:65], 26, v149
	v_cmp_gt_i32_e64 s[66:67], 27, v149
	v_cmp_gt_i32_e64 s[62:63], 25, v149
	s_and_b64 s[64:65], s[66:67], s[64:65]
	v_cmp_gt_i32_e64 s[60:61], 24, v149
	s_and_b64 s[62:63], s[64:65], s[62:63]
	v_cmp_gt_i32_e64 s[58:59], 19, v149
	s_and_b64 s[60:61], s[62:63], s[60:61]
	v_cmp_gt_i32_e64 s[56:57], 18, v149
	s_and_b64 s[58:59], s[60:61], s[58:59]
	v_cmp_gt_i32_e64 s[54:55], 17, v149
	s_and_b64 s[56:57], s[58:59], s[56:57]
	v_cmp_gt_i32_e64 s[52:53], 16, v149
	s_and_b64 s[54:55], s[56:57], s[54:55]
	v_cmp_gt_i32_e64 s[50:51], 11, v149
	s_and_b64 s[52:53], s[54:55], s[52:53]
	v_cmp_gt_i32_e64 s[48:49], 10, v149
	s_and_b64 s[50:51], s[52:53], s[50:51]
	v_cmp_gt_i32_e64 s[46:47], 9, v149
	s_and_b64 s[48:49], s[50:51], s[48:49]
	v_cmp_gt_i32_e64 s[44:45], 8, v149
	s_and_b64 s[46:47], s[48:49], s[46:47]
	v_cmp_gt_i32_e64 s[42:43], 3, v149
	s_and_b64 s[44:45], s[46:47], s[44:45]
	v_cmp_gt_i32_e64 s[40:41], 2, v149
	s_and_b64 s[42:43], s[44:45], s[42:43]
	v_cmp_gt_i32_e64 s[38:39], 1, v149
	s_and_b64 s[40:41], s[42:43], s[40:41]
	v_cmp_gt_i32_e64 s[34:35], 0, v149
	s_and_b64 s[38:39], s[40:41], s[38:39]
	s_and_b64 s[34:35], s[38:39], s[34:35]
	v_cmp_gt_i32_e64 s[30:31], 58, v149
	v_cndmask_b32_e64 v80, v80, v198, s[34:35]
	v_cmp_gt_i32_e64 s[34:35], 59, v149
	v_cmp_gt_i32_e64 s[28:29], 57, v149
	s_and_b64 s[30:31], s[34:35], s[30:31]
	v_cmp_gt_i32_e64 s[26:27], 56, v149
	s_and_b64 s[28:29], s[30:31], s[28:29]
	v_cmp_gt_i32_e64 s[24:25], 51, v149
	s_and_b64 s[26:27], s[28:29], s[26:27]
	v_cmp_gt_i32_e64 s[22:23], 50, v149
	s_and_b64 s[24:25], s[26:27], s[24:25]
	v_cmp_gt_i32_e64 s[20:21], 49, v149
	s_and_b64 s[22:23], s[24:25], s[22:23]
	v_cmp_gt_i32_e64 s[18:19], 48, v149
	s_and_b64 s[20:21], s[22:23], s[20:21]
	v_cmp_gt_i32_e64 s[16:17], 43, v149
	s_and_b64 s[18:19], s[20:21], s[18:19]
	v_cmp_gt_i32_e64 s[14:15], 42, v149
	s_and_b64 s[16:17], s[18:19], s[16:17]
	v_cmp_gt_i32_e64 s[12:13], 41, v149
	s_and_b64 s[14:15], s[16:17], s[14:15]
	v_cmp_gt_i32_e64 s[10:11], 40, v149
	s_and_b64 s[12:13], s[14:15], s[12:13]
	v_cmp_gt_i32_e64 s[8:9], 35, v149
	s_and_b64 s[10:11], s[12:13], s[10:11]
	v_cmp_gt_i32_e64 s[6:7], 34, v149
	s_and_b64 s[8:9], s[10:11], s[8:9]
	v_cmp_gt_i32_e64 s[0:1], 33, v149
	s_and_b64 s[6:7], s[8:9], s[6:7]
	v_cmp_gt_i32_e32 vcc, 32, v149
	s_and_b64 s[0:1], s[6:7], s[0:1]
	s_and_b64 vcc, s[0:1], vcc
	v_cndmask_b32_e64 v95, v95, v198, s[66:67]
	v_cndmask_b32_e64 v94, v94, v198, s[64:65]
	v_cndmask_b32_e64 v93, v93, v198, s[62:63]
	v_cndmask_b32_e64 v92, v92, v198, s[60:61]
	v_cndmask_b32_e64 v91, v91, v198, s[58:59]
	v_cndmask_b32_e64 v90, v90, v198, s[56:57]
	v_cndmask_b32_e64 v89, v89, v198, s[54:55]
	v_cndmask_b32_e64 v88, v88, v198, s[52:53]
	v_cndmask_b32_e64 v87, v87, v198, s[50:51]
	v_cndmask_b32_e64 v86, v86, v198, s[48:49]
	v_cndmask_b32_e64 v85, v85, v198, s[46:47]
	v_cndmask_b32_e64 v84, v84, v198, s[44:45]
	v_cndmask_b32_e64 v83, v83, v198, s[42:43]
	v_cndmask_b32_e64 v82, v82, v198, s[40:41]
	v_cndmask_b32_e64 v81, v81, v198, s[38:39]
	v_cndmask_b32_e64 v79, v79, v198, s[34:35]
	v_cndmask_b32_e64 v78, v78, v198, s[30:31]
	v_cndmask_b32_e64 v77, v77, v198, s[28:29]
	v_cndmask_b32_e64 v76, v76, v198, s[26:27]
	v_cndmask_b32_e64 v75, v75, v198, s[24:25]
	v_cndmask_b32_e64 v74, v74, v198, s[22:23]
	v_cndmask_b32_e64 v73, v73, v198, s[20:21]
	v_cndmask_b32_e64 v72, v72, v198, s[18:19]
	v_cndmask_b32_e64 v71, v71, v198, s[16:17]
	v_cndmask_b32_e64 v70, v70, v198, s[14:15]
	v_cndmask_b32_e64 v69, v69, v198, s[12:13]
	v_cndmask_b32_e64 v68, v68, v198, s[10:11]
	v_cndmask_b32_e64 v67, v67, v198, s[8:9]
	v_cndmask_b32_e64 v66, v66, v198, s[6:7]
	v_cndmask_b32_e64 v65, v65, v198, s[0:1]
	v_cndmask_b32_e32 v64, v64, v198, vcc

; __device__ __forceinline__ void partialSM(f32x16& p0, f32x16& p1, float& m_reg, float& mn, float& alpha) {
;     ...
;     constexpr float C2 = 1.4426950408889634f * SCALE;
;     if (__builtin_expect(__all((pmax - m_reg) * SCALE <= THR), 1)) { mn = m_reg; alpha = 1.f; }
;     else { mn = fmaxf(m_reg, pmax); alpha = __builtin_amdgcn_exp2f((m_reg - mn) * C2); m_reg = mn; }
;     const float mnL = -mn * C2;
; #pragma unroll
;     for (int r = 0; r < 16; ++r) p0[r] = fmaf(p0[r], C2, mnL);
; #pragma unroll
;     for (int r = 0; r < 16; ++r) p1[r] = fmaf(p1[r], C2, mnL);
; #pragma unroll
;     for (int r = 0; r < 16; ++r) p0[r] = __builtin_amdgcn_exp2f(p0[r]);
.LBB0_977:
	v_cndmask_b32_e64 v214, v149, v148, s[6:7]
	v_mul_f32_e32 v215, 0xbdd53b94, v214
	v_fmamk_f32 v80, v80, 0x3dd53b94, v215
	v_fmamk_f32 v81, v81, 0x3dd53b94, v215
	v_fmamk_f32 v82, v82, 0x3dd53b94, v215
	v_fmamk_f32 v83, v83, 0x3dd53b94, v215
	v_fmamk_f32 v84, v84, 0x3dd53b94, v215
	v_fmamk_f32 v85, v85, 0x3dd53b94, v215
	v_fmamk_f32 v86, v86, 0x3dd53b94, v215
	v_fmamk_f32 v87, v87, 0x3dd53b94, v215
	v_fmamk_f32 v88, v88, 0x3dd53b94, v215
	v_fmamk_f32 v89, v89, 0x3dd53b94, v215
	v_fmamk_f32 v90, v90, 0x3dd53b94, v215
	v_fmamk_f32 v91, v91, 0x3dd53b94, v215
	v_fmamk_f32 v92, v92, 0x3dd53b94, v215
	v_fmamk_f32 v93, v93, 0x3dd53b94, v215
	v_fmamk_f32 v94, v94, 0x3dd53b94, v215
	v_fmamk_f32 v95, v95, 0x3dd53b94, v215
	v_exp_f32_e32 v148, v80
	v_exp_f32_e32 v163, v81
	v_exp_f32_e32 v149, v82
	v_exp_f32_e32 v162, v83
	v_exp_f32_e32 v150, v84
	v_exp_f32_e32 v161, v85
	v_exp_f32_e32 v151, v86
	v_exp_f32_e32 v160, v87
	v_exp_f32_e32 v152, v88
	v_exp_f32_e32 v159, v89
	v_exp_f32_e32 v153, v90
	v_exp_f32_e32 v158, v91
	v_exp_f32_e32 v154, v92
	v_exp_f32_e32 v157, v93
	v_exp_f32_e32 v155, v94
	v_exp_f32_e32 v156, v95
	v_fmamk_f32 v224, v64, 0x3dd53b94, v215
	v_fmamk_f32 v225, v65, 0x3dd53b94, v215
	v_fmamk_f32 v226, v66, 0x3dd53b94, v215
	v_fmamk_f32 v227, v67, 0x3dd53b94, v215
	v_fmamk_f32 v228, v68, 0x3dd53b94, v215
	v_fmamk_f32 v217, v69, 0x3dd53b94, v215
	v_fmamk_f32 v218, v70, 0x3dd53b94, v215
	v_fmamk_f32 v219, v71, 0x3dd53b94, v215
	v_fmamk_f32 v220, v72, 0x3dd53b94, v215
	v_fmamk_f32 v221, v73, 0x3dd53b94, v215
	v_fmamk_f32 v222, v74, 0x3dd53b94, v215
	v_fmamk_f32 v223, v75, 0x3dd53b94, v215
	v_fmamk_f32 v216, v76, 0x3dd53b94, v215
	v_fmamk_f32 v229, v77, 0x3dd53b94, v215
	v_fmamk_f32 v230, v78, 0x3dd53b94, v215
	v_fmac_f32_e32 v215, 0x3dd53b94, v79
	s_waitcnt lgkmcnt(0)
	s_barrier
; __device__ __forceinline__ void finishSM(f32x16& p0, f32x16& p1, float alpha, float& l_reg, bf16x8& pa0, bf16x8& pa1, bf16x8& pa2, bf16x8& pa3) {
; #pragma unroll
;     for (int r = 0; r < 16; ++r) p1[r] = __builtin_amdgcn_exp2f(p1[r]);
;     float ps = 0;
; #pragma unroll
;     for (int r = 0; r < 16; ++r) ps += p0[r];
; #pragma unroll
;     for (int r = 0; r < 16; ++r) ps += p1[r];
;     { auto rr = __builtin_amdgcn_permlane32_swap(__float_as_uint(ps), __float_as_uint(ps), false, false);
;       ps = __uint_as_float(rr[0]) + __uint_as_float(rr[1]); }
;     l_reg = l_reg * alpha + ps;
;     PK4(p0, 0, pa0); PK4(p0, 8, pa1); PK4(p1, 0, pa2); PK4(p1, 8, pa3);
; }
; template <int KB>
; __device__ __forceinline__ void qkt(f32x16& p0, f32x16& p1, const char* K_lds, int r32, int hi, const bf16x8* qr, const char* qx) {
;     p0 = f32x16{}; p1 = f32x16{};
;     const char* kb[4];
; #pragma unroll
;     for (int dd = 0; dd < 4; ++dd) kb[dd] = K_lds + KB * SHM_K + KSWZ(r32, (dd * 16 + hi * 8) * 2);
; #pragma unroll
;     for (int d0 = 0; d0 < 12; ++d0) { const char* a = kb[d0 & 3] + (d0 >> 2) * 128;
;         bf16x8 b0 = *reinterpret_cast<const bf16x8*>(a);
;         bf16x8 b1 = *reinterpret_cast<const bf16x8*>(a + 32 * 384);
;         const bf16x8 q = d0 < 8 ? qr[d0 & 7] : *reinterpret_cast<const bf16x8*>(qx + (d0 - 8) * 1024);
;         p0 = __builtin_amdgcn_mfma_f32_32x32x16_bf16(b0, q, p0, 0, 0, 0);
;         p1 = __builtin_amdgcn_mfma_f32_32x32x16_bf16(b1, q, p1, 0, 0, 0); }
	ds_read_b128 v[128:131], v194
	ds_read_b128 v[132:135], v194 offset:12288
	ds_read_b128 v[136:139], v195
	ds_read_b128 v[140:143], v195 offset:12288
	ds_read_b128 v[144:147], v196
	ds_read_b128 v[236:239], v196 offset:12288
	v_exp_f32_e32 v224, v224
	v_exp_f32_e32 v225, v225
	s_nop 1
	v_exp_f32_e32 v226, v226
	s_waitcnt lgkmcnt(5)
	v_mfma_f32_32x32x16_bf16 v[80:95], v[128:131], v[124:127], 0
	v_exp_f32_e32 v227, v227
	v_exp_f32_e32 v228, v228
	v_exp_f32_e32 v217, v217
	s_waitcnt lgkmcnt(4)
	v_mfma_f32_32x32x16_bf16 v[64:79], v[132:135], v[124:127], 0
	ds_read_b128 v[128:131], v197
	ds_read_b128 v[132:135], v197 offset:12288
	v_exp_f32_e32 v218, v218
	v_exp_f32_e32 v219, v219
	v_exp_f32_e32 v220, v220
	s_waitcnt lgkmcnt(5)
	v_mfma_f32_32x32x16_bf16 v[80:95], v[136:139], v[120:123], v[80:95]
	v_exp_f32_e32 v221, v221
	v_exp_f32_e32 v222, v222
	v_exp_f32_e32 v223, v223
	s_waitcnt lgkmcnt(4)
	v_mfma_f32_32x32x16_bf16 v[64:79], v[140:143], v[120:123], v[64:79]
	ds_read_b128 v[136:139], v194 offset:128
	ds_read_b128 v[140:143], v194 offset:12416
	v_exp_f32_e32 v231, v216
	v_exp_f32_e32 v229, v229
	v_exp_f32_e32 v230, v230
	s_waitcnt lgkmcnt(5)
	v_mfma_f32_32x32x16_bf16 v[80:95], v[144:147], v[116:119], v[80:95]
	v_exp_f32_e32 v232, v215
	v_add_f32_e32 v215, 0, v148
	v_add_f32_e32 v215, v163, v215
	s_waitcnt lgkmcnt(4)
	v_mfma_f32_32x32x16_bf16 v[64:79], v[236:239], v[116:119], v[64:79]
	ds_read_b128 v[144:147], v195 offset:128
	ds_read_b128 v[236:239], v195 offset:12416
	v_add_f32_e32 v215, v149, v215
	v_add_f32_e32 v215, v162, v215
	v_add_f32_e32 v215, v150, v215
	s_waitcnt lgkmcnt(5)
	v_mfma_f32_32x32x16_bf16 v[80:95], v[128:131], v[112:115], v[80:95]
	v_add_f32_e32 v215, v161, v215
	v_add_f32_e32 v215, v151, v215
	v_add_f32_e32 v215, v160, v215
	s_waitcnt lgkmcnt(4)
	v_mfma_f32_32x32x16_bf16 v[64:79], v[132:135], v[112:115], v[64:79]
	ds_read_b128 v[128:131], v196 offset:128
	ds_read_b128 v[132:135], v196 offset:12416
	v_add_f32_e32 v215, v152, v215
	v_add_f32_e32 v215, v159, v215
	v_add_f32_e32 v215, v153, v215
	s_waitcnt lgkmcnt(5)
	v_mfma_f32_32x32x16_bf16 v[80:95], v[136:139], v[108:111], v[80:95]
	v_add_f32_e32 v215, v158, v215
	v_add_f32_e32 v215, v154, v215
	v_add_f32_e32 v215, v157, v215
	s_waitcnt lgkmcnt(4)
	v_mfma_f32_32x32x16_bf16 v[64:79], v[140:143], v[108:111], v[64:79]
	ds_read_b128 v[136:139], v197 offset:128
	ds_read_b128 v[140:143], v197 offset:12416
	v_add_f32_e32 v215, v155, v215
	v_add_f32_e32 v215, v156, v215
	v_add_f32_e32 v215, v224, v215
	s_waitcnt lgkmcnt(5)
	v_mfma_f32_32x32x16_bf16 v[80:95], v[144:147], v[104:107], v[80:95]
	v_add_f32_e32 v215, v225, v215
	v_add_f32_e32 v215, v226, v215
	v_add_f32_e32 v215, v227, v215
	s_waitcnt lgkmcnt(4)
	v_mfma_f32_32x32x16_bf16 v[64:79], v[236:239], v[104:107], v[64:79]
	ds_read_b128 v[240:243], v204
	ds_read_b128 v[144:147], v194 offset:256
	ds_read_b128 v[236:239], v194 offset:12544
	v_add_f32_e32 v215, v228, v215
	v_add_f32_e32 v215, v217, v215
	v_add_f32_e32 v215, v218, v215
	s_waitcnt lgkmcnt(6)
	v_mfma_f32_32x32x16_bf16 v[80:95], v[128:131], v[100:103], v[80:95]
	v_add_f32_e32 v215, v219, v215
	v_add_f32_e32 v215, v220, v215
	v_add_f32_e32 v215, v221, v215
	s_waitcnt lgkmcnt(5)
	v_mfma_f32_32x32x16_bf16 v[64:79], v[132:135], v[100:103], v[64:79]
	ds_read_b128 v[244:247], v204 offset:1024
	ds_read_b128 v[128:131], v195 offset:256
	ds_read_b128 v[132:135], v195 offset:12544
	v_add_f32_e32 v215, v222, v215
	v_add_f32_e32 v215, v223, v215
	v_add_f32_e32 v215, v231, v215
	s_waitcnt lgkmcnt(7)
	v_mfma_f32_32x32x16_bf16 v[80:95], v[136:139], v[96:99], v[80:95]
	v_add_f32_e32 v215, v229, v215
	v_add_f32_e32 v215, v230, v215
	v_add_f32_e32 v215, v232, v215
	s_waitcnt lgkmcnt(6)
	v_mfma_f32_32x32x16_bf16 v[64:79], v[140:143], v[96:99], v[64:79]
	ds_read_b128 v[136:139], v196 offset:256
	ds_read_b128 v[140:143], v196 offset:12544
	v_mov_b32_e32 v216, v215
	v_cvt_pk_bf16_f32 v148, v148, v163
	v_cvt_pk_bf16_f32 v149, v149, v162
	s_waitcnt lgkmcnt(6)
	v_mfma_f32_32x32x16_bf16 v[80:95], v[144:147], v[240:243], v[80:95]
	v_cvt_pk_bf16_f32 v150, v150, v161
	v_cvt_pk_bf16_f32 v151, v151, v160
	v_cvt_pk_bf16_f32 v152, v152, v159
	s_waitcnt lgkmcnt(5)
	v_mfma_f32_32x32x16_bf16 v[64:79], v[236:239], v[240:243], v[64:79]
	ds_read_b128 v[144:147], v197 offset:256
	ds_read_b128 v[236:239], v197 offset:12544
	ds_read_b128 v[240:243], v204 offset:2048
	v_cvt_pk_bf16_f32 v153, v153, v158
	v_cvt_pk_bf16_f32 v154, v154, v157
	v_cvt_pk_bf16_f32 v155, v155, v156
	s_waitcnt lgkmcnt(6)
	v_mfma_f32_32x32x16_bf16 v[80:95], v[128:131], v[244:247], v[80:95]
	v_cvt_pk_bf16_f32 v156, v224, v225
	v_cvt_pk_bf16_f32 v157, v226, v227
	v_cvt_pk_bf16_f32 v158, v228, v217
	s_waitcnt lgkmcnt(5)
	v_mfma_f32_32x32x16_bf16 v[64:79], v[132:135], v[244:247], v[64:79]
	ds_read_b128 v[244:247], v204 offset:3072
	v_cvt_pk_bf16_f32 v159, v218, v219
	v_cvt_pk_bf16_f32 v160, v220, v221
	v_cvt_pk_bf16_f32 v161, v222, v223
	s_waitcnt lgkmcnt(1)
	v_mfma_f32_32x32x16_bf16 v[80:95], v[136:139], v[240:243], v[80:95]
	v_cvt_pk_bf16_f32 v162, v231, v229
	v_cvt_pk_bf16_f32 v163, v230, v232
	s_nop 1
	s_waitcnt lgkmcnt(4)
	v_mfma_f32_32x32x16_bf16 v[64:79], v[140:143], v[240:243], v[64:79]
	v_permlane32_swap_b32_e32 v215, v216
	v_permlane32_swap_b32_e32 v148, v150
	v_permlane32_swap_b32_e32 v149, v151
	s_waitcnt lgkmcnt(0)
	v_mfma_f32_32x32x16_bf16 v[80:95], v[144:147], v[244:247], v[80:95]
	v_permlane32_swap_b32_e32 v152, v154
	v_permlane32_swap_b32_e32 v153, v155
	v_permlane32_swap_b32_e32 v156, v158
	s_waitcnt lgkmcnt(2)
	v_mfma_f32_32x32x16_bf16 v[64:79], v[236:239], v[244:247], v[64:79]
	v_permlane32_swap_b32_e32 v157, v159
	v_permlane32_swap_b32_e32 v160, v162
	v_permlane32_swap_b32_e32 v161, v163
	s_add_i32 s0, s74, 1
	s_cmp_lt_i32 s0, s75
	s_cselect_b64 s[36:37], -1, 0
	s_cmp_ge_i32 s0, s75
	s_cbranch_scc1 .LBB0_979
	v_add_co_u32_e32 v128, vcc, 0xc0000, v180
	s_nop 1
	v_addc_co_u32_e32 v129, vcc, 0, v181, vcc
	v_add_co_u32_e32 v132, vcc, 0xe0000, v180
	s_nop 1
	v_addc_co_u32_e32 v133, vcc, 0, v181, vcc
	v_add_co_u32_e32 v136, vcc, 0xc0000, v178
	s_nop 1
	v_addc_co_u32_e32 v137, vcc, 0, v179, vcc
	v_add_co_u32_e32 v140, vcc, 0xe0000, v178
	s_nop 1
	v_addc_co_u32_e32 v141, vcc, 0, v179, vcc
	v_add_co_u32_e32 v144, vcc, 0x2000, v176
	s_nop 1
	v_addc_co_u32_e32 v145, vcc, 0, v177, vcc
	global_load_dwordx4 v[136:139], v[136:137], off
	global_load_dwordx4 v[140:143], v[140:141], off
	global_load_dwordx4 v[144:147], v[144:145], off
	global_load_dwordx4 v[128:131], v[128:129], off
	global_load_dwordx4 v[132:135], v[132:133], off
